# GEMM K loops: LDS-DMA stages issued ahead of the ds_read burst in each load segment
# baseline (speedup 1.0000x reference)
.LBB0_179:
	s_add_u32 s29, s56, 0xfffc0080
	s_addc_u32 s30, s57, -1
	s_add_i32 s31, 0, 0x10000
	s_cmp_eq_u32 s28, 12
	s_cselect_b32 s61, s6, s30
	s_cselect_b32 s60, s7, s29
	s_cselect_b32 s59, s24, s27
	s_cselect_b32 s58, s25, s26
	s_add_i32 s29, 0, 0x14000
	v_add_u32_e32 v156, s31, v145
	v_add_u32_e32 v162, s29, v145
	ds_read_b128 v[140:143], v156
	ds_read_b128 v[148:151], v156 offset:1024
	ds_read_b128 v[152:155], v156 offset:2048
	ds_read_b128 v[156:159], v156 offset:3072
	ds_read_b128 v[178:181], v162
	ds_read_b128 v[182:185], v162 offset:1024
	ds_read_b128 v[186:189], v162 offset:2048
	ds_read_b128 v[190:193], v162 offset:3072
	v_lshl_add_u64 v[174:175], s[56:57], 0, v[136:137]
	s_add_i32 m0, s65, 0xc000
	ds_read_b128 v[194:197], v147
	ds_read_b128 v[198:201], v147 offset:1024
	ds_read_b128 v[202:205], v147 offset:2048
	ds_read_b128 v[220:223], v147 offset:3072
	ds_read_b128 v[228:231], v147 offset:4096
	ds_read_b128 v[232:235], v147 offset:5120
	ds_read_b128 v[236:239], v147 offset:6144
	ds_read_b128 v[240:243], v147 offset:7168
	global_load_lds_dwordx4 v[174:175], off
	v_lshl_add_u64 v[174:175], s[56:57], 0, v[138:139]
	s_add_i32 m0, s65, 0xe000
	s_nop 0
	global_load_lds_dwordx4 v[174:175], off
	s_waitcnt vmcnt(8)
	s_waitcnt lgkmcnt(0)
	s_barrier
	s_setprio 1
	s_waitcnt lgkmcnt(0)
	v_mfma_f32_16x16x32_bf16 v[124:127], v[140:143], v[194:197], v[124:127]
	v_mfma_f32_16x16x32_bf16 v[120:123], v[152:155], v[194:197], v[120:123]
	v_mfma_f32_16x16x32_bf16 v[108:111], v[140:143], v[202:205], v[108:111]
	v_mfma_f32_16x16x32_bf16 v[104:107], v[152:155], v[202:205], v[104:107]
	v_mfma_f32_16x16x32_bf16 v[92:95], v[140:143], v[228:231], v[92:95]
	v_mfma_f32_16x16x32_bf16 v[88:91], v[152:155], v[228:231], v[88:91]
	v_mfma_f32_16x16x32_bf16 v[76:79], v[140:143], v[236:239], v[76:79]
	v_mfma_f32_16x16x32_bf16 v[72:75], v[152:155], v[236:239], v[72:75]
	v_mfma_f32_16x16x32_bf16 v[124:127], v[148:151], v[198:201], v[124:127]
	v_mfma_f32_16x16x32_bf16 v[120:123], v[156:159], v[198:201], v[120:123]
	v_mfma_f32_16x16x32_bf16 v[108:111], v[148:151], v[220:223], v[108:111]
	v_mfma_f32_16x16x32_bf16 v[104:107], v[156:159], v[220:223], v[104:107]
	v_mfma_f32_16x16x32_bf16 v[92:95], v[148:151], v[232:235], v[92:95]
	v_mfma_f32_16x16x32_bf16 v[88:91], v[156:159], v[232:235], v[88:91]
	v_mfma_f32_16x16x32_bf16 v[76:79], v[148:151], v[240:243], v[76:79]
	v_mfma_f32_16x16x32_bf16 v[72:75], v[156:159], v[240:243], v[72:75]
	s_setprio 0
	s_setprio 1
	v_mfma_f32_16x16x32_bf16 v[116:119], v[178:181], v[194:197], v[116:119]
	v_mfma_f32_16x16x32_bf16 v[112:115], v[186:189], v[194:197], v[112:115]
	v_mfma_f32_16x16x32_bf16 v[100:103], v[178:181], v[202:205], v[100:103]
	v_mfma_f32_16x16x32_bf16 v[96:99], v[186:189], v[202:205], v[96:99]
	v_mfma_f32_16x16x32_bf16 v[84:87], v[178:181], v[228:231], v[84:87]
	v_mfma_f32_16x16x32_bf16 v[80:83], v[186:189], v[228:231], v[80:83]
	v_mfma_f32_16x16x32_bf16 v[68:71], v[178:181], v[236:239], v[68:71]
	v_mfma_f32_16x16x32_bf16 v[64:67], v[186:189], v[236:239], v[64:67]
	v_mfma_f32_16x16x32_bf16 v[116:119], v[182:185], v[198:201], v[116:119]
	v_mfma_f32_16x16x32_bf16 v[112:115], v[190:193], v[198:201], v[112:115]
	v_mfma_f32_16x16x32_bf16 v[100:103], v[182:185], v[220:223], v[100:103]
	v_mfma_f32_16x16x32_bf16 v[96:99], v[190:193], v[220:223], v[96:99]
	v_mfma_f32_16x16x32_bf16 v[84:87], v[182:185], v[232:235], v[84:87]
	v_mfma_f32_16x16x32_bf16 v[80:83], v[190:193], v[232:235], v[80:83]
	v_mfma_f32_16x16x32_bf16 v[68:71], v[182:185], v[240:243], v[68:71]
	v_mfma_f32_16x16x32_bf16 v[64:67], v[190:193], v[240:243], v[64:67]
	s_setprio 0
	s_barrier
	s_add_i32 s30, s31, s64
	v_lshl_add_u64 v[174:175], s[58:59], 0, v[132:133]
	s_mov_b32 m0, s30
	s_nop 0
	global_load_lds_dwordx4 v[174:175], off
	s_add_i32 m0, s30, 0x2000
	s_add_u32 s30, s58, 0x40000
	v_lshl_add_u64 v[176:177], s[58:59], 0, v[128:129]
	s_addc_u32 s31, s59, 0
	s_add_i32 s29, s29, s64
	global_load_lds_dwordx4 v[176:177], off
	v_lshl_add_u64 v[244:245], s[30:31], 0, v[132:133]
	s_mov_b32 m0, s29
	v_lshl_add_u64 v[246:247], s[60:61], 0, v[130:131]
	global_load_lds_dwordx4 v[244:245], off
	v_lshl_add_u64 v[244:245], s[30:31], 0, v[128:129]
	s_add_i32 m0, s29, 0x2000
	s_nop 0
	global_load_lds_dwordx4 v[244:245], off
	v_lshl_add_u64 v[244:245], s[60:61], 0, v[134:135]
	s_mov_b32 m0, s65
	s_nop 0
	global_load_lds_dwordx4 v[244:245], off
	s_mov_b32 m0, s66
	s_nop 0
	global_load_lds_dwordx4 v[246:247], off
	ds_read_b128 v[194:197], v147 offset:16384
	ds_read_b128 v[198:201], v147 offset:17408
	ds_read_b128 v[202:205], v147 offset:18432
	ds_read_b128 v[220:223], v147 offset:19456
	ds_read_b128 v[228:231], v147 offset:20480
	ds_read_b128 v[232:235], v147 offset:21504
	ds_read_b128 v[236:239], v147 offset:22528
	ds_read_b128 v[240:243], v147 offset:23552
	s_waitcnt vmcnt(8)
	s_waitcnt lgkmcnt(0)
	s_barrier
	s_setprio 1
	s_waitcnt lgkmcnt(0)
	v_mfma_f32_16x16x32_bf16 v[60:63], v[140:143], v[194:197], v[60:63]
	v_mfma_f32_16x16x32_bf16 v[56:59], v[152:155], v[194:197], v[56:59]
	v_mfma_f32_16x16x32_bf16 v[44:47], v[140:143], v[202:205], v[44:47]
	v_mfma_f32_16x16x32_bf16 v[40:43], v[152:155], v[202:205], v[40:43]
	v_mfma_f32_16x16x32_bf16 v[28:31], v[140:143], v[228:231], v[28:31]
	v_mfma_f32_16x16x32_bf16 v[24:27], v[152:155], v[228:231], v[24:27]
	v_mfma_f32_16x16x32_bf16 v[12:15], v[140:143], v[236:239], v[12:15]
	v_mfma_f32_16x16x32_bf16 v[8:11], v[152:155], v[236:239], v[8:11]
	v_mfma_f32_16x16x32_bf16 v[60:63], v[148:151], v[198:201], v[60:63]
	v_mfma_f32_16x16x32_bf16 v[56:59], v[156:159], v[198:201], v[56:59]
	v_mfma_f32_16x16x32_bf16 v[44:47], v[148:151], v[220:223], v[44:47]
	v_mfma_f32_16x16x32_bf16 v[40:43], v[156:159], v[220:223], v[40:43]
	v_mfma_f32_16x16x32_bf16 v[28:31], v[148:151], v[232:235], v[28:31]
	v_mfma_f32_16x16x32_bf16 v[24:27], v[156:159], v[232:235], v[24:27]
	v_mfma_f32_16x16x32_bf16 v[12:15], v[148:151], v[240:243], v[12:15]
	v_mfma_f32_16x16x32_bf16 v[8:11], v[156:159], v[240:243], v[8:11]
	s_setprio 0
	s_setprio 1
	v_mfma_f32_16x16x32_bf16 v[52:55], v[178:181], v[194:197], v[52:55]
	v_mfma_f32_16x16x32_bf16 v[48:51], v[186:189], v[194:197], v[48:51]
	v_mfma_f32_16x16x32_bf16 v[36:39], v[178:181], v[202:205], v[36:39]
	v_mfma_f32_16x16x32_bf16 v[32:35], v[186:189], v[202:205], v[32:35]
	v_mfma_f32_16x16x32_bf16 v[20:23], v[178:181], v[228:231], v[20:23]
	v_mfma_f32_16x16x32_bf16 v[16:19], v[186:189], v[228:231], v[16:19]
	v_mfma_f32_16x16x32_bf16 v[4:7], v[178:181], v[236:239], v[4:7]
	v_mfma_f32_16x16x32_bf16 v[0:3], v[186:189], v[236:239], v[0:3]
	v_mfma_f32_16x16x32_bf16 v[52:55], v[182:185], v[198:201], v[52:55]
	v_mfma_f32_16x16x32_bf16 v[48:51], v[190:193], v[198:201], v[48:51]
	v_mfma_f32_16x16x32_bf16 v[36:39], v[182:185], v[220:223], v[36:39]
	v_mfma_f32_16x16x32_bf16 v[32:35], v[190:193], v[220:223], v[32:35]
	v_mfma_f32_16x16x32_bf16 v[20:23], v[182:185], v[232:235], v[20:23]
	v_mfma_f32_16x16x32_bf16 v[16:19], v[190:193], v[232:235], v[16:19]
	v_mfma_f32_16x16x32_bf16 v[4:7], v[182:185], v[240:243], v[4:7]
	v_mfma_f32_16x16x32_bf16 v[0:3], v[190:193], v[240:243], v[0:3]
	s_setprio 0
	s_barrier
	s_add_i32 s29, 0, 0x18000
	s_add_i32 s49, 0, 0x1c000
	v_add_u32_e32 v156, s29, v145
	v_add_u32_e32 v162, s49, v145
	ds_read_b128 v[140:143], v156
	ds_read_b128 v[148:151], v156 offset:1024
	ds_read_b128 v[152:155], v156 offset:2048
	ds_read_b128 v[156:159], v156 offset:3072
	ds_read_b128 v[178:181], v162
	ds_read_b128 v[182:185], v162 offset:1024
	ds_read_b128 v[186:189], v162 offset:2048
	ds_read_b128 v[190:193], v162 offset:3072
	s_add_u32 s30, s60, 0x40000
	s_addc_u32 s31, s61, 0
	s_mov_b32 m0, s67
	v_lshl_add_u64 v[248:249], s[30:31], 0, v[134:135]
	ds_read_b128 v[194:197], v147 offset:32768
	ds_read_b128 v[198:201], v147 offset:33792
	ds_read_b128 v[202:205], v147 offset:34816
	ds_read_b128 v[220:223], v147 offset:35840
	ds_read_b128 v[228:231], v147 offset:36864
	ds_read_b128 v[232:235], v147 offset:37888
	ds_read_b128 v[236:239], v147 offset:38912
	ds_read_b128 v[240:243], v147 offset:39936
	global_load_lds_dwordx4 v[248:249], off
	v_lshl_add_u64 v[248:249], s[30:31], 0, v[130:131]
	s_mov_b32 m0, s68
	s_nop 0
	global_load_lds_dwordx4 v[248:249], off
	s_waitcnt vmcnt(8)
	s_waitcnt lgkmcnt(0)
	s_barrier
	s_setprio 1
	s_waitcnt lgkmcnt(0)
	v_mfma_f32_16x16x32_bf16 v[124:127], v[140:143], v[194:197], v[124:127]
	v_mfma_f32_16x16x32_bf16 v[120:123], v[152:155], v[194:197], v[120:123]
	v_mfma_f32_16x16x32_bf16 v[108:111], v[140:143], v[202:205], v[108:111]
	v_mfma_f32_16x16x32_bf16 v[104:107], v[152:155], v[202:205], v[104:107]
	v_mfma_f32_16x16x32_bf16 v[92:95], v[140:143], v[228:231], v[92:95]
	v_mfma_f32_16x16x32_bf16 v[88:91], v[152:155], v[228:231], v[88:91]
	v_mfma_f32_16x16x32_bf16 v[76:79], v[140:143], v[236:239], v[76:79]
	v_mfma_f32_16x16x32_bf16 v[72:75], v[152:155], v[236:239], v[72:75]
	v_mfma_f32_16x16x32_bf16 v[124:127], v[148:151], v[198:201], v[124:127]
	v_mfma_f32_16x16x32_bf16 v[120:123], v[156:159], v[198:201], v[120:123]
	v_mfma_f32_16x16x32_bf16 v[108:111], v[148:151], v[220:223], v[108:111]
	v_mfma_f32_16x16x32_bf16 v[104:107], v[156:159], v[220:223], v[104:107]
	v_mfma_f32_16x16x32_bf16 v[92:95], v[148:151], v[232:235], v[92:95]
	v_mfma_f32_16x16x32_bf16 v[88:91], v[156:159], v[232:235], v[88:91]
	v_mfma_f32_16x16x32_bf16 v[76:79], v[148:151], v[240:243], v[76:79]
	v_mfma_f32_16x16x32_bf16 v[72:75], v[156:159], v[240:243], v[72:75]
	s_setprio 0
	s_setprio 1
	v_mfma_f32_16x16x32_bf16 v[116:119], v[178:181], v[194:197], v[116:119]
	v_mfma_f32_16x16x32_bf16 v[112:115], v[186:189], v[194:197], v[112:115]
	v_mfma_f32_16x16x32_bf16 v[100:103], v[178:181], v[202:205], v[100:103]
	v_mfma_f32_16x16x32_bf16 v[96:99], v[186:189], v[202:205], v[96:99]
	v_mfma_f32_16x16x32_bf16 v[84:87], v[178:181], v[228:231], v[84:87]
	v_mfma_f32_16x16x32_bf16 v[80:83], v[186:189], v[228:231], v[80:83]
	v_mfma_f32_16x16x32_bf16 v[68:71], v[178:181], v[236:239], v[68:71]
	v_mfma_f32_16x16x32_bf16 v[64:67], v[186:189], v[236:239], v[64:67]
	v_mfma_f32_16x16x32_bf16 v[116:119], v[182:185], v[198:201], v[116:119]
	v_mfma_f32_16x16x32_bf16 v[112:115], v[190:193], v[198:201], v[112:115]
	v_mfma_f32_16x16x32_bf16 v[100:103], v[182:185], v[220:223], v[100:103]
	v_mfma_f32_16x16x32_bf16 v[96:99], v[190:193], v[220:223], v[96:99]
	v_mfma_f32_16x16x32_bf16 v[84:87], v[182:185], v[232:235], v[84:87]
	v_mfma_f32_16x16x32_bf16 v[80:83], v[190:193], v[232:235], v[80:83]
	v_mfma_f32_16x16x32_bf16 v[68:71], v[182:185], v[240:243], v[68:71]
	v_mfma_f32_16x16x32_bf16 v[64:67], v[190:193], v[240:243], v[64:67]
	s_setprio 0
	s_barrier
	s_add_i32 s29, s29, s64
	v_lshl_add_u64 v[174:175], v[174:175], 0, s[4:5]
	s_mov_b32 m0, s29
	s_nop 0
	global_load_lds_dwordx4 v[174:175], off
	s_add_i32 m0, s29, 0x2000
	s_add_u32 s30, s58, 0x40080
	v_lshl_add_u64 v[174:175], v[176:177], 0, s[4:5]
	s_addc_u32 s31, s59, 0
	s_add_i32 s29, s49, s64
	global_load_lds_dwordx4 v[174:175], off
	v_lshl_add_u64 v[174:175], s[30:31], 0, v[132:133]
	s_mov_b32 m0, s29
	s_nop 0
	global_load_lds_dwordx4 v[174:175], off
	v_lshl_add_u64 v[174:175], s[30:31], 0, v[128:129]
	s_add_i32 m0, s29, 0x2000
	s_nop 0
	global_load_lds_dwordx4 v[174:175], off
	v_lshl_add_u64 v[174:175], v[244:245], 0, s[4:5]
	s_mov_b32 m0, s73
	s_nop 0
	global_load_lds_dwordx4 v[174:175], off
	v_lshl_add_u64 v[174:175], v[246:247], 0, s[4:5]
	s_mov_b32 m0, s74
	s_nop 0
	global_load_lds_dwordx4 v[174:175], off
	ds_read_b128 v[194:197], v147 offset:49152
	ds_read_b128 v[198:201], v147 offset:50176
	ds_read_b128 v[202:205], v147 offset:51200
	ds_read_b128 v[220:223], v147 offset:52224
	ds_read_b128 v[228:231], v147 offset:53248
	ds_read_b128 v[232:235], v147 offset:54272
	ds_read_b128 v[236:239], v147 offset:55296
	ds_read_b128 v[240:243], v147 offset:56320
	s_waitcnt vmcnt(8)
	s_waitcnt lgkmcnt(0)
	s_barrier
	s_setprio 1
	s_waitcnt lgkmcnt(0)
	v_mfma_f32_16x16x32_bf16 v[60:63], v[140:143], v[194:197], v[60:63]
	v_mfma_f32_16x16x32_bf16 v[56:59], v[152:155], v[194:197], v[56:59]
	v_mfma_f32_16x16x32_bf16 v[44:47], v[140:143], v[202:205], v[44:47]
	v_mfma_f32_16x16x32_bf16 v[40:43], v[152:155], v[202:205], v[40:43]
	v_mfma_f32_16x16x32_bf16 v[28:31], v[140:143], v[228:231], v[28:31]
	v_mfma_f32_16x16x32_bf16 v[24:27], v[152:155], v[228:231], v[24:27]
	v_mfma_f32_16x16x32_bf16 v[12:15], v[140:143], v[236:239], v[12:15]
	v_mfma_f32_16x16x32_bf16 v[8:11], v[152:155], v[236:239], v[8:11]
	v_mfma_f32_16x16x32_bf16 v[60:63], v[148:151], v[198:201], v[60:63]
	v_mfma_f32_16x16x32_bf16 v[56:59], v[156:159], v[198:201], v[56:59]
	v_mfma_f32_16x16x32_bf16 v[44:47], v[148:151], v[220:223], v[44:47]
	v_mfma_f32_16x16x32_bf16 v[40:43], v[156:159], v[220:223], v[40:43]
	v_mfma_f32_16x16x32_bf16 v[28:31], v[148:151], v[232:235], v[28:31]
	v_mfma_f32_16x16x32_bf16 v[24:27], v[156:159], v[232:235], v[24:27]
	v_mfma_f32_16x16x32_bf16 v[12:15], v[148:151], v[240:243], v[12:15]
	v_mfma_f32_16x16x32_bf16 v[8:11], v[156:159], v[240:243], v[8:11]
	s_setprio 0
	s_setprio 1
	v_mfma_f32_16x16x32_bf16 v[52:55], v[178:181], v[194:197], v[52:55]
	v_mfma_f32_16x16x32_bf16 v[48:51], v[186:189], v[194:197], v[48:51]
	v_mfma_f32_16x16x32_bf16 v[36:39], v[178:181], v[202:205], v[36:39]
	v_mfma_f32_16x16x32_bf16 v[32:35], v[186:189], v[202:205], v[32:35]
	v_mfma_f32_16x16x32_bf16 v[20:23], v[178:181], v[228:231], v[20:23]
	v_mfma_f32_16x16x32_bf16 v[16:19], v[186:189], v[228:231], v[16:19]
	v_mfma_f32_16x16x32_bf16 v[4:7], v[178:181], v[236:239], v[4:7]
	v_mfma_f32_16x16x32_bf16 v[0:3], v[186:189], v[236:239], v[0:3]
	v_mfma_f32_16x16x32_bf16 v[52:55], v[182:185], v[198:201], v[52:55]
	v_mfma_f32_16x16x32_bf16 v[48:51], v[190:193], v[198:201], v[48:51]
	v_mfma_f32_16x16x32_bf16 v[36:39], v[182:185], v[220:223], v[36:39]
	v_mfma_f32_16x16x32_bf16 v[32:35], v[190:193], v[220:223], v[32:35]
	v_mfma_f32_16x16x32_bf16 v[20:23], v[182:185], v[232:235], v[20:23]
	v_mfma_f32_16x16x32_bf16 v[16:19], v[190:193], v[232:235], v[16:19]
	v_mfma_f32_16x16x32_bf16 v[4:7], v[182:185], v[240:243], v[4:7]
	v_mfma_f32_16x16x32_bf16 v[0:3], v[190:193], v[240:243], v[0:3]
	s_setprio 0
	s_barrier
	s_add_i32 s28, s28, 2
	s_add_u32 s56, s56, 0x100
	s_addc_u32 s57, s57, 0
	s_add_u32 s26, s26, 0x100
	s_addc_u32 s27, s27, 0
	s_cmp_gt_u32 s28, 13
	s_cbranch_scc0 .LBB0_179
	s_and_b64 vcc, exec, s[46:47]
	s_cbranch_vccz .LBB0_182
	s_barrier

.LBB0_204:
	s_add_u32 s28, s42, 0xfffc0080
	s_addc_u32 s29, s43, -1
	s_add_i32 s30, 0, 0x10000
	s_cmp_eq_u32 s27, 12
	s_cselect_b32 s63, s6, s29
	s_cselect_b32 s62, s7, s28
	s_cselect_b32 s61, s23, s26
	s_cselect_b32 s60, s24, s25
	s_add_i32 s31, 0, 0x14000
	v_add_u32_e32 v140, s30, v221
	v_add_u32_e32 v156, s31, v221
	ds_read_b128 v[128:131], v140
	ds_read_b128 v[132:135], v140 offset:1024
	ds_read_b128 v[136:139], v140 offset:2048
	ds_read_b128 v[140:143], v140 offset:3072
	ds_read_b128 v[144:147], v156
	ds_read_b128 v[148:151], v156 offset:1024
	ds_read_b128 v[152:155], v156 offset:2048
	ds_read_b128 v[156:159], v156 offset:3072
	v_lshl_add_u64 v[174:175], s[42:43], 0, v[184:185]
	s_add_i32 m0, s67, 0xc000
	ds_read_b128 v[188:191], v223
	ds_read_b128 v[192:195], v223 offset:1024
	ds_read_b128 v[196:199], v223 offset:2048
	ds_read_b128 v[200:203], v223 offset:3072
	ds_read_b128 v[228:231], v223 offset:4096
	ds_read_b128 v[232:235], v223 offset:5120
	ds_read_b128 v[236:239], v223 offset:6144
	ds_read_b128 v[240:243], v223 offset:7168
	global_load_lds_dwordx4 v[174:175], off
	v_lshl_add_u64 v[174:175], s[42:43], 0, v[186:187]
	s_add_i32 m0, s67, 0xe000
	s_nop 0
	global_load_lds_dwordx4 v[174:175], off
	s_waitcnt vmcnt(8)
	s_waitcnt lgkmcnt(0)
	s_barrier
	s_setprio 1
	s_waitcnt lgkmcnt(0)
	v_mfma_f32_16x16x32_bf16 v[124:127], v[128:131], v[188:191], v[124:127]
	v_mfma_f32_16x16x32_bf16 v[120:123], v[136:139], v[188:191], v[120:123]
	v_mfma_f32_16x16x32_bf16 v[116:119], v[128:131], v[196:199], v[116:119]
	v_mfma_f32_16x16x32_bf16 v[108:111], v[136:139], v[196:199], v[108:111]
	v_mfma_f32_16x16x32_bf16 v[100:103], v[128:131], v[228:231], v[100:103]
	v_mfma_f32_16x16x32_bf16 v[92:95], v[136:139], v[228:231], v[92:95]
	v_mfma_f32_16x16x32_bf16 v[84:87], v[128:131], v[236:239], v[84:87]
	v_mfma_f32_16x16x32_bf16 v[76:79], v[136:139], v[236:239], v[76:79]
	v_mfma_f32_16x16x32_bf16 v[124:127], v[132:135], v[192:195], v[124:127]
	v_mfma_f32_16x16x32_bf16 v[120:123], v[140:143], v[192:195], v[120:123]
	v_mfma_f32_16x16x32_bf16 v[116:119], v[132:135], v[200:203], v[116:119]
	v_mfma_f32_16x16x32_bf16 v[108:111], v[140:143], v[200:203], v[108:111]
	v_mfma_f32_16x16x32_bf16 v[100:103], v[132:135], v[232:235], v[100:103]
	v_mfma_f32_16x16x32_bf16 v[92:95], v[140:143], v[232:235], v[92:95]
	v_mfma_f32_16x16x32_bf16 v[84:87], v[132:135], v[240:243], v[84:87]
	v_mfma_f32_16x16x32_bf16 v[76:79], v[140:143], v[240:243], v[76:79]
	s_setprio 0
	s_setprio 1
	v_mfma_f32_16x16x32_bf16 v[112:115], v[144:147], v[188:191], v[112:115]
	v_mfma_f32_16x16x32_bf16 v[104:107], v[152:155], v[188:191], v[104:107]
	v_mfma_f32_16x16x32_bf16 v[96:99], v[144:147], v[196:199], v[96:99]
	v_mfma_f32_16x16x32_bf16 v[88:91], v[152:155], v[196:199], v[88:91]
	v_mfma_f32_16x16x32_bf16 v[80:83], v[144:147], v[228:231], v[80:83]
	v_mfma_f32_16x16x32_bf16 v[72:75], v[152:155], v[228:231], v[72:75]
	v_mfma_f32_16x16x32_bf16 v[68:71], v[144:147], v[236:239], v[68:71]
	v_mfma_f32_16x16x32_bf16 v[64:67], v[152:155], v[236:239], v[64:67]
	v_mfma_f32_16x16x32_bf16 v[112:115], v[148:151], v[192:195], v[112:115]
	v_mfma_f32_16x16x32_bf16 v[104:107], v[156:159], v[192:195], v[104:107]
	v_mfma_f32_16x16x32_bf16 v[96:99], v[148:151], v[200:203], v[96:99]
	v_mfma_f32_16x16x32_bf16 v[88:91], v[156:159], v[200:203], v[88:91]
	v_mfma_f32_16x16x32_bf16 v[80:83], v[148:151], v[232:235], v[80:83]
	v_mfma_f32_16x16x32_bf16 v[72:75], v[156:159], v[232:235], v[72:75]
	v_mfma_f32_16x16x32_bf16 v[68:71], v[148:151], v[240:243], v[68:71]
	v_mfma_f32_16x16x32_bf16 v[64:67], v[156:159], v[240:243], v[64:67]
	s_setprio 0
	s_barrier
	s_add_i32 s28, s30, s66
	v_lshl_add_u64 v[174:175], s[60:61], 0, v[162:163]
	s_mov_b32 m0, s28
	s_nop 0
	global_load_lds_dwordx4 v[174:175], off
	s_add_i32 m0, s28, 0x2000
	s_add_u32 s28, s60, 0x40000
	v_lshl_add_u64 v[176:177], s[60:61], 0, v[178:179]
	s_addc_u32 s29, s61, 0
	s_add_i32 s30, s31, s66
	global_load_lds_dwordx4 v[176:177], off
	v_lshl_add_u64 v[204:205], s[28:29], 0, v[162:163]
	s_mov_b32 m0, s30
	v_lshl_add_u64 v[244:245], s[62:63], 0, v[180:181]
	global_load_lds_dwordx4 v[204:205], off
	v_lshl_add_u64 v[204:205], s[28:29], 0, v[178:179]
	s_add_i32 m0, s30, 0x2000
	s_nop 0
	global_load_lds_dwordx4 v[204:205], off
	v_lshl_add_u64 v[204:205], s[62:63], 0, v[182:183]
	s_mov_b32 m0, s67
	s_nop 0
	global_load_lds_dwordx4 v[204:205], off
	s_mov_b32 m0, s68
	s_nop 0
	global_load_lds_dwordx4 v[244:245], off
	ds_read_b128 v[188:191], v223 offset:16384
	ds_read_b128 v[192:195], v223 offset:17408
	ds_read_b128 v[196:199], v223 offset:18432
	ds_read_b128 v[200:203], v223 offset:19456
	ds_read_b128 v[228:231], v223 offset:20480
	ds_read_b128 v[232:235], v223 offset:21504
	ds_read_b128 v[236:239], v223 offset:22528
	ds_read_b128 v[240:243], v223 offset:23552
	s_waitcnt vmcnt(8)
	s_waitcnt lgkmcnt(0)
	s_barrier
	s_setprio 1
	s_waitcnt lgkmcnt(0)
	v_mfma_f32_16x16x32_bf16 v[60:63], v[128:131], v[188:191], v[60:63]
	v_mfma_f32_16x16x32_bf16 v[56:59], v[136:139], v[188:191], v[56:59]
	v_mfma_f32_16x16x32_bf16 v[52:55], v[128:131], v[196:199], v[52:55]
	v_mfma_f32_16x16x32_bf16 v[44:47], v[136:139], v[196:199], v[44:47]
	v_mfma_f32_16x16x32_bf16 v[36:39], v[128:131], v[228:231], v[36:39]
	v_mfma_f32_16x16x32_bf16 v[28:31], v[136:139], v[228:231], v[28:31]
	v_mfma_f32_16x16x32_bf16 v[20:23], v[128:131], v[236:239], v[20:23]
	v_mfma_f32_16x16x32_bf16 v[12:15], v[136:139], v[236:239], v[12:15]
	v_mfma_f32_16x16x32_bf16 v[60:63], v[132:135], v[192:195], v[60:63]
	v_mfma_f32_16x16x32_bf16 v[56:59], v[140:143], v[192:195], v[56:59]
	v_mfma_f32_16x16x32_bf16 v[52:55], v[132:135], v[200:203], v[52:55]
	v_mfma_f32_16x16x32_bf16 v[44:47], v[140:143], v[200:203], v[44:47]
	v_mfma_f32_16x16x32_bf16 v[36:39], v[132:135], v[232:235], v[36:39]
	v_mfma_f32_16x16x32_bf16 v[28:31], v[140:143], v[232:235], v[28:31]
	v_mfma_f32_16x16x32_bf16 v[20:23], v[132:135], v[240:243], v[20:23]
	v_mfma_f32_16x16x32_bf16 v[12:15], v[140:143], v[240:243], v[12:15]
	s_setprio 0
	s_setprio 1
	v_mfma_f32_16x16x32_bf16 v[48:51], v[144:147], v[188:191], v[48:51]
	v_mfma_f32_16x16x32_bf16 v[40:43], v[152:155], v[188:191], v[40:43]
	v_mfma_f32_16x16x32_bf16 v[32:35], v[144:147], v[196:199], v[32:35]
	v_mfma_f32_16x16x32_bf16 v[24:27], v[152:155], v[196:199], v[24:27]
	v_mfma_f32_16x16x32_bf16 v[16:19], v[144:147], v[228:231], v[16:19]
	v_mfma_f32_16x16x32_bf16 v[8:11], v[152:155], v[228:231], v[8:11]
	v_mfma_f32_16x16x32_bf16 v[4:7], v[144:147], v[236:239], v[4:7]
	v_mfma_f32_16x16x32_bf16 v[0:3], v[152:155], v[236:239], v[0:3]
	v_mfma_f32_16x16x32_bf16 v[48:51], v[148:151], v[192:195], v[48:51]
	v_mfma_f32_16x16x32_bf16 v[40:43], v[156:159], v[192:195], v[40:43]
	v_mfma_f32_16x16x32_bf16 v[32:35], v[148:151], v[200:203], v[32:35]
	v_mfma_f32_16x16x32_bf16 v[24:27], v[156:159], v[200:203], v[24:27]
	v_mfma_f32_16x16x32_bf16 v[16:19], v[148:151], v[232:235], v[16:19]
	v_mfma_f32_16x16x32_bf16 v[8:11], v[156:159], v[232:235], v[8:11]
	v_mfma_f32_16x16x32_bf16 v[4:7], v[148:151], v[240:243], v[4:7]
	v_mfma_f32_16x16x32_bf16 v[0:3], v[156:159], v[240:243], v[0:3]
	s_setprio 0
	s_barrier
	s_add_i32 s30, 0, 0x18000
	s_add_i32 s31, 0, 0x1c000
	v_add_u32_e32 v140, s30, v221
	v_add_u32_e32 v156, s31, v221
	ds_read_b128 v[128:131], v140
	ds_read_b128 v[132:135], v140 offset:1024
	ds_read_b128 v[136:139], v140 offset:2048
	ds_read_b128 v[140:143], v140 offset:3072
	ds_read_b128 v[144:147], v156
	ds_read_b128 v[148:151], v156 offset:1024
	ds_read_b128 v[152:155], v156 offset:2048
	ds_read_b128 v[156:159], v156 offset:3072
	s_add_u32 s28, s62, 0x40000
	s_addc_u32 s29, s63, 0
	s_mov_b32 m0, s69
	v_lshl_add_u64 v[246:247], s[28:29], 0, v[182:183]
	ds_read_b128 v[188:191], v223 offset:32768
	ds_read_b128 v[192:195], v223 offset:33792
	ds_read_b128 v[196:199], v223 offset:34816
	ds_read_b128 v[200:203], v223 offset:35840
	ds_read_b128 v[228:231], v223 offset:36864
	ds_read_b128 v[232:235], v223 offset:37888
	ds_read_b128 v[236:239], v223 offset:38912
	ds_read_b128 v[240:243], v223 offset:39936
	global_load_lds_dwordx4 v[246:247], off
	v_lshl_add_u64 v[246:247], s[28:29], 0, v[180:181]
	s_mov_b32 m0, s70
	s_nop 0
	global_load_lds_dwordx4 v[246:247], off
	s_waitcnt vmcnt(8)
	s_waitcnt lgkmcnt(0)
	s_barrier
	s_setprio 1
	s_waitcnt lgkmcnt(0)
	v_mfma_f32_16x16x32_bf16 v[124:127], v[128:131], v[188:191], v[124:127]
	v_mfma_f32_16x16x32_bf16 v[120:123], v[136:139], v[188:191], v[120:123]
	v_mfma_f32_16x16x32_bf16 v[116:119], v[128:131], v[196:199], v[116:119]
	v_mfma_f32_16x16x32_bf16 v[108:111], v[136:139], v[196:199], v[108:111]
	v_mfma_f32_16x16x32_bf16 v[100:103], v[128:131], v[228:231], v[100:103]
	v_mfma_f32_16x16x32_bf16 v[92:95], v[136:139], v[228:231], v[92:95]
	v_mfma_f32_16x16x32_bf16 v[84:87], v[128:131], v[236:239], v[84:87]
	v_mfma_f32_16x16x32_bf16 v[76:79], v[136:139], v[236:239], v[76:79]
	v_mfma_f32_16x16x32_bf16 v[124:127], v[132:135], v[192:195], v[124:127]
	v_mfma_f32_16x16x32_bf16 v[120:123], v[140:143], v[192:195], v[120:123]
	v_mfma_f32_16x16x32_bf16 v[116:119], v[132:135], v[200:203], v[116:119]
	v_mfma_f32_16x16x32_bf16 v[108:111], v[140:143], v[200:203], v[108:111]
	v_mfma_f32_16x16x32_bf16 v[100:103], v[132:135], v[232:235], v[100:103]
	v_mfma_f32_16x16x32_bf16 v[92:95], v[140:143], v[232:235], v[92:95]
	v_mfma_f32_16x16x32_bf16 v[84:87], v[132:135], v[240:243], v[84:87]
	v_mfma_f32_16x16x32_bf16 v[76:79], v[140:143], v[240:243], v[76:79]
	s_setprio 0
	s_setprio 1
	v_mfma_f32_16x16x32_bf16 v[112:115], v[144:147], v[188:191], v[112:115]
	v_mfma_f32_16x16x32_bf16 v[104:107], v[152:155], v[188:191], v[104:107]
	v_mfma_f32_16x16x32_bf16 v[96:99], v[144:147], v[196:199], v[96:99]
	v_mfma_f32_16x16x32_bf16 v[88:91], v[152:155], v[196:199], v[88:91]
	v_mfma_f32_16x16x32_bf16 v[80:83], v[144:147], v[228:231], v[80:83]
	v_mfma_f32_16x16x32_bf16 v[72:75], v[152:155], v[228:231], v[72:75]
	v_mfma_f32_16x16x32_bf16 v[68:71], v[144:147], v[236:239], v[68:71]
	v_mfma_f32_16x16x32_bf16 v[64:67], v[152:155], v[236:239], v[64:67]
	v_mfma_f32_16x16x32_bf16 v[112:115], v[148:151], v[192:195], v[112:115]
	v_mfma_f32_16x16x32_bf16 v[104:107], v[156:159], v[192:195], v[104:107]
	v_mfma_f32_16x16x32_bf16 v[96:99], v[148:151], v[200:203], v[96:99]
	v_mfma_f32_16x16x32_bf16 v[88:91], v[156:159], v[200:203], v[88:91]
	v_mfma_f32_16x16x32_bf16 v[80:83], v[148:151], v[232:235], v[80:83]
	v_mfma_f32_16x16x32_bf16 v[72:75], v[156:159], v[232:235], v[72:75]
	v_mfma_f32_16x16x32_bf16 v[68:71], v[148:151], v[240:243], v[68:71]
	v_mfma_f32_16x16x32_bf16 v[64:67], v[156:159], v[240:243], v[64:67]
	s_setprio 0
	s_barrier
	s_add_i32 s28, s30, s66
	v_lshl_add_u64 v[174:175], v[174:175], 0, s[4:5]
	s_mov_b32 m0, s28
	s_nop 0
	global_load_lds_dwordx4 v[174:175], off
	s_add_i32 m0, s28, 0x2000
	s_add_u32 s28, s60, 0x40080
	v_lshl_add_u64 v[174:175], v[176:177], 0, s[4:5]
	s_addc_u32 s29, s61, 0
	s_add_i32 s30, s31, s66
	global_load_lds_dwordx4 v[174:175], off
	v_lshl_add_u64 v[174:175], s[28:29], 0, v[162:163]
	s_mov_b32 m0, s30
	s_nop 0
	global_load_lds_dwordx4 v[174:175], off
	v_lshl_add_u64 v[174:175], s[28:29], 0, v[178:179]
	s_add_i32 m0, s30, 0x2000
	s_nop 0
	global_load_lds_dwordx4 v[174:175], off
	v_lshl_add_u64 v[174:175], v[204:205], 0, s[4:5]
	s_mov_b32 m0, s71
	s_nop 0
	global_load_lds_dwordx4 v[174:175], off
	v_lshl_add_u64 v[174:175], v[244:245], 0, s[4:5]
	s_mov_b32 m0, s72
	s_nop 0
	global_load_lds_dwordx4 v[174:175], off
	ds_read_b128 v[188:191], v223 offset:49152
	ds_read_b128 v[192:195], v223 offset:50176
	ds_read_b128 v[196:199], v223 offset:51200
	ds_read_b128 v[200:203], v223 offset:52224
	ds_read_b128 v[228:231], v223 offset:53248
	ds_read_b128 v[232:235], v223 offset:54272
	ds_read_b128 v[236:239], v223 offset:55296
	ds_read_b128 v[240:243], v223 offset:56320
	s_waitcnt vmcnt(8)
	s_waitcnt lgkmcnt(0)
	s_barrier
	s_setprio 1
	s_waitcnt lgkmcnt(0)
	v_mfma_f32_16x16x32_bf16 v[60:63], v[128:131], v[188:191], v[60:63]
	v_mfma_f32_16x16x32_bf16 v[56:59], v[136:139], v[188:191], v[56:59]
	v_mfma_f32_16x16x32_bf16 v[52:55], v[128:131], v[196:199], v[52:55]
	v_mfma_f32_16x16x32_bf16 v[44:47], v[136:139], v[196:199], v[44:47]
	v_mfma_f32_16x16x32_bf16 v[36:39], v[128:131], v[228:231], v[36:39]
	v_mfma_f32_16x16x32_bf16 v[28:31], v[136:139], v[228:231], v[28:31]
	v_mfma_f32_16x16x32_bf16 v[20:23], v[128:131], v[236:239], v[20:23]
	v_mfma_f32_16x16x32_bf16 v[12:15], v[136:139], v[236:239], v[12:15]
	v_mfma_f32_16x16x32_bf16 v[60:63], v[132:135], v[192:195], v[60:63]
	v_mfma_f32_16x16x32_bf16 v[56:59], v[140:143], v[192:195], v[56:59]
	v_mfma_f32_16x16x32_bf16 v[52:55], v[132:135], v[200:203], v[52:55]
	v_mfma_f32_16x16x32_bf16 v[44:47], v[140:143], v[200:203], v[44:47]
	v_mfma_f32_16x16x32_bf16 v[36:39], v[132:135], v[232:235], v[36:39]
	v_mfma_f32_16x16x32_bf16 v[28:31], v[140:143], v[232:235], v[28:31]
	v_mfma_f32_16x16x32_bf16 v[20:23], v[132:135], v[240:243], v[20:23]
	v_mfma_f32_16x16x32_bf16 v[12:15], v[140:143], v[240:243], v[12:15]
	s_setprio 0
	s_setprio 1
	v_mfma_f32_16x16x32_bf16 v[48:51], v[144:147], v[188:191], v[48:51]
	v_mfma_f32_16x16x32_bf16 v[40:43], v[152:155], v[188:191], v[40:43]
	v_mfma_f32_16x16x32_bf16 v[32:35], v[144:147], v[196:199], v[32:35]
	v_mfma_f32_16x16x32_bf16 v[24:27], v[152:155], v[196:199], v[24:27]
	v_mfma_f32_16x16x32_bf16 v[16:19], v[144:147], v[228:231], v[16:19]
	v_mfma_f32_16x16x32_bf16 v[8:11], v[152:155], v[228:231], v[8:11]
	v_mfma_f32_16x16x32_bf16 v[4:7], v[144:147], v[236:239], v[4:7]
	v_mfma_f32_16x16x32_bf16 v[0:3], v[152:155], v[236:239], v[0:3]
	v_mfma_f32_16x16x32_bf16 v[48:51], v[148:151], v[192:195], v[48:51]
	v_mfma_f32_16x16x32_bf16 v[40:43], v[156:159], v[192:195], v[40:43]
	v_mfma_f32_16x16x32_bf16 v[32:35], v[148:151], v[200:203], v[32:35]
	v_mfma_f32_16x16x32_bf16 v[24:27], v[156:159], v[200:203], v[24:27]
	v_mfma_f32_16x16x32_bf16 v[16:19], v[148:151], v[232:235], v[16:19]
	v_mfma_f32_16x16x32_bf16 v[8:11], v[156:159], v[232:235], v[8:11]
	v_mfma_f32_16x16x32_bf16 v[4:7], v[148:151], v[240:243], v[4:7]
	v_mfma_f32_16x16x32_bf16 v[0:3], v[156:159], v[240:243], v[0:3]
	s_setprio 0
	s_barrier
	s_add_i32 s27, s27, 2
	s_add_u32 s42, s42, 0x100
	s_addc_u32 s43, s43, 0
	s_add_u32 s25, s25, 0x100
	s_addc_u32 s26, s26, 0
	s_cmp_gt_u32 s27, 13
	s_cbranch_scc0 .LBB0_204
	s_and_b64 vcc, exec, s[50:51]
	s_cbranch_vccz .LBB0_207
	s_barrier

.LBB0_502:
	s_add_i32 s62, 0, 0x10000
	s_add_i32 s61, 0, 0x14000
	v_add_u32_e32 v19, s62, v16
	v_add_u32_e32 v20, s61, v16
	s_add_u32 s58, s50, 0x18080
	s_addc_u32 s59, s51, 0
	s_add_i32 s65, s26, 0xc000
	v_lshl_add_u64 v[78:79], s[58:59], 0, v[6:7]
	s_mov_b32 m0, s65
	s_add_i32 s57, s26, 0xe000
	global_load_lds_dwordx4 v[78:79], off
	v_lshl_add_u64 v[78:79], s[58:59], 0, v[2:3]
	s_mov_b32 m0, s57
	s_nop 0
	global_load_lds_dwordx4 v[78:79], off
	ds_read_b128 v[22:25], v19
	ds_read_b128 v[26:29], v19 offset:1024
	ds_read_b128 v[30:33], v19 offset:2048
	ds_read_b128 v[34:37], v19 offset:3072
	ds_read_b128 v[38:41], v20
	ds_read_b128 v[42:45], v20 offset:1024
	ds_read_b128 v[46:49], v20 offset:2048
	ds_read_b128 v[50:53], v20 offset:3072
	ds_read_b128 v[8:11], v17
	ds_read_b128 v[12:15], v17 offset:1024
	ds_read_b128 v[54:57], v17 offset:2048
	ds_read_b128 v[58:61], v17 offset:3072
	ds_read_b128 v[62:65], v17 offset:4096
	ds_read_b128 v[66:69], v17 offset:5120
	ds_read_b128 v[70:73], v17 offset:6144
	ds_read_b128 v[74:77], v17 offset:7168
	s_waitcnt vmcnt(8)
	s_waitcnt lgkmcnt(0)
	s_barrier
	s_setprio 1
	s_waitcnt lgkmcnt(0)
	v_mfma_f32_16x16x32_bf16 v[78:81], v[22:25], v[8:11], 0
	v_mfma_f32_16x16x32_bf16 v[82:85], v[30:33], v[8:11], 0
	v_mfma_f32_16x16x32_bf16 v[86:89], v[22:25], v[54:57], 0
	v_mfma_f32_16x16x32_bf16 v[90:93], v[30:33], v[54:57], 0
	v_mfma_f32_16x16x32_bf16 v[94:97], v[22:25], v[62:65], 0
	v_mfma_f32_16x16x32_bf16 v[98:101], v[30:33], v[62:65], 0
	v_mfma_f32_16x16x32_bf16 v[102:105], v[22:25], v[70:73], 0
	v_mfma_f32_16x16x32_bf16 v[106:109], v[30:33], v[70:73], 0
	v_mfma_f32_16x16x32_bf16 v[78:81], v[26:29], v[12:15], v[78:81]
	v_mfma_f32_16x16x32_bf16 v[82:85], v[34:37], v[12:15], v[82:85]
	v_mfma_f32_16x16x32_bf16 v[86:89], v[26:29], v[58:61], v[86:89]
	v_mfma_f32_16x16x32_bf16 v[90:93], v[34:37], v[58:61], v[90:93]
	v_mfma_f32_16x16x32_bf16 v[94:97], v[26:29], v[66:69], v[94:97]
	v_mfma_f32_16x16x32_bf16 v[98:101], v[34:37], v[66:69], v[98:101]
	v_mfma_f32_16x16x32_bf16 v[102:105], v[26:29], v[74:77], v[102:105]
	v_mfma_f32_16x16x32_bf16 v[106:109], v[34:37], v[74:77], v[106:109]
	s_setprio 0
	s_setprio 1
	v_mfma_f32_16x16x32_bf16 v[110:113], v[38:41], v[8:11], 0
	v_mfma_f32_16x16x32_bf16 v[8:11], v[46:49], v[8:11], 0
	v_mfma_f32_16x16x32_bf16 v[114:117], v[50:53], v[12:15], v[8:11]
	v_mfma_f32_16x16x32_bf16 v[8:11], v[38:41], v[54:57], 0
	v_mfma_f32_16x16x32_bf16 v[118:121], v[42:45], v[58:61], v[8:11]
	v_mfma_f32_16x16x32_bf16 v[8:11], v[46:49], v[54:57], 0
	v_mfma_f32_16x16x32_bf16 v[54:57], v[50:53], v[58:61], v[8:11]
	v_mfma_f32_16x16x32_bf16 v[8:11], v[38:41], v[62:65], 0
	v_mfma_f32_16x16x32_bf16 v[58:61], v[42:45], v[66:69], v[8:11]
	v_mfma_f32_16x16x32_bf16 v[8:11], v[46:49], v[62:65], 0
	v_mfma_f32_16x16x32_bf16 v[62:65], v[50:53], v[66:69], v[8:11]
	v_mfma_f32_16x16x32_bf16 v[8:11], v[38:41], v[70:73], 0
	v_mfma_f32_16x16x32_bf16 v[66:69], v[42:45], v[74:77], v[8:11]
	v_mfma_f32_16x16x32_bf16 v[8:11], v[46:49], v[70:73], 0
	v_mfma_f32_16x16x32_bf16 v[110:113], v[42:45], v[12:15], v[110:113]
	v_mfma_f32_16x16x32_bf16 v[70:73], v[50:53], v[74:77], v[8:11]
	s_setprio 0
	s_barrier
	s_nop 3
	v_lshl_add_u64 v[8:9], s[52:53], 0, v[4:5]
	s_mov_b64 s[68:69], 0x100
	s_add_i32 s62, s62, s25
	v_lshl_add_u64 v[10:11], v[8:9], 0, s[68:69]
	s_mov_b32 m0, s62
	s_add_i32 s58, s62, 0x2000
	global_load_lds_dwordx4 v[10:11], off
	v_lshl_add_u64 v[10:11], s[52:53], 0, v[0:1]
	s_add_u32 s66, s52, 0x18100
	v_lshl_add_u64 v[12:13], v[10:11], 0, s[68:69]
	s_mov_b32 m0, s58
	s_addc_u32 s67, s53, 0
	s_add_i32 s59, s61, s25
	global_load_lds_dwordx4 v[12:13], off
	v_lshl_add_u64 v[12:13], s[66:67], 0, v[4:5]
	s_mov_b32 m0, s59
	s_add_i32 s61, s59, 0x2000
	global_load_lds_dwordx4 v[12:13], off
	v_lshl_add_u64 v[12:13], s[66:67], 0, v[0:1]
	s_mov_b32 m0, s61
	s_nop 0
	global_load_lds_dwordx4 v[12:13], off
	v_lshl_add_u64 v[12:13], s[50:51], 0, v[6:7]
	v_lshl_add_u64 v[14:15], v[12:13], 0, s[68:69]
	s_mov_b32 m0, s26
	s_nop 0
	global_load_lds_dwordx4 v[14:15], off
	v_lshl_add_u64 v[14:15], s[50:51], 0, v[2:3]
	v_lshl_add_u64 v[150:151], v[14:15], 0, s[68:69]
	s_mov_b32 m0, s27
	s_nop 0
	global_load_lds_dwordx4 v[150:151], off
	ds_read_b128 v[74:77], v17 offset:16384
	ds_read_b128 v[122:125], v17 offset:17408
	ds_read_b128 v[126:129], v17 offset:18432
	ds_read_b128 v[130:133], v17 offset:19456
	ds_read_b128 v[134:137], v17 offset:20480
	ds_read_b128 v[138:141], v17 offset:21504
	ds_read_b128 v[142:145], v17 offset:22528
	ds_read_b128 v[146:149], v17 offset:23552
	s_waitcnt vmcnt(8)
	s_waitcnt lgkmcnt(0)
	s_barrier
	s_setprio 1
	s_waitcnt lgkmcnt(0)
	v_mfma_f32_16x16x32_bf16 v[150:153], v[22:25], v[74:77], 0
	v_mfma_f32_16x16x32_bf16 v[178:181], v[22:25], v[126:129], 0
	v_mfma_f32_16x16x32_bf16 v[186:189], v[22:25], v[134:137], 0
	v_mfma_f32_16x16x32_bf16 v[22:25], v[22:25], v[142:145], 0
	v_mfma_f32_16x16x32_bf16 v[150:153], v[26:29], v[122:125], v[150:153]
	v_mfma_f32_16x16x32_bf16 v[154:157], v[30:33], v[74:77], 0
	v_mfma_f32_16x16x32_bf16 v[178:181], v[26:29], v[130:133], v[178:181]
	v_mfma_f32_16x16x32_bf16 v[182:185], v[30:33], v[126:129], 0
	v_mfma_f32_16x16x32_bf16 v[186:189], v[26:29], v[138:141], v[186:189]
	v_mfma_f32_16x16x32_bf16 v[190:193], v[30:33], v[134:137], 0
	v_mfma_f32_16x16x32_bf16 v[24:27], v[26:29], v[146:149], v[22:25]
	v_mfma_f32_16x16x32_bf16 v[28:31], v[30:33], v[142:145], 0
	v_mfma_f32_16x16x32_bf16 v[154:157], v[34:37], v[122:125], v[154:157]
	v_mfma_f32_16x16x32_bf16 v[182:185], v[34:37], v[130:133], v[182:185]
	v_mfma_f32_16x16x32_bf16 v[190:193], v[34:37], v[138:141], v[190:193]
	v_mfma_f32_16x16x32_bf16 v[28:31], v[34:37], v[146:149], v[28:31]
	s_setprio 0
	s_setprio 1
	v_mfma_f32_16x16x32_bf16 v[32:35], v[38:41], v[74:77], 0
	v_mfma_f32_16x16x32_bf16 v[74:77], v[46:49], v[74:77], 0
	v_mfma_f32_16x16x32_bf16 v[32:35], v[42:45], v[122:125], v[32:35]
	v_mfma_f32_16x16x32_bf16 v[74:77], v[50:53], v[122:125], v[74:77]
	v_mfma_f32_16x16x32_bf16 v[122:125], v[38:41], v[126:129], 0
	v_mfma_f32_16x16x32_bf16 v[126:129], v[46:49], v[126:129], 0
	v_mfma_f32_16x16x32_bf16 v[122:125], v[42:45], v[130:133], v[122:125]
	v_mfma_f32_16x16x32_bf16 v[126:129], v[50:53], v[130:133], v[126:129]
	v_mfma_f32_16x16x32_bf16 v[130:133], v[38:41], v[134:137], 0
	v_mfma_f32_16x16x32_bf16 v[36:39], v[38:41], v[142:145], 0
	v_mfma_f32_16x16x32_bf16 v[130:133], v[42:45], v[138:141], v[130:133]
	v_mfma_f32_16x16x32_bf16 v[134:137], v[46:49], v[134:137], 0
	v_mfma_f32_16x16x32_bf16 v[36:39], v[42:45], v[146:149], v[36:39]
	v_mfma_f32_16x16x32_bf16 v[40:43], v[46:49], v[142:145], 0
	v_mfma_f32_16x16x32_bf16 v[134:137], v[50:53], v[138:141], v[134:137]
	v_mfma_f32_16x16x32_bf16 v[40:43], v[50:53], v[146:149], v[40:43]
	s_setprio 0
	s_barrier
	s_add_i32 s63, 0, 0x18000
	s_add_i32 s64, 0, 0x1c000
	v_add_u32_e32 v21, s63, v16
	v_add_u32_e32 v22, s64, v16
	s_add_u32 s66, s50, 0x18100
	s_addc_u32 s67, s51, 0
	s_mov_b32 m0, s28
	v_lshl_add_u64 v[52:53], s[66:67], 0, v[6:7]
	global_load_lds_dwordx4 v[52:53], off
	v_lshl_add_u64 v[52:53], s[66:67], 0, v[2:3]
	s_mov_b32 m0, s29
	s_nop 0
	global_load_lds_dwordx4 v[52:53], off
	ds_read_b128 v[44:47], v21
	ds_read_b128 v[48:51], v21 offset:1024
	ds_read_b128 v[138:141], v21 offset:2048
	ds_read_b128 v[142:145], v21 offset:3072
	ds_read_b128 v[146:149], v22
	ds_read_b128 v[194:197], v22 offset:1024
	ds_read_b128 v[198:201], v22 offset:2048
	ds_read_b128 v[202:205], v22 offset:3072
	ds_read_b128 v[220:223], v17 offset:32768
	ds_read_b128 v[228:231], v17 offset:33792
	ds_read_b128 v[232:235], v17 offset:34816
	ds_read_b128 v[236:239], v17 offset:35840
	ds_read_b128 v[240:243], v17 offset:36864
	ds_read_b128 v[244:247], v17 offset:37888
	ds_read_b128 v[248:251], v17 offset:38912
	ds_read_b128 v[174:177], v17 offset:39936
	s_waitcnt vmcnt(8)
	s_waitcnt lgkmcnt(0)
	s_barrier
	s_setprio 1
	s_waitcnt lgkmcnt(0)
	v_mfma_f32_16x16x32_bf16 v[78:81], v[44:47], v[220:223], v[78:81]
	v_mfma_f32_16x16x32_bf16 v[82:85], v[138:141], v[220:223], v[82:85]
	v_mfma_f32_16x16x32_bf16 v[86:89], v[44:47], v[232:235], v[86:89]
	v_mfma_f32_16x16x32_bf16 v[90:93], v[138:141], v[232:235], v[90:93]
	v_mfma_f32_16x16x32_bf16 v[94:97], v[44:47], v[240:243], v[94:97]
	v_mfma_f32_16x16x32_bf16 v[98:101], v[138:141], v[240:243], v[98:101]
	v_mfma_f32_16x16x32_bf16 v[102:105], v[44:47], v[248:251], v[102:105]
	v_mfma_f32_16x16x32_bf16 v[106:109], v[138:141], v[248:251], v[106:109]
	v_mfma_f32_16x16x32_bf16 v[78:81], v[48:51], v[228:231], v[78:81]
	v_mfma_f32_16x16x32_bf16 v[82:85], v[142:145], v[228:231], v[82:85]
	v_mfma_f32_16x16x32_bf16 v[86:89], v[48:51], v[236:239], v[86:89]
	v_mfma_f32_16x16x32_bf16 v[90:93], v[142:145], v[236:239], v[90:93]
	v_mfma_f32_16x16x32_bf16 v[94:97], v[48:51], v[244:247], v[94:97]
	v_mfma_f32_16x16x32_bf16 v[98:101], v[142:145], v[244:247], v[98:101]
	v_mfma_f32_16x16x32_bf16 v[102:105], v[48:51], v[174:177], v[102:105]
	v_mfma_f32_16x16x32_bf16 v[106:109], v[142:145], v[174:177], v[106:109]
	s_setprio 0
	s_setprio 1
	v_mfma_f32_16x16x32_bf16 v[110:113], v[146:149], v[220:223], v[110:113]
	v_mfma_f32_16x16x32_bf16 v[114:117], v[198:201], v[220:223], v[114:117]
	v_mfma_f32_16x16x32_bf16 v[118:121], v[146:149], v[232:235], v[118:121]
	v_mfma_f32_16x16x32_bf16 v[52:55], v[198:201], v[232:235], v[54:57]
	v_mfma_f32_16x16x32_bf16 v[56:59], v[146:149], v[240:243], v[58:61]
	v_mfma_f32_16x16x32_bf16 v[60:63], v[198:201], v[240:243], v[62:65]
	v_mfma_f32_16x16x32_bf16 v[64:67], v[146:149], v[248:251], v[66:69]
	v_mfma_f32_16x16x32_bf16 v[68:71], v[198:201], v[248:251], v[70:73]
	v_mfma_f32_16x16x32_bf16 v[110:113], v[194:197], v[228:231], v[110:113]
	v_mfma_f32_16x16x32_bf16 v[114:117], v[202:205], v[228:231], v[114:117]
	v_mfma_f32_16x16x32_bf16 v[118:121], v[194:197], v[236:239], v[118:121]
	v_mfma_f32_16x16x32_bf16 v[52:55], v[202:205], v[236:239], v[52:55]
	v_mfma_f32_16x16x32_bf16 v[56:59], v[194:197], v[244:247], v[56:59]
	v_mfma_f32_16x16x32_bf16 v[60:63], v[202:205], v[244:247], v[60:63]
	v_mfma_f32_16x16x32_bf16 v[64:67], v[194:197], v[174:177], v[64:67]
	v_mfma_f32_16x16x32_bf16 v[68:71], v[202:205], v[174:177], v[68:71]
	s_setprio 0
	s_barrier
	s_add_i32 s67, s63, s25
	s_mov_b64 s[70:71], 0x180
	s_add_i32 s63, s67, 0x2000
	v_lshl_add_u64 v[72:73], v[8:9], 0, s[70:71]
	s_mov_b32 m0, s67
	s_add_u32 s68, s52, 0x18180
	global_load_lds_dwordx4 v[72:73], off
	v_lshl_add_u64 v[72:73], v[10:11], 0, s[70:71]
	s_mov_b32 m0, s63
	s_addc_u32 s69, s53, 0
	s_add_i32 s64, s64, s25
	global_load_lds_dwordx4 v[72:73], off
	v_lshl_add_u64 v[72:73], s[68:69], 0, v[4:5]
	s_mov_b32 m0, s64
	s_add_i32 s66, s64, 0x2000
	global_load_lds_dwordx4 v[72:73], off
	v_lshl_add_u64 v[72:73], s[68:69], 0, v[0:1]
	s_mov_b32 m0, s66
	s_nop 0
	global_load_lds_dwordx4 v[72:73], off
	v_lshl_add_u64 v[72:73], v[12:13], 0, s[70:71]
	s_mov_b32 m0, s30
	s_nop 0
	global_load_lds_dwordx4 v[72:73], off
	v_lshl_add_u64 v[72:73], v[14:15], 0, s[70:71]
	s_mov_b32 m0, s31
	s_nop 0
	global_load_lds_dwordx4 v[72:73], off
	ds_read_b128 v[174:177], v17 offset:49152
	ds_read_b128 v[220:223], v17 offset:50176
	ds_read_b128 v[228:231], v17 offset:51200
	ds_read_b128 v[232:235], v17 offset:52224
	ds_read_b128 v[236:239], v17 offset:53248
	ds_read_b128 v[240:243], v17 offset:54272
	ds_read_b128 v[244:247], v17 offset:55296
	ds_read_b128 v[248:251], v17 offset:56320
	s_waitcnt vmcnt(8)
	s_waitcnt lgkmcnt(0)
	s_barrier
	s_setprio 1
	s_waitcnt lgkmcnt(0)
	v_mfma_f32_16x16x32_bf16 v[150:153], v[44:47], v[174:177], v[150:153]
	v_mfma_f32_16x16x32_bf16 v[154:157], v[138:141], v[174:177], v[154:157]
	v_mfma_f32_16x16x32_bf16 v[178:181], v[44:47], v[228:231], v[178:181]
	v_mfma_f32_16x16x32_bf16 v[182:185], v[138:141], v[228:231], v[182:185]
	v_mfma_f32_16x16x32_bf16 v[186:189], v[44:47], v[236:239], v[186:189]
	v_mfma_f32_16x16x32_bf16 v[190:193], v[138:141], v[236:239], v[190:193]
	v_mfma_f32_16x16x32_bf16 v[24:27], v[44:47], v[244:247], v[24:27]
	v_mfma_f32_16x16x32_bf16 v[28:31], v[138:141], v[244:247], v[28:31]
	v_mfma_f32_16x16x32_bf16 v[150:153], v[48:51], v[220:223], v[150:153]
	v_mfma_f32_16x16x32_bf16 v[154:157], v[142:145], v[220:223], v[154:157]
	v_mfma_f32_16x16x32_bf16 v[178:181], v[48:51], v[232:235], v[178:181]
	v_mfma_f32_16x16x32_bf16 v[182:185], v[142:145], v[232:235], v[182:185]
	v_mfma_f32_16x16x32_bf16 v[186:189], v[48:51], v[240:243], v[186:189]
	v_mfma_f32_16x16x32_bf16 v[190:193], v[142:145], v[240:243], v[190:193]
	v_mfma_f32_16x16x32_bf16 v[24:27], v[48:51], v[248:251], v[24:27]
	v_mfma_f32_16x16x32_bf16 v[28:31], v[142:145], v[248:251], v[28:31]
	s_setprio 0
	s_setprio 1
	v_mfma_f32_16x16x32_bf16 v[32:35], v[146:149], v[174:177], v[32:35]
	v_mfma_f32_16x16x32_bf16 v[44:47], v[198:201], v[174:177], v[74:77]
	v_mfma_f32_16x16x32_bf16 v[48:51], v[146:149], v[228:231], v[122:125]
	v_mfma_f32_16x16x32_bf16 v[72:75], v[198:201], v[228:231], v[126:129]
	v_mfma_f32_16x16x32_bf16 v[122:125], v[146:149], v[236:239], v[130:133]
	v_mfma_f32_16x16x32_bf16 v[126:129], v[198:201], v[236:239], v[134:137]
	v_mfma_f32_16x16x32_bf16 v[36:39], v[146:149], v[244:247], v[36:39]
	v_mfma_f32_16x16x32_bf16 v[40:43], v[198:201], v[244:247], v[40:43]
	v_mfma_f32_16x16x32_bf16 v[32:35], v[194:197], v[220:223], v[32:35]
	v_mfma_f32_16x16x32_bf16 v[44:47], v[202:205], v[220:223], v[44:47]
	v_mfma_f32_16x16x32_bf16 v[48:51], v[194:197], v[232:235], v[48:51]
	v_mfma_f32_16x16x32_bf16 v[72:75], v[202:205], v[232:235], v[72:75]
	v_mfma_f32_16x16x32_bf16 v[122:125], v[194:197], v[240:243], v[122:125]
	v_mfma_f32_16x16x32_bf16 v[126:129], v[202:205], v[240:243], v[126:129]
	v_mfma_f32_16x16x32_bf16 v[36:39], v[194:197], v[248:251], v[36:39]
	v_mfma_f32_16x16x32_bf16 v[40:43], v[202:205], v[248:251], v[40:43]
	s_setprio 0
	s_barrier
	s_add_u32 s68, s50, 0x18180
	s_addc_u32 s69, s51, 0
	s_mov_b32 m0, s65
	v_lshl_add_u64 v[76:77], s[68:69], 0, v[6:7]
	global_load_lds_dwordx4 v[76:77], off
	v_lshl_add_u64 v[76:77], s[68:69], 0, v[2:3]
	s_mov_b32 m0, s57
	s_nop 0
	global_load_lds_dwordx4 v[76:77], off
	ds_read_b128 v[130:133], v19
	ds_read_b128 v[134:137], v19 offset:1024
	ds_read_b128 v[138:141], v19 offset:2048
	ds_read_b128 v[142:145], v19 offset:3072
	ds_read_b128 v[146:149], v20
	ds_read_b128 v[174:177], v20 offset:1024
	ds_read_b128 v[194:197], v20 offset:2048
	ds_read_b128 v[198:201], v20 offset:3072
	ds_read_b128 v[202:205], v17
	ds_read_b128 v[220:223], v17 offset:1024
	ds_read_b128 v[228:231], v17 offset:2048
	ds_read_b128 v[232:235], v17 offset:3072
	ds_read_b128 v[236:239], v17 offset:4096
	ds_read_b128 v[240:243], v17 offset:5120
	ds_read_b128 v[244:247], v17 offset:6144
	ds_read_b128 v[248:251], v17 offset:7168
	s_waitcnt vmcnt(8)
	s_waitcnt lgkmcnt(0)
	s_barrier
	s_setprio 1
	s_waitcnt lgkmcnt(0)
	v_mfma_f32_16x16x32_bf16 v[76:79], v[130:133], v[202:205], v[78:81]
	v_mfma_f32_16x16x32_bf16 v[80:83], v[138:141], v[202:205], v[82:85]
	v_mfma_f32_16x16x32_bf16 v[84:87], v[130:133], v[228:231], v[86:89]
	v_mfma_f32_16x16x32_bf16 v[88:91], v[138:141], v[228:231], v[90:93]
	v_mfma_f32_16x16x32_bf16 v[92:95], v[130:133], v[236:239], v[94:97]
	v_mfma_f32_16x16x32_bf16 v[96:99], v[138:141], v[236:239], v[98:101]
	v_mfma_f32_16x16x32_bf16 v[100:103], v[130:133], v[244:247], v[102:105]
	v_mfma_f32_16x16x32_bf16 v[104:107], v[138:141], v[244:247], v[106:109]
	v_mfma_f32_16x16x32_bf16 v[76:79], v[134:137], v[220:223], v[76:79]
	v_mfma_f32_16x16x32_bf16 v[80:83], v[142:145], v[220:223], v[80:83]
	v_mfma_f32_16x16x32_bf16 v[84:87], v[134:137], v[232:235], v[84:87]
	v_mfma_f32_16x16x32_bf16 v[88:91], v[142:145], v[232:235], v[88:91]
	v_mfma_f32_16x16x32_bf16 v[92:95], v[134:137], v[240:243], v[92:95]
	v_mfma_f32_16x16x32_bf16 v[96:99], v[142:145], v[240:243], v[96:99]
	v_mfma_f32_16x16x32_bf16 v[100:103], v[134:137], v[248:251], v[100:103]
	v_mfma_f32_16x16x32_bf16 v[104:107], v[142:145], v[248:251], v[104:107]
	s_setprio 0
	s_setprio 1
	v_mfma_f32_16x16x32_bf16 v[108:111], v[146:149], v[202:205], v[110:113]
	v_mfma_f32_16x16x32_bf16 v[112:115], v[194:197], v[202:205], v[114:117]
	v_mfma_f32_16x16x32_bf16 v[116:119], v[146:149], v[228:231], v[118:121]
	v_mfma_f32_16x16x32_bf16 v[52:55], v[194:197], v[228:231], v[52:55]
	v_mfma_f32_16x16x32_bf16 v[56:59], v[146:149], v[236:239], v[56:59]
	v_mfma_f32_16x16x32_bf16 v[60:63], v[194:197], v[236:239], v[60:63]
	v_mfma_f32_16x16x32_bf16 v[64:67], v[146:149], v[244:247], v[64:67]
	v_mfma_f32_16x16x32_bf16 v[68:71], v[194:197], v[244:247], v[68:71]
	v_mfma_f32_16x16x32_bf16 v[108:111], v[174:177], v[220:223], v[108:111]
	v_mfma_f32_16x16x32_bf16 v[112:115], v[198:201], v[220:223], v[112:115]
	v_mfma_f32_16x16x32_bf16 v[116:119], v[174:177], v[232:235], v[116:119]
	v_mfma_f32_16x16x32_bf16 v[52:55], v[198:201], v[232:235], v[52:55]
	v_mfma_f32_16x16x32_bf16 v[56:59], v[174:177], v[240:243], v[56:59]
	v_mfma_f32_16x16x32_bf16 v[60:63], v[198:201], v[240:243], v[60:63]
	v_mfma_f32_16x16x32_bf16 v[64:67], v[174:177], v[248:251], v[64:67]
	v_mfma_f32_16x16x32_bf16 v[68:71], v[198:201], v[248:251], v[68:71]
	s_setprio 0
	s_barrier
	s_mov_b64 s[70:71], 0x200
	s_mov_b32 m0, s62
	v_lshl_add_u64 v[120:121], v[8:9], 0, s[70:71]
	s_add_u32 s68, s52, 0x18200
	global_load_lds_dwordx4 v[120:121], off
	v_lshl_add_u64 v[120:121], v[10:11], 0, s[70:71]
	s_mov_b32 m0, s58
	s_addc_u32 s69, s53, 0
	global_load_lds_dwordx4 v[120:121], off
	v_lshl_add_u64 v[120:121], s[68:69], 0, v[4:5]
	s_mov_b32 m0, s59
	s_nop 0
	global_load_lds_dwordx4 v[120:121], off
	v_lshl_add_u64 v[120:121], s[68:69], 0, v[0:1]
	s_mov_b32 m0, s61
	s_nop 0
	global_load_lds_dwordx4 v[120:121], off
	v_lshl_add_u64 v[120:121], v[12:13], 0, s[70:71]
	s_mov_b32 m0, s26
	s_nop 0
	global_load_lds_dwordx4 v[120:121], off
	v_lshl_add_u64 v[120:121], v[14:15], 0, s[70:71]
	s_mov_b32 m0, s27
	s_nop 0
	global_load_lds_dwordx4 v[120:121], off
	ds_read_b128 v[202:205], v17 offset:16384
	ds_read_b128 v[220:223], v17 offset:17408
	ds_read_b128 v[228:231], v17 offset:18432
	ds_read_b128 v[232:235], v17 offset:19456
	ds_read_b128 v[236:239], v17 offset:20480
	ds_read_b128 v[240:243], v17 offset:21504
	ds_read_b128 v[244:247], v17 offset:22528
	ds_read_b128 v[248:251], v17 offset:23552
	s_waitcnt vmcnt(8)
	s_waitcnt lgkmcnt(0)
	s_barrier
	s_setprio 1
	s_waitcnt lgkmcnt(0)
	v_mfma_f32_16x16x32_bf16 v[150:153], v[130:133], v[202:205], v[150:153]
	v_mfma_f32_16x16x32_bf16 v[154:157], v[138:141], v[202:205], v[154:157]
	v_mfma_f32_16x16x32_bf16 v[178:181], v[130:133], v[228:231], v[178:181]
	v_mfma_f32_16x16x32_bf16 v[182:185], v[138:141], v[228:231], v[182:185]
	v_mfma_f32_16x16x32_bf16 v[186:189], v[130:133], v[236:239], v[186:189]
	v_mfma_f32_16x16x32_bf16 v[190:193], v[138:141], v[236:239], v[190:193]
	v_mfma_f32_16x16x32_bf16 v[24:27], v[130:133], v[244:247], v[24:27]
	v_mfma_f32_16x16x32_bf16 v[28:31], v[138:141], v[244:247], v[28:31]
	v_mfma_f32_16x16x32_bf16 v[150:153], v[134:137], v[220:223], v[150:153]
	v_mfma_f32_16x16x32_bf16 v[154:157], v[142:145], v[220:223], v[154:157]
	v_mfma_f32_16x16x32_bf16 v[178:181], v[134:137], v[232:235], v[178:181]
	v_mfma_f32_16x16x32_bf16 v[182:185], v[142:145], v[232:235], v[182:185]
	v_mfma_f32_16x16x32_bf16 v[186:189], v[134:137], v[240:243], v[186:189]
	v_mfma_f32_16x16x32_bf16 v[190:193], v[142:145], v[240:243], v[190:193]
	v_mfma_f32_16x16x32_bf16 v[24:27], v[134:137], v[248:251], v[24:27]
	v_mfma_f32_16x16x32_bf16 v[28:31], v[142:145], v[248:251], v[28:31]
	s_setprio 0
	s_setprio 1
	v_mfma_f32_16x16x32_bf16 v[32:35], v[146:149], v[202:205], v[32:35]
	v_mfma_f32_16x16x32_bf16 v[44:47], v[194:197], v[202:205], v[44:47]
	v_mfma_f32_16x16x32_bf16 v[48:51], v[146:149], v[228:231], v[48:51]
	v_mfma_f32_16x16x32_bf16 v[72:75], v[194:197], v[228:231], v[72:75]
	v_mfma_f32_16x16x32_bf16 v[120:123], v[146:149], v[236:239], v[122:125]
	v_mfma_f32_16x16x32_bf16 v[124:127], v[194:197], v[236:239], v[126:129]
	v_mfma_f32_16x16x32_bf16 v[36:39], v[146:149], v[244:247], v[36:39]
	v_mfma_f32_16x16x32_bf16 v[40:43], v[194:197], v[244:247], v[40:43]
	v_mfma_f32_16x16x32_bf16 v[32:35], v[174:177], v[220:223], v[32:35]
	v_mfma_f32_16x16x32_bf16 v[44:47], v[198:201], v[220:223], v[44:47]
	v_mfma_f32_16x16x32_bf16 v[48:51], v[174:177], v[232:235], v[48:51]
	v_mfma_f32_16x16x32_bf16 v[72:75], v[198:201], v[232:235], v[72:75]
	v_mfma_f32_16x16x32_bf16 v[120:123], v[174:177], v[240:243], v[120:123]
	v_mfma_f32_16x16x32_bf16 v[124:127], v[198:201], v[240:243], v[124:127]
	v_mfma_f32_16x16x32_bf16 v[36:39], v[174:177], v[248:251], v[36:39]
	v_mfma_f32_16x16x32_bf16 v[40:43], v[198:201], v[248:251], v[40:43]
	s_setprio 0
	s_barrier
	s_add_u32 s68, s50, 0x18200
	s_addc_u32 s69, s51, 0
	s_mov_b32 m0, s28
	v_lshl_add_u64 v[148:149], s[68:69], 0, v[6:7]
	global_load_lds_dwordx4 v[148:149], off
	v_lshl_add_u64 v[148:149], s[68:69], 0, v[2:3]
	s_mov_b32 m0, s29
	s_nop 0
	global_load_lds_dwordx4 v[148:149], off
	ds_read_b128 v[128:131], v21
	ds_read_b128 v[132:135], v21 offset:1024
	ds_read_b128 v[136:139], v21 offset:2048
	ds_read_b128 v[140:143], v21 offset:3072
	ds_read_b128 v[144:147], v22
	ds_read_b128 v[174:177], v22 offset:1024
	ds_read_b128 v[194:197], v22 offset:2048
	ds_read_b128 v[198:201], v22 offset:3072
	ds_read_b128 v[202:205], v17 offset:32768
	ds_read_b128 v[220:223], v17 offset:33792
	ds_read_b128 v[228:231], v17 offset:34816
	ds_read_b128 v[232:235], v17 offset:35840
	ds_read_b128 v[236:239], v17 offset:36864
	ds_read_b128 v[240:243], v17 offset:37888
	ds_read_b128 v[244:247], v17 offset:38912
	ds_read_b128 v[248:251], v17 offset:39936
	s_waitcnt vmcnt(8)
	s_waitcnt lgkmcnt(0)
	s_barrier
	s_setprio 1
	s_waitcnt lgkmcnt(0)
	v_mfma_f32_16x16x32_bf16 v[76:79], v[128:131], v[202:205], v[76:79]
	v_mfma_f32_16x16x32_bf16 v[80:83], v[136:139], v[202:205], v[80:83]
	v_mfma_f32_16x16x32_bf16 v[84:87], v[128:131], v[228:231], v[84:87]
	v_mfma_f32_16x16x32_bf16 v[88:91], v[136:139], v[228:231], v[88:91]
	v_mfma_f32_16x16x32_bf16 v[92:95], v[128:131], v[236:239], v[92:95]
	v_mfma_f32_16x16x32_bf16 v[96:99], v[136:139], v[236:239], v[96:99]
	v_mfma_f32_16x16x32_bf16 v[100:103], v[128:131], v[244:247], v[100:103]
	v_mfma_f32_16x16x32_bf16 v[104:107], v[136:139], v[244:247], v[104:107]
	v_mfma_f32_16x16x32_bf16 v[76:79], v[132:135], v[220:223], v[76:79]
	v_mfma_f32_16x16x32_bf16 v[80:83], v[140:143], v[220:223], v[80:83]
	v_mfma_f32_16x16x32_bf16 v[84:87], v[132:135], v[232:235], v[84:87]
	v_mfma_f32_16x16x32_bf16 v[88:91], v[140:143], v[232:235], v[88:91]
	v_mfma_f32_16x16x32_bf16 v[92:95], v[132:135], v[240:243], v[92:95]
	v_mfma_f32_16x16x32_bf16 v[96:99], v[140:143], v[240:243], v[96:99]
	v_mfma_f32_16x16x32_bf16 v[100:103], v[132:135], v[248:251], v[100:103]
	v_mfma_f32_16x16x32_bf16 v[104:107], v[140:143], v[248:251], v[104:107]
	s_setprio 0
	s_setprio 1
	v_mfma_f32_16x16x32_bf16 v[108:111], v[144:147], v[202:205], v[108:111]
	v_mfma_f32_16x16x32_bf16 v[112:115], v[194:197], v[202:205], v[112:115]
	v_mfma_f32_16x16x32_bf16 v[116:119], v[144:147], v[228:231], v[116:119]
	v_mfma_f32_16x16x32_bf16 v[52:55], v[194:197], v[228:231], v[52:55]
	v_mfma_f32_16x16x32_bf16 v[56:59], v[144:147], v[236:239], v[56:59]
	v_mfma_f32_16x16x32_bf16 v[60:63], v[194:197], v[236:239], v[60:63]
	v_mfma_f32_16x16x32_bf16 v[64:67], v[144:147], v[244:247], v[64:67]
	v_mfma_f32_16x16x32_bf16 v[68:71], v[194:197], v[244:247], v[68:71]
	v_mfma_f32_16x16x32_bf16 v[108:111], v[174:177], v[220:223], v[108:111]
	v_mfma_f32_16x16x32_bf16 v[112:115], v[198:201], v[220:223], v[112:115]
	v_mfma_f32_16x16x32_bf16 v[116:119], v[174:177], v[232:235], v[116:119]
	v_mfma_f32_16x16x32_bf16 v[52:55], v[198:201], v[232:235], v[52:55]
	v_mfma_f32_16x16x32_bf16 v[56:59], v[174:177], v[240:243], v[56:59]
	v_mfma_f32_16x16x32_bf16 v[60:63], v[198:201], v[240:243], v[60:63]
	v_mfma_f32_16x16x32_bf16 v[64:67], v[174:177], v[248:251], v[64:67]
	v_mfma_f32_16x16x32_bf16 v[68:71], v[198:201], v[248:251], v[68:71]
	s_setprio 0
	s_barrier
	s_mov_b64 s[68:69], 0x280
	s_mov_b32 m0, s67
	v_lshl_add_u64 v[8:9], v[8:9], 0, s[68:69]
	s_add_u32 s52, s52, 0x18280
	global_load_lds_dwordx4 v[8:9], off
	v_lshl_add_u64 v[8:9], v[10:11], 0, s[68:69]
	s_mov_b32 m0, s63
	s_addc_u32 s53, s53, 0
	global_load_lds_dwordx4 v[8:9], off
	v_lshl_add_u64 v[8:9], s[52:53], 0, v[4:5]
	s_mov_b32 m0, s64
	s_nop 0
	global_load_lds_dwordx4 v[8:9], off
	v_lshl_add_u64 v[8:9], s[52:53], 0, v[0:1]
	s_mov_b32 m0, s66
	s_nop 0
	global_load_lds_dwordx4 v[8:9], off
	v_lshl_add_u64 v[8:9], v[12:13], 0, s[68:69]
	s_mov_b32 m0, s30
	s_nop 0
	global_load_lds_dwordx4 v[8:9], off
	v_lshl_add_u64 v[8:9], v[14:15], 0, s[68:69]
	s_mov_b32 m0, s31
	s_nop 0
	global_load_lds_dwordx4 v[8:9], off
	ds_read_b128 v[202:205], v17 offset:49152
	ds_read_b128 v[220:223], v17 offset:50176
	ds_read_b128 v[228:231], v17 offset:51200
	ds_read_b128 v[232:235], v17 offset:52224
	ds_read_b128 v[236:239], v17 offset:53248
	ds_read_b128 v[240:243], v17 offset:54272
	ds_read_b128 v[244:247], v17 offset:55296
	ds_read_b128 v[248:251], v17 offset:56320
	s_waitcnt vmcnt(8)
	s_waitcnt lgkmcnt(0)
	s_barrier
	s_setprio 1
	s_waitcnt lgkmcnt(0)
	v_mfma_f32_16x16x32_bf16 v[8:11], v[128:131], v[202:205], v[150:153]
	v_mfma_f32_16x16x32_bf16 v[12:15], v[136:139], v[202:205], v[154:157]
	v_mfma_f32_16x16x32_bf16 v[148:151], v[128:131], v[228:231], v[178:181]
	v_mfma_f32_16x16x32_bf16 v[152:155], v[136:139], v[228:231], v[182:185]
	v_mfma_f32_16x16x32_bf16 v[156:159], v[128:131], v[236:239], v[186:189]
	v_mfma_f32_16x16x32_bf16 v[178:181], v[136:139], v[236:239], v[190:193]
	v_mfma_f32_16x16x32_bf16 v[24:27], v[128:131], v[244:247], v[24:27]
	v_mfma_f32_16x16x32_bf16 v[28:31], v[136:139], v[244:247], v[28:31]
	v_mfma_f32_16x16x32_bf16 v[8:11], v[132:135], v[220:223], v[8:11]
	v_mfma_f32_16x16x32_bf16 v[12:15], v[140:143], v[220:223], v[12:15]
	v_mfma_f32_16x16x32_bf16 v[148:151], v[132:135], v[232:235], v[148:151]
	v_mfma_f32_16x16x32_bf16 v[152:155], v[140:143], v[232:235], v[152:155]
	v_mfma_f32_16x16x32_bf16 v[156:159], v[132:135], v[240:243], v[156:159]
	v_mfma_f32_16x16x32_bf16 v[178:181], v[140:143], v[240:243], v[178:181]
	v_mfma_f32_16x16x32_bf16 v[24:27], v[132:135], v[248:251], v[24:27]
	v_mfma_f32_16x16x32_bf16 v[28:31], v[140:143], v[248:251], v[28:31]
	s_setprio 0
	s_setprio 1
	v_mfma_f32_16x16x32_bf16 v[32:35], v[144:147], v[202:205], v[32:35]
	v_mfma_f32_16x16x32_bf16 v[44:47], v[194:197], v[202:205], v[44:47]
	v_mfma_f32_16x16x32_bf16 v[48:51], v[144:147], v[228:231], v[48:51]
	v_mfma_f32_16x16x32_bf16 v[72:75], v[194:197], v[228:231], v[72:75]
	v_mfma_f32_16x16x32_bf16 v[120:123], v[144:147], v[236:239], v[120:123]
	v_mfma_f32_16x16x32_bf16 v[124:127], v[194:197], v[236:239], v[124:127]
	v_mfma_f32_16x16x32_bf16 v[36:39], v[144:147], v[244:247], v[36:39]
	v_mfma_f32_16x16x32_bf16 v[40:43], v[194:197], v[244:247], v[40:43]
	v_mfma_f32_16x16x32_bf16 v[32:35], v[174:177], v[220:223], v[32:35]
	v_mfma_f32_16x16x32_bf16 v[44:47], v[198:201], v[220:223], v[44:47]
	v_mfma_f32_16x16x32_bf16 v[48:51], v[174:177], v[232:235], v[48:51]
	v_mfma_f32_16x16x32_bf16 v[72:75], v[198:201], v[232:235], v[72:75]
	v_mfma_f32_16x16x32_bf16 v[120:123], v[174:177], v[240:243], v[120:123]
	v_mfma_f32_16x16x32_bf16 v[124:127], v[198:201], v[240:243], v[124:127]
	v_mfma_f32_16x16x32_bf16 v[36:39], v[174:177], v[248:251], v[36:39]
	v_mfma_f32_16x16x32_bf16 v[40:43], v[198:201], v[248:251], v[40:43]
	s_setprio 0
	s_barrier
	s_add_u32 s50, s50, 0x18280
	s_addc_u32 s51, s51, 0
	s_mov_b32 m0, s65
	v_lshl_add_u64 v[240:241], s[50:51], 0, v[6:7]
	global_load_lds_dwordx4 v[240:241], off
	v_lshl_add_u64 v[240:241], s[50:51], 0, v[2:3]
	s_mov_b32 m0, s57
	s_nop 0
	global_load_lds_dwordx4 v[240:241], off
	ds_read_b128 v[128:131], v19
	ds_read_b128 v[132:135], v19 offset:1024
	ds_read_b128 v[136:139], v19 offset:2048
	ds_read_b128 v[140:143], v19 offset:3072
	ds_read_b128 v[144:147], v20
	ds_read_b128 v[174:177], v20 offset:1024
	ds_read_b128 v[182:185], v20 offset:2048
	ds_read_b128 v[186:189], v20 offset:3072
	ds_read_b128 v[190:193], v17
	ds_read_b128 v[194:197], v17 offset:1024
	ds_read_b128 v[198:201], v17 offset:2048
	ds_read_b128 v[202:205], v17 offset:3072
	ds_read_b128 v[220:223], v17 offset:4096
	ds_read_b128 v[228:231], v17 offset:5120
	ds_read_b128 v[232:235], v17 offset:6144
	ds_read_b128 v[236:239], v17 offset:7168
	s_waitcnt vmcnt(8)
	s_waitcnt lgkmcnt(0)
	s_barrier
	s_setprio 1
	s_waitcnt lgkmcnt(0)
	v_mfma_f32_16x16x32_bf16 v[76:79], v[128:131], v[190:193], v[76:79]
	v_mfma_f32_16x16x32_bf16 v[80:83], v[136:139], v[190:193], v[80:83]
	v_mfma_f32_16x16x32_bf16 v[84:87], v[128:131], v[198:201], v[84:87]
	v_mfma_f32_16x16x32_bf16 v[88:91], v[136:139], v[198:201], v[88:91]
	v_mfma_f32_16x16x32_bf16 v[92:95], v[128:131], v[220:223], v[92:95]
	v_mfma_f32_16x16x32_bf16 v[96:99], v[136:139], v[220:223], v[96:99]
	v_mfma_f32_16x16x32_bf16 v[100:103], v[128:131], v[232:235], v[100:103]
	v_mfma_f32_16x16x32_bf16 v[104:107], v[136:139], v[232:235], v[104:107]
	v_mfma_f32_16x16x32_bf16 v[76:79], v[132:135], v[194:197], v[76:79]
	v_mfma_f32_16x16x32_bf16 v[80:83], v[140:143], v[194:197], v[80:83]
	v_mfma_f32_16x16x32_bf16 v[84:87], v[132:135], v[202:205], v[84:87]
	v_mfma_f32_16x16x32_bf16 v[88:91], v[140:143], v[202:205], v[88:91]
	v_mfma_f32_16x16x32_bf16 v[92:95], v[132:135], v[228:231], v[92:95]
	v_mfma_f32_16x16x32_bf16 v[96:99], v[140:143], v[228:231], v[96:99]
	v_mfma_f32_16x16x32_bf16 v[100:103], v[132:135], v[236:239], v[100:103]
	v_mfma_f32_16x16x32_bf16 v[104:107], v[140:143], v[236:239], v[104:107]
	s_setprio 0
	s_setprio 1
	v_mfma_f32_16x16x32_bf16 v[108:111], v[144:147], v[190:193], v[108:111]
	v_mfma_f32_16x16x32_bf16 v[112:115], v[182:185], v[190:193], v[112:115]
	v_mfma_f32_16x16x32_bf16 v[116:119], v[144:147], v[198:201], v[116:119]
	v_mfma_f32_16x16x32_bf16 v[52:55], v[182:185], v[198:201], v[52:55]
	v_mfma_f32_16x16x32_bf16 v[56:59], v[144:147], v[220:223], v[56:59]
	v_mfma_f32_16x16x32_bf16 v[60:63], v[182:185], v[220:223], v[60:63]
	v_mfma_f32_16x16x32_bf16 v[64:67], v[144:147], v[232:235], v[64:67]
	v_mfma_f32_16x16x32_bf16 v[68:71], v[182:185], v[232:235], v[68:71]
	v_mfma_f32_16x16x32_bf16 v[108:111], v[174:177], v[194:197], v[108:111]
	v_mfma_f32_16x16x32_bf16 v[112:115], v[186:189], v[194:197], v[112:115]
	v_mfma_f32_16x16x32_bf16 v[116:119], v[174:177], v[202:205], v[116:119]
	v_mfma_f32_16x16x32_bf16 v[52:55], v[186:189], v[202:205], v[52:55]
	v_mfma_f32_16x16x32_bf16 v[56:59], v[174:177], v[228:231], v[56:59]
	v_mfma_f32_16x16x32_bf16 v[60:63], v[186:189], v[228:231], v[60:63]
	v_mfma_f32_16x16x32_bf16 v[64:67], v[174:177], v[236:239], v[64:67]
	v_mfma_f32_16x16x32_bf16 v[68:71], v[186:189], v[236:239], v[68:71]
	s_setprio 0
	s_barrier
	s_mov_b32 m0, s62
	v_lshl_add_u64 v[240:241], s[44:45], 0, v[4:5]
	s_add_u32 s50, s44, 0x18000
	global_load_lds_dwordx4 v[240:241], off
	v_lshl_add_u64 v[242:243], s[44:45], 0, v[0:1]
	s_mov_b32 m0, s58
	s_addc_u32 s51, s45, 0
	global_load_lds_dwordx4 v[242:243], off
	v_lshl_add_u64 v[244:245], s[50:51], 0, v[4:5]
	s_mov_b32 m0, s59
	v_lshl_add_u64 v[246:247], s[42:43], 0, v[2:3]
	global_load_lds_dwordx4 v[244:245], off
	v_lshl_add_u64 v[244:245], s[50:51], 0, v[0:1]
	s_mov_b32 m0, s61
	s_nop 0
	global_load_lds_dwordx4 v[244:245], off
	v_lshl_add_u64 v[244:245], s[42:43], 0, v[6:7]
	s_mov_b32 m0, s26
	s_nop 0
	global_load_lds_dwordx4 v[244:245], off
	s_mov_b32 m0, s27
	s_nop 0
	global_load_lds_dwordx4 v[246:247], off
	ds_read_b128 v[190:193], v17 offset:16384
	ds_read_b128 v[194:197], v17 offset:17408
	ds_read_b128 v[198:201], v17 offset:18432
	ds_read_b128 v[202:205], v17 offset:19456
	ds_read_b128 v[220:223], v17 offset:20480
	ds_read_b128 v[228:231], v17 offset:21504
	ds_read_b128 v[232:235], v17 offset:22528
	ds_read_b128 v[236:239], v17 offset:23552
	s_waitcnt vmcnt(8)
	s_waitcnt lgkmcnt(0)
	s_barrier
	s_setprio 1
	s_waitcnt lgkmcnt(0)
	v_mfma_f32_16x16x32_bf16 v[8:11], v[128:131], v[190:193], v[8:11]
	v_mfma_f32_16x16x32_bf16 v[12:15], v[136:139], v[190:193], v[12:15]
	v_mfma_f32_16x16x32_bf16 v[148:151], v[128:131], v[198:201], v[148:151]
	v_mfma_f32_16x16x32_bf16 v[152:155], v[136:139], v[198:201], v[152:155]
	v_mfma_f32_16x16x32_bf16 v[156:159], v[128:131], v[220:223], v[156:159]
	v_mfma_f32_16x16x32_bf16 v[178:181], v[136:139], v[220:223], v[178:181]
	v_mfma_f32_16x16x32_bf16 v[24:27], v[128:131], v[232:235], v[24:27]
	v_mfma_f32_16x16x32_bf16 v[28:31], v[136:139], v[232:235], v[28:31]
	v_mfma_f32_16x16x32_bf16 v[8:11], v[132:135], v[194:197], v[8:11]
	v_mfma_f32_16x16x32_bf16 v[12:15], v[140:143], v[194:197], v[12:15]
	v_mfma_f32_16x16x32_bf16 v[148:151], v[132:135], v[202:205], v[148:151]
	v_mfma_f32_16x16x32_bf16 v[152:155], v[140:143], v[202:205], v[152:155]
	v_mfma_f32_16x16x32_bf16 v[156:159], v[132:135], v[228:231], v[156:159]
	v_mfma_f32_16x16x32_bf16 v[178:181], v[140:143], v[228:231], v[178:181]
	v_mfma_f32_16x16x32_bf16 v[24:27], v[132:135], v[236:239], v[24:27]
	v_mfma_f32_16x16x32_bf16 v[28:31], v[140:143], v[236:239], v[28:31]
	s_setprio 0
	s_setprio 1
	v_mfma_f32_16x16x32_bf16 v[32:35], v[144:147], v[190:193], v[32:35]
	v_mfma_f32_16x16x32_bf16 v[44:47], v[182:185], v[190:193], v[44:47]
	v_mfma_f32_16x16x32_bf16 v[48:51], v[144:147], v[198:201], v[48:51]
	v_mfma_f32_16x16x32_bf16 v[72:75], v[182:185], v[198:201], v[72:75]
	v_mfma_f32_16x16x32_bf16 v[120:123], v[144:147], v[220:223], v[120:123]
	v_mfma_f32_16x16x32_bf16 v[124:127], v[182:185], v[220:223], v[124:127]
	v_mfma_f32_16x16x32_bf16 v[36:39], v[144:147], v[232:235], v[36:39]
	v_mfma_f32_16x16x32_bf16 v[40:43], v[182:185], v[232:235], v[40:43]
	v_mfma_f32_16x16x32_bf16 v[32:35], v[174:177], v[194:197], v[32:35]
	v_mfma_f32_16x16x32_bf16 v[44:47], v[186:189], v[194:197], v[44:47]
	v_mfma_f32_16x16x32_bf16 v[48:51], v[174:177], v[202:205], v[48:51]
	v_mfma_f32_16x16x32_bf16 v[72:75], v[186:189], v[202:205], v[72:75]
	v_mfma_f32_16x16x32_bf16 v[120:123], v[174:177], v[228:231], v[120:123]
	v_mfma_f32_16x16x32_bf16 v[124:127], v[186:189], v[228:231], v[124:127]
	v_mfma_f32_16x16x32_bf16 v[36:39], v[174:177], v[236:239], v[36:39]
	v_mfma_f32_16x16x32_bf16 v[40:43], v[186:189], v[236:239], v[40:43]
	s_setprio 0
	s_barrier
	s_add_u32 s50, s42, 0x18000
	s_addc_u32 s51, s43, 0
	s_mov_b32 m0, s28
	v_lshl_add_u64 v[236:237], s[50:51], 0, v[6:7]
	global_load_lds_dwordx4 v[236:237], off
	v_lshl_add_u64 v[236:237], s[50:51], 0, v[2:3]
	s_mov_b32 m0, s29
	s_nop 0
	global_load_lds_dwordx4 v[236:237], off
	ds_read_b128 v[128:131], v21
	ds_read_b128 v[132:135], v21 offset:1024
	ds_read_b128 v[136:139], v21 offset:2048
	ds_read_b128 v[140:143], v21 offset:3072
	ds_read_b128 v[144:147], v22
	ds_read_b128 v[174:177], v22 offset:1024
	ds_read_b128 v[182:185], v22 offset:2048
	ds_read_b128 v[20:23], v22 offset:3072
	ds_read_b128 v[186:189], v17 offset:32768
	ds_read_b128 v[190:193], v17 offset:33792
	ds_read_b128 v[194:197], v17 offset:34816
	ds_read_b128 v[198:201], v17 offset:35840
	ds_read_b128 v[202:205], v17 offset:36864
	ds_read_b128 v[220:223], v17 offset:37888
	ds_read_b128 v[228:231], v17 offset:38912
	ds_read_b128 v[232:235], v17 offset:39936
	s_waitcnt vmcnt(8)
	s_waitcnt lgkmcnt(0)
	s_barrier
	s_setprio 1
	s_waitcnt lgkmcnt(0)
	v_mfma_f32_16x16x32_bf16 v[76:79], v[128:131], v[186:189], v[76:79]
	v_mfma_f32_16x16x32_bf16 v[80:83], v[136:139], v[186:189], v[80:83]
	v_mfma_f32_16x16x32_bf16 v[84:87], v[128:131], v[194:197], v[84:87]
	v_mfma_f32_16x16x32_bf16 v[88:91], v[136:139], v[194:197], v[88:91]
	v_mfma_f32_16x16x32_bf16 v[92:95], v[128:131], v[202:205], v[92:95]
	v_mfma_f32_16x16x32_bf16 v[96:99], v[136:139], v[202:205], v[96:99]
	v_mfma_f32_16x16x32_bf16 v[100:103], v[128:131], v[228:231], v[100:103]
	v_mfma_f32_16x16x32_bf16 v[104:107], v[136:139], v[228:231], v[104:107]
	v_mfma_f32_16x16x32_bf16 v[76:79], v[132:135], v[190:193], v[76:79]
	v_mfma_f32_16x16x32_bf16 v[80:83], v[140:143], v[190:193], v[80:83]
	v_mfma_f32_16x16x32_bf16 v[84:87], v[132:135], v[198:201], v[84:87]
	v_mfma_f32_16x16x32_bf16 v[88:91], v[140:143], v[198:201], v[88:91]
	v_mfma_f32_16x16x32_bf16 v[92:95], v[132:135], v[220:223], v[92:95]
	v_mfma_f32_16x16x32_bf16 v[96:99], v[140:143], v[220:223], v[96:99]
	v_mfma_f32_16x16x32_bf16 v[100:103], v[132:135], v[232:235], v[100:103]
	v_mfma_f32_16x16x32_bf16 v[104:107], v[140:143], v[232:235], v[104:107]
	s_setprio 0
	s_setprio 1
	v_mfma_f32_16x16x32_bf16 v[108:111], v[144:147], v[186:189], v[108:111]
	v_mfma_f32_16x16x32_bf16 v[112:115], v[182:185], v[186:189], v[112:115]
	v_mfma_f32_16x16x32_bf16 v[116:119], v[144:147], v[194:197], v[116:119]
	v_mfma_f32_16x16x32_bf16 v[52:55], v[182:185], v[194:197], v[52:55]
	v_mfma_f32_16x16x32_bf16 v[56:59], v[144:147], v[202:205], v[56:59]
	v_mfma_f32_16x16x32_bf16 v[60:63], v[182:185], v[202:205], v[60:63]
	v_mfma_f32_16x16x32_bf16 v[64:67], v[144:147], v[228:231], v[64:67]
	v_mfma_f32_16x16x32_bf16 v[68:71], v[182:185], v[228:231], v[68:71]
	v_mfma_f32_16x16x32_bf16 v[108:111], v[174:177], v[190:193], v[108:111]
	v_mfma_f32_16x16x32_bf16 v[112:115], v[20:23], v[190:193], v[112:115]
	v_mfma_f32_16x16x32_bf16 v[116:119], v[174:177], v[198:201], v[116:119]
	v_mfma_f32_16x16x32_bf16 v[52:55], v[20:23], v[198:201], v[52:55]
	v_mfma_f32_16x16x32_bf16 v[56:59], v[174:177], v[220:223], v[56:59]
	v_mfma_f32_16x16x32_bf16 v[60:63], v[20:23], v[220:223], v[60:63]
	v_mfma_f32_16x16x32_bf16 v[64:67], v[174:177], v[232:235], v[64:67]
	v_mfma_f32_16x16x32_bf16 v[68:71], v[20:23], v[232:235], v[68:71]
	s_setprio 0
	s_barrier
	s_mov_b32 m0, s67
	v_lshl_add_u64 v[236:237], v[240:241], 0, s[4:5]
	s_add_u32 s50, s44, 0x18080
	global_load_lds_dwordx4 v[236:237], off
	v_lshl_add_u64 v[236:237], v[242:243], 0, s[4:5]
	s_mov_b32 m0, s63
	s_addc_u32 s51, s45, 0
	global_load_lds_dwordx4 v[236:237], off
	v_lshl_add_u64 v[236:237], s[50:51], 0, v[4:5]
	s_mov_b32 m0, s64
	s_nop 0
	global_load_lds_dwordx4 v[236:237], off
	v_lshl_add_u64 v[236:237], s[50:51], 0, v[0:1]
	s_mov_b32 m0, s66
	s_nop 0
	global_load_lds_dwordx4 v[236:237], off
	v_lshl_add_u64 v[236:237], v[244:245], 0, s[4:5]
	s_mov_b32 m0, s30
	s_nop 0
	global_load_lds_dwordx4 v[236:237], off
	v_lshl_add_u64 v[236:237], v[246:247], 0, s[4:5]
	s_mov_b32 m0, s31
	s_nop 0
	global_load_lds_dwordx4 v[236:237], off
	ds_read_b128 v[186:189], v17 offset:49152
	ds_read_b128 v[190:193], v17 offset:50176
	ds_read_b128 v[194:197], v17 offset:51200
	ds_read_b128 v[198:201], v17 offset:52224
	ds_read_b128 v[202:205], v17 offset:53248
	ds_read_b128 v[220:223], v17 offset:54272
	ds_read_b128 v[228:231], v17 offset:55296
	ds_read_b128 v[232:235], v17 offset:56320
	s_waitcnt vmcnt(8)
	s_waitcnt lgkmcnt(0)
	s_barrier
	s_setprio 1
	s_waitcnt lgkmcnt(0)
	v_mfma_f32_16x16x32_bf16 v[8:11], v[128:131], v[186:189], v[8:11]
	v_mfma_f32_16x16x32_bf16 v[12:15], v[136:139], v[186:189], v[12:15]
	v_mfma_f32_16x16x32_bf16 v[148:151], v[128:131], v[194:197], v[148:151]
	v_mfma_f32_16x16x32_bf16 v[152:155], v[136:139], v[194:197], v[152:155]
	v_mfma_f32_16x16x32_bf16 v[156:159], v[128:131], v[202:205], v[156:159]
	v_mfma_f32_16x16x32_bf16 v[178:181], v[136:139], v[202:205], v[178:181]
	v_mfma_f32_16x16x32_bf16 v[24:27], v[128:131], v[228:231], v[24:27]
	v_mfma_f32_16x16x32_bf16 v[28:31], v[136:139], v[228:231], v[28:31]
	v_mfma_f32_16x16x32_bf16 v[8:11], v[132:135], v[190:193], v[8:11]
	v_mfma_f32_16x16x32_bf16 v[12:15], v[140:143], v[190:193], v[12:15]
	v_mfma_f32_16x16x32_bf16 v[148:151], v[132:135], v[198:201], v[148:151]
	v_mfma_f32_16x16x32_bf16 v[152:155], v[140:143], v[198:201], v[152:155]
	v_mfma_f32_16x16x32_bf16 v[156:159], v[132:135], v[220:223], v[156:159]
	v_mfma_f32_16x16x32_bf16 v[178:181], v[140:143], v[220:223], v[178:181]
	v_mfma_f32_16x16x32_bf16 v[24:27], v[132:135], v[232:235], v[24:27]
	v_mfma_f32_16x16x32_bf16 v[28:31], v[140:143], v[232:235], v[28:31]
	s_setprio 0
	s_setprio 1
	v_mfma_f32_16x16x32_bf16 v[32:35], v[144:147], v[186:189], v[32:35]
	v_mfma_f32_16x16x32_bf16 v[44:47], v[182:185], v[186:189], v[44:47]
	v_mfma_f32_16x16x32_bf16 v[48:51], v[144:147], v[194:197], v[48:51]
	v_mfma_f32_16x16x32_bf16 v[72:75], v[182:185], v[194:197], v[72:75]
	v_mfma_f32_16x16x32_bf16 v[120:123], v[144:147], v[202:205], v[120:123]
	v_mfma_f32_16x16x32_bf16 v[124:127], v[182:185], v[202:205], v[124:127]
	v_mfma_f32_16x16x32_bf16 v[36:39], v[144:147], v[228:231], v[36:39]
	v_mfma_f32_16x16x32_bf16 v[40:43], v[182:185], v[228:231], v[40:43]
	v_mfma_f32_16x16x32_bf16 v[32:35], v[174:177], v[190:193], v[32:35]
	v_mfma_f32_16x16x32_bf16 v[44:47], v[20:23], v[190:193], v[44:47]
	v_mfma_f32_16x16x32_bf16 v[48:51], v[174:177], v[198:201], v[48:51]
	v_mfma_f32_16x16x32_bf16 v[72:75], v[20:23], v[198:201], v[72:75]
	v_mfma_f32_16x16x32_bf16 v[120:123], v[174:177], v[220:223], v[120:123]
	v_mfma_f32_16x16x32_bf16 v[124:127], v[20:23], v[220:223], v[124:127]
	v_mfma_f32_16x16x32_bf16 v[36:39], v[174:177], v[232:235], v[36:39]
	v_mfma_f32_16x16x32_bf16 v[20:23], v[20:23], v[232:235], v[40:43]
	s_setprio 0
	s_barrier
	s_lshl_b32 s50, s55, 8
	s_lshl_b32 s51, s56, 19
	s_add_i32 s50, s50, s51
	v_add_u32_e32 v162, s50, v18
	v_lshl_add_u64 v[128:129], v[162:163], 1, s[46:47]
	v_cvt_pk_bf16_f32 v40, v76, v77
	v_cvt_pk_bf16_f32 v41, v78, v79
	v_cvt_pk_bf16_f32 v42, v80, v81
	v_cvt_pk_bf16_f32 v43, v82, v83
	global_store_dwordx4 v[128:129], v[40:43], off
	v_cvt_pk_bf16_f32 v8, v8, v9
	v_cvt_pk_bf16_f32 v9, v10, v11
	v_cvt_pk_bf16_f32 v40, v108, v109
	v_cvt_pk_bf16_f32 v41, v110, v111
	v_cvt_pk_bf16_f32 v42, v112, v113
	v_cvt_pk_bf16_f32 v43, v114, v115
	global_store_dwordx4 v[128:129], v[40:43], off offset:256
	v_cvt_pk_bf16_f32 v10, v12, v13
	v_cvt_pk_bf16_f32 v11, v14, v15
	v_add_u32_e32 v40, 0x8000, v162
	v_mov_b32_e32 v41, v163
	v_lshl_add_u64 v[76:77], v[40:41], 1, s[46:47]
	v_cvt_pk_bf16_f32 v40, v84, v85
	v_cvt_pk_bf16_f32 v41, v86, v87
	v_cvt_pk_bf16_f32 v42, v88, v89
	v_cvt_pk_bf16_f32 v43, v90, v91
	global_store_dwordx4 v[76:77], v[40:43], off
	s_add_i32 s54, s54, s82
	s_andn2_b64 vcc, exec, s[40:41]
	v_cvt_pk_bf16_f32 v40, v116, v117
	v_cvt_pk_bf16_f32 v41, v118, v119
	v_cvt_pk_bf16_f32 v42, v52, v53
	v_cvt_pk_bf16_f32 v43, v54, v55
	global_store_dwordx4 v[76:77], v[40:43], off offset:256
	s_mov_b32 s55, s6
	s_mov_b32 s56, s7
	v_add_u32_e32 v40, 0x10000, v162
	v_mov_b32_e32 v41, v163
	v_lshl_add_u64 v[52:53], v[40:41], 1, s[46:47]
	v_cvt_pk_bf16_f32 v40, v92, v93
	v_cvt_pk_bf16_f32 v41, v94, v95
	v_cvt_pk_bf16_f32 v42, v96, v97
	v_cvt_pk_bf16_f32 v43, v98, v99
	global_store_dwordx4 v[52:53], v[40:43], off
	s_mov_b64 s[52:53], s[44:45]
	s_mov_b64 s[50:51], s[42:43]
	v_cvt_pk_bf16_f32 v40, v56, v57
	v_cvt_pk_bf16_f32 v41, v58, v59
	v_cvt_pk_bf16_f32 v42, v60, v61
	v_cvt_pk_bf16_f32 v43, v62, v63
	global_store_dwordx4 v[52:53], v[40:43], off offset:256
	s_nop 1
	v_add_u32_e32 v40, 0x18000, v162
	v_mov_b32_e32 v41, v163
	v_lshl_add_u64 v[52:53], v[40:41], 1, s[46:47]
	v_cvt_pk_bf16_f32 v40, v100, v101
	v_cvt_pk_bf16_f32 v41, v102, v103
	v_cvt_pk_bf16_f32 v42, v104, v105
	v_cvt_pk_bf16_f32 v43, v106, v107
	global_store_dwordx4 v[52:53], v[40:43], off
	s_nop 1
	v_cvt_pk_bf16_f32 v40, v64, v65
	v_cvt_pk_bf16_f32 v41, v66, v67
	v_cvt_pk_bf16_f32 v42, v68, v69
	v_cvt_pk_bf16_f32 v43, v70, v71
	global_store_dwordx4 v[52:53], v[40:43], off offset:256
	s_nop 1
	v_add_u32_e32 v40, 0x40000, v162
	v_mov_b32_e32 v41, v163
	v_lshl_add_u64 v[40:41], v[40:41], 1, s[46:47]
	global_store_dwordx4 v[40:41], v[8:11], off
	s_nop 1
	v_cvt_pk_bf16_f32 v8, v32, v33
	v_cvt_pk_bf16_f32 v9, v34, v35
	v_cvt_pk_bf16_f32 v10, v44, v45
	v_cvt_pk_bf16_f32 v11, v46, v47
	global_store_dwordx4 v[40:41], v[8:11], off offset:256
	s_nop 1
	v_add_u32_e32 v8, 0x48000, v162
	v_mov_b32_e32 v9, v163
	v_lshl_add_u64 v[12:13], v[8:9], 1, s[46:47]
	v_cvt_pk_bf16_f32 v8, v148, v149
	v_cvt_pk_bf16_f32 v9, v150, v151
	v_cvt_pk_bf16_f32 v10, v152, v153
	v_cvt_pk_bf16_f32 v11, v154, v155
	global_store_dwordx4 v[12:13], v[8:11], off
	s_nop 1
	v_cvt_pk_bf16_f32 v8, v48, v49
	v_cvt_pk_bf16_f32 v9, v50, v51
	v_cvt_pk_bf16_f32 v10, v72, v73
	v_cvt_pk_bf16_f32 v11, v74, v75
	global_store_dwordx4 v[12:13], v[8:11], off offset:256
	s_nop 1
	v_add_u32_e32 v8, 0x50000, v162
	v_mov_b32_e32 v9, v163
	v_lshl_add_u64 v[12:13], v[8:9], 1, s[46:47]
	v_cvt_pk_bf16_f32 v8, v156, v157
	v_cvt_pk_bf16_f32 v9, v158, v159
	v_cvt_pk_bf16_f32 v10, v178, v179
	v_cvt_pk_bf16_f32 v11, v180, v181
	global_store_dwordx4 v[12:13], v[8:11], off
	v_add_u32_e32 v162, 0x58000, v162
	s_nop 0
	v_cvt_pk_bf16_f32 v8, v120, v121
	v_cvt_pk_bf16_f32 v9, v122, v123
	v_cvt_pk_bf16_f32 v10, v124, v125
	v_cvt_pk_bf16_f32 v11, v126, v127
	global_store_dwordx4 v[12:13], v[8:11], off offset:256
	v_lshl_add_u64 v[12:13], v[162:163], 1, s[46:47]
	s_nop 0
	v_cvt_pk_bf16_f32 v8, v24, v25
	v_cvt_pk_bf16_f32 v9, v26, v27
	v_cvt_pk_bf16_f32 v10, v28, v29
	v_cvt_pk_bf16_f32 v11, v30, v31
	global_store_dwordx4 v[12:13], v[8:11], off
	s_nop 1
	v_cvt_pk_bf16_f32 v8, v36, v37
	v_cvt_pk_bf16_f32 v9, v38, v39
	v_cvt_pk_bf16_f32 v10, v20, v21
	v_cvt_pk_bf16_f32 v11, v22, v23
	global_store_dwordx4 v[12:13], v[8:11], off offset:256
	s_cbranch_vccz .LBB0_513

.LBB0_771:
	s_add_u32 s55, s60, 0xfffc0080
	s_addc_u32 s62, s61, -1
	s_add_i32 s72, 0, 0x10000
	s_cmp_eq_u32 s53, 12
	s_cselect_b32 s65, s6, s62
	s_cselect_b32 s64, s7, s55
	s_cselect_b32 s63, s28, s31
	s_cselect_b32 s62, s29, s30
	s_add_i32 s55, 0, 0x14000
	v_add_u32_e32 v156, s72, v145
	v_add_u32_e32 v162, s55, v145
	ds_read_b128 v[140:143], v156
	ds_read_b128 v[148:151], v156 offset:1024
	ds_read_b128 v[152:155], v156 offset:2048
	ds_read_b128 v[156:159], v156 offset:3072
	ds_read_b128 v[174:177], v162
	ds_read_b128 v[178:181], v162 offset:1024
	ds_read_b128 v[182:185], v162 offset:2048
	ds_read_b128 v[186:189], v162 offset:3072
	v_lshl_add_u64 v[240:241], s[60:61], 0, v[136:137]
	s_add_i32 m0, s25, 0xc000
	ds_read_b128 v[190:193], v147
	ds_read_b128 v[194:197], v147 offset:1024
	ds_read_b128 v[198:201], v147 offset:2048
	ds_read_b128 v[202:205], v147 offset:3072
	ds_read_b128 v[220:223], v147 offset:4096
	ds_read_b128 v[228:231], v147 offset:5120
	ds_read_b128 v[232:235], v147 offset:6144
	ds_read_b128 v[236:239], v147 offset:7168
	global_load_lds_dwordx4 v[240:241], off
	v_lshl_add_u64 v[240:241], s[60:61], 0, v[138:139]
	s_add_i32 m0, s25, 0xe000
	s_nop 0
	global_load_lds_dwordx4 v[240:241], off
	s_waitcnt vmcnt(8)
	s_waitcnt lgkmcnt(0)
	s_barrier
	s_setprio 1
	s_waitcnt lgkmcnt(0)
	v_mfma_f32_16x16x32_bf16 v[124:127], v[140:143], v[190:193], v[124:127]
	v_mfma_f32_16x16x32_bf16 v[120:123], v[152:155], v[190:193], v[120:123]
	v_mfma_f32_16x16x32_bf16 v[108:111], v[140:143], v[198:201], v[108:111]
	v_mfma_f32_16x16x32_bf16 v[104:107], v[152:155], v[198:201], v[104:107]
	v_mfma_f32_16x16x32_bf16 v[92:95], v[140:143], v[220:223], v[92:95]
	v_mfma_f32_16x16x32_bf16 v[88:91], v[152:155], v[220:223], v[88:91]
	v_mfma_f32_16x16x32_bf16 v[76:79], v[140:143], v[232:235], v[76:79]
	v_mfma_f32_16x16x32_bf16 v[72:75], v[152:155], v[232:235], v[72:75]
	v_mfma_f32_16x16x32_bf16 v[124:127], v[148:151], v[194:197], v[124:127]
	v_mfma_f32_16x16x32_bf16 v[120:123], v[156:159], v[194:197], v[120:123]
	v_mfma_f32_16x16x32_bf16 v[108:111], v[148:151], v[202:205], v[108:111]
	v_mfma_f32_16x16x32_bf16 v[104:107], v[156:159], v[202:205], v[104:107]
	v_mfma_f32_16x16x32_bf16 v[92:95], v[148:151], v[228:231], v[92:95]
	v_mfma_f32_16x16x32_bf16 v[88:91], v[156:159], v[228:231], v[88:91]
	v_mfma_f32_16x16x32_bf16 v[76:79], v[148:151], v[236:239], v[76:79]
	v_mfma_f32_16x16x32_bf16 v[72:75], v[156:159], v[236:239], v[72:75]
	s_setprio 0
	s_setprio 1
	v_mfma_f32_16x16x32_bf16 v[116:119], v[174:177], v[190:193], v[116:119]
	v_mfma_f32_16x16x32_bf16 v[112:115], v[182:185], v[190:193], v[112:115]
	v_mfma_f32_16x16x32_bf16 v[100:103], v[174:177], v[198:201], v[100:103]
	v_mfma_f32_16x16x32_bf16 v[96:99], v[182:185], v[198:201], v[96:99]
	v_mfma_f32_16x16x32_bf16 v[84:87], v[174:177], v[220:223], v[84:87]
	v_mfma_f32_16x16x32_bf16 v[80:83], v[182:185], v[220:223], v[80:83]
	v_mfma_f32_16x16x32_bf16 v[68:71], v[174:177], v[232:235], v[68:71]
	v_mfma_f32_16x16x32_bf16 v[64:67], v[182:185], v[232:235], v[64:67]
	v_mfma_f32_16x16x32_bf16 v[116:119], v[178:181], v[194:197], v[116:119]
	v_mfma_f32_16x16x32_bf16 v[112:115], v[186:189], v[194:197], v[112:115]
	v_mfma_f32_16x16x32_bf16 v[100:103], v[178:181], v[202:205], v[100:103]
	v_mfma_f32_16x16x32_bf16 v[96:99], v[186:189], v[202:205], v[96:99]
	v_mfma_f32_16x16x32_bf16 v[84:87], v[178:181], v[228:231], v[84:87]
	v_mfma_f32_16x16x32_bf16 v[80:83], v[186:189], v[228:231], v[80:83]
	v_mfma_f32_16x16x32_bf16 v[68:71], v[178:181], v[236:239], v[68:71]
	v_mfma_f32_16x16x32_bf16 v[64:67], v[186:189], v[236:239], v[64:67]
	s_setprio 0
	s_barrier
	s_add_i32 s72, s72, s24
	v_lshl_add_u64 v[240:241], s[62:63], 0, v[132:133]
	s_mov_b32 m0, s72
	s_nop 0
	global_load_lds_dwordx4 v[240:241], off
	s_add_i32 m0, s72, 0x2000
	s_add_u32 s72, s62, 0x40000
	v_lshl_add_u64 v[242:243], s[62:63], 0, v[128:129]
	s_addc_u32 s73, s63, 0
	s_add_i32 s55, s55, s24
	global_load_lds_dwordx4 v[242:243], off
	v_lshl_add_u64 v[244:245], s[72:73], 0, v[132:133]
	s_mov_b32 m0, s55
	v_lshl_add_u64 v[246:247], s[64:65], 0, v[130:131]
	global_load_lds_dwordx4 v[244:245], off
	v_lshl_add_u64 v[244:245], s[72:73], 0, v[128:129]
	s_add_i32 m0, s55, 0x2000
	s_nop 0
	global_load_lds_dwordx4 v[244:245], off
	v_lshl_add_u64 v[244:245], s[64:65], 0, v[134:135]
	s_mov_b32 m0, s25
	s_nop 0
	global_load_lds_dwordx4 v[244:245], off
	s_mov_b32 m0, s66
	s_nop 0
	global_load_lds_dwordx4 v[246:247], off
	ds_read_b128 v[190:193], v147 offset:16384
	ds_read_b128 v[194:197], v147 offset:17408
	ds_read_b128 v[198:201], v147 offset:18432
	ds_read_b128 v[202:205], v147 offset:19456
	ds_read_b128 v[220:223], v147 offset:20480
	ds_read_b128 v[228:231], v147 offset:21504
	ds_read_b128 v[232:235], v147 offset:22528
	ds_read_b128 v[236:239], v147 offset:23552
	s_waitcnt vmcnt(8)
	s_waitcnt lgkmcnt(0)
	s_barrier
	s_setprio 1
	s_waitcnt lgkmcnt(0)
	v_mfma_f32_16x16x32_bf16 v[60:63], v[140:143], v[190:193], v[60:63]
	v_mfma_f32_16x16x32_bf16 v[56:59], v[152:155], v[190:193], v[56:59]
	v_mfma_f32_16x16x32_bf16 v[44:47], v[140:143], v[198:201], v[44:47]
	v_mfma_f32_16x16x32_bf16 v[40:43], v[152:155], v[198:201], v[40:43]
	v_mfma_f32_16x16x32_bf16 v[28:31], v[140:143], v[220:223], v[28:31]
	v_mfma_f32_16x16x32_bf16 v[24:27], v[152:155], v[220:223], v[24:27]
	v_mfma_f32_16x16x32_bf16 v[12:15], v[140:143], v[232:235], v[12:15]
	v_mfma_f32_16x16x32_bf16 v[8:11], v[152:155], v[232:235], v[8:11]
	v_mfma_f32_16x16x32_bf16 v[60:63], v[148:151], v[194:197], v[60:63]
	v_mfma_f32_16x16x32_bf16 v[56:59], v[156:159], v[194:197], v[56:59]
	v_mfma_f32_16x16x32_bf16 v[44:47], v[148:151], v[202:205], v[44:47]
	v_mfma_f32_16x16x32_bf16 v[40:43], v[156:159], v[202:205], v[40:43]
	v_mfma_f32_16x16x32_bf16 v[28:31], v[148:151], v[228:231], v[28:31]
	v_mfma_f32_16x16x32_bf16 v[24:27], v[156:159], v[228:231], v[24:27]
	v_mfma_f32_16x16x32_bf16 v[12:15], v[148:151], v[236:239], v[12:15]
	v_mfma_f32_16x16x32_bf16 v[8:11], v[156:159], v[236:239], v[8:11]
	s_setprio 0
	s_setprio 1
	v_mfma_f32_16x16x32_bf16 v[52:55], v[174:177], v[190:193], v[52:55]
	v_mfma_f32_16x16x32_bf16 v[48:51], v[182:185], v[190:193], v[48:51]
	v_mfma_f32_16x16x32_bf16 v[36:39], v[174:177], v[198:201], v[36:39]
	v_mfma_f32_16x16x32_bf16 v[32:35], v[182:185], v[198:201], v[32:35]
	v_mfma_f32_16x16x32_bf16 v[20:23], v[174:177], v[220:223], v[20:23]
	v_mfma_f32_16x16x32_bf16 v[16:19], v[182:185], v[220:223], v[16:19]
	v_mfma_f32_16x16x32_bf16 v[4:7], v[174:177], v[232:235], v[4:7]
	v_mfma_f32_16x16x32_bf16 v[0:3], v[182:185], v[232:235], v[0:3]
	v_mfma_f32_16x16x32_bf16 v[52:55], v[178:181], v[194:197], v[52:55]
	v_mfma_f32_16x16x32_bf16 v[48:51], v[186:189], v[194:197], v[48:51]
	v_mfma_f32_16x16x32_bf16 v[36:39], v[178:181], v[202:205], v[36:39]
	v_mfma_f32_16x16x32_bf16 v[32:35], v[186:189], v[202:205], v[32:35]
	v_mfma_f32_16x16x32_bf16 v[20:23], v[178:181], v[228:231], v[20:23]
	v_mfma_f32_16x16x32_bf16 v[16:19], v[186:189], v[228:231], v[16:19]
	v_mfma_f32_16x16x32_bf16 v[4:7], v[178:181], v[236:239], v[4:7]
	v_mfma_f32_16x16x32_bf16 v[0:3], v[186:189], v[236:239], v[0:3]
	s_setprio 0
	s_barrier
	s_add_i32 s55, 0, 0x18000
	s_add_i32 s72, 0, 0x1c000
	v_add_u32_e32 v156, s55, v145
	v_add_u32_e32 v162, s72, v145
	ds_read_b128 v[140:143], v156
	ds_read_b128 v[148:151], v156 offset:1024
	ds_read_b128 v[152:155], v156 offset:2048
	ds_read_b128 v[156:159], v156 offset:3072
	ds_read_b128 v[174:177], v162
	ds_read_b128 v[178:181], v162 offset:1024
	ds_read_b128 v[182:185], v162 offset:2048
	ds_read_b128 v[186:189], v162 offset:3072
	s_add_u32 s64, s64, 0x40000
	s_addc_u32 s65, s65, 0
	s_mov_b32 m0, s67
	v_lshl_add_u64 v[248:249], s[64:65], 0, v[134:135]
	ds_read_b128 v[190:193], v147 offset:32768
	ds_read_b128 v[194:197], v147 offset:33792
	ds_read_b128 v[198:201], v147 offset:34816
	ds_read_b128 v[202:205], v147 offset:35840
	ds_read_b128 v[220:223], v147 offset:36864
	ds_read_b128 v[228:231], v147 offset:37888
	ds_read_b128 v[232:235], v147 offset:38912
	ds_read_b128 v[236:239], v147 offset:39936
	global_load_lds_dwordx4 v[248:249], off
	v_lshl_add_u64 v[248:249], s[64:65], 0, v[130:131]
	s_mov_b32 m0, s68
	s_nop 0
	global_load_lds_dwordx4 v[248:249], off
	s_waitcnt vmcnt(8)
	s_waitcnt lgkmcnt(0)
	s_barrier
	s_setprio 1
	s_waitcnt lgkmcnt(0)
	v_mfma_f32_16x16x32_bf16 v[124:127], v[140:143], v[190:193], v[124:127]
	v_mfma_f32_16x16x32_bf16 v[120:123], v[152:155], v[190:193], v[120:123]
	v_mfma_f32_16x16x32_bf16 v[108:111], v[140:143], v[198:201], v[108:111]
	v_mfma_f32_16x16x32_bf16 v[104:107], v[152:155], v[198:201], v[104:107]
	v_mfma_f32_16x16x32_bf16 v[92:95], v[140:143], v[220:223], v[92:95]
	v_mfma_f32_16x16x32_bf16 v[88:91], v[152:155], v[220:223], v[88:91]
	v_mfma_f32_16x16x32_bf16 v[76:79], v[140:143], v[232:235], v[76:79]
	v_mfma_f32_16x16x32_bf16 v[72:75], v[152:155], v[232:235], v[72:75]
	v_mfma_f32_16x16x32_bf16 v[124:127], v[148:151], v[194:197], v[124:127]
	v_mfma_f32_16x16x32_bf16 v[120:123], v[156:159], v[194:197], v[120:123]
	v_mfma_f32_16x16x32_bf16 v[108:111], v[148:151], v[202:205], v[108:111]
	v_mfma_f32_16x16x32_bf16 v[104:107], v[156:159], v[202:205], v[104:107]
	v_mfma_f32_16x16x32_bf16 v[92:95], v[148:151], v[228:231], v[92:95]
	v_mfma_f32_16x16x32_bf16 v[88:91], v[156:159], v[228:231], v[88:91]
	v_mfma_f32_16x16x32_bf16 v[76:79], v[148:151], v[236:239], v[76:79]
	v_mfma_f32_16x16x32_bf16 v[72:75], v[156:159], v[236:239], v[72:75]
	s_setprio 0
	s_setprio 1
	v_mfma_f32_16x16x32_bf16 v[116:119], v[174:177], v[190:193], v[116:119]
	v_mfma_f32_16x16x32_bf16 v[112:115], v[182:185], v[190:193], v[112:115]
	v_mfma_f32_16x16x32_bf16 v[100:103], v[174:177], v[198:201], v[100:103]
	v_mfma_f32_16x16x32_bf16 v[96:99], v[182:185], v[198:201], v[96:99]
	v_mfma_f32_16x16x32_bf16 v[84:87], v[174:177], v[220:223], v[84:87]
	v_mfma_f32_16x16x32_bf16 v[80:83], v[182:185], v[220:223], v[80:83]
	v_mfma_f32_16x16x32_bf16 v[68:71], v[174:177], v[232:235], v[68:71]
	v_mfma_f32_16x16x32_bf16 v[64:67], v[182:185], v[232:235], v[64:67]
	v_mfma_f32_16x16x32_bf16 v[116:119], v[178:181], v[194:197], v[116:119]
	v_mfma_f32_16x16x32_bf16 v[112:115], v[186:189], v[194:197], v[112:115]
	v_mfma_f32_16x16x32_bf16 v[100:103], v[178:181], v[202:205], v[100:103]
	v_mfma_f32_16x16x32_bf16 v[96:99], v[186:189], v[202:205], v[96:99]
	v_mfma_f32_16x16x32_bf16 v[84:87], v[178:181], v[228:231], v[84:87]
	v_mfma_f32_16x16x32_bf16 v[80:83], v[186:189], v[228:231], v[80:83]
	v_mfma_f32_16x16x32_bf16 v[68:71], v[178:181], v[236:239], v[68:71]
	v_mfma_f32_16x16x32_bf16 v[64:67], v[186:189], v[236:239], v[64:67]
	s_setprio 0
	s_barrier
	s_add_i32 s55, s55, s24
	v_lshl_add_u64 v[240:241], v[240:241], 0, s[4:5]
	s_mov_b32 m0, s55
	s_nop 0
	global_load_lds_dwordx4 v[240:241], off
	s_add_i32 m0, s55, 0x2000
	s_add_u32 s62, s62, 0x40080
	v_lshl_add_u64 v[240:241], v[242:243], 0, s[4:5]
	s_addc_u32 s63, s63, 0
	s_add_i32 s55, s72, s24
	global_load_lds_dwordx4 v[240:241], off
	v_lshl_add_u64 v[240:241], s[62:63], 0, v[132:133]
	s_mov_b32 m0, s55
	s_nop 0
	global_load_lds_dwordx4 v[240:241], off
	v_lshl_add_u64 v[240:241], s[62:63], 0, v[128:129]
	s_add_i32 m0, s55, 0x2000
	s_nop 0
	global_load_lds_dwordx4 v[240:241], off
	v_lshl_add_u64 v[240:241], v[244:245], 0, s[4:5]
	s_mov_b32 m0, s69
	s_nop 0
	global_load_lds_dwordx4 v[240:241], off
	v_lshl_add_u64 v[240:241], v[246:247], 0, s[4:5]
	s_mov_b32 m0, s70
	s_nop 0
	global_load_lds_dwordx4 v[240:241], off
	ds_read_b128 v[190:193], v147 offset:49152
	ds_read_b128 v[194:197], v147 offset:50176
	ds_read_b128 v[198:201], v147 offset:51200
	ds_read_b128 v[202:205], v147 offset:52224
	ds_read_b128 v[220:223], v147 offset:53248
	ds_read_b128 v[228:231], v147 offset:54272
	ds_read_b128 v[232:235], v147 offset:55296
	ds_read_b128 v[236:239], v147 offset:56320
	s_waitcnt vmcnt(8)
	s_waitcnt lgkmcnt(0)
	s_barrier
	s_setprio 1
	s_waitcnt lgkmcnt(0)
	v_mfma_f32_16x16x32_bf16 v[60:63], v[140:143], v[190:193], v[60:63]
	v_mfma_f32_16x16x32_bf16 v[56:59], v[152:155], v[190:193], v[56:59]
	v_mfma_f32_16x16x32_bf16 v[44:47], v[140:143], v[198:201], v[44:47]
	v_mfma_f32_16x16x32_bf16 v[40:43], v[152:155], v[198:201], v[40:43]
	v_mfma_f32_16x16x32_bf16 v[28:31], v[140:143], v[220:223], v[28:31]
	v_mfma_f32_16x16x32_bf16 v[24:27], v[152:155], v[220:223], v[24:27]
	v_mfma_f32_16x16x32_bf16 v[12:15], v[140:143], v[232:235], v[12:15]
	v_mfma_f32_16x16x32_bf16 v[8:11], v[152:155], v[232:235], v[8:11]
	v_mfma_f32_16x16x32_bf16 v[60:63], v[148:151], v[194:197], v[60:63]
	v_mfma_f32_16x16x32_bf16 v[56:59], v[156:159], v[194:197], v[56:59]
	v_mfma_f32_16x16x32_bf16 v[44:47], v[148:151], v[202:205], v[44:47]
	v_mfma_f32_16x16x32_bf16 v[40:43], v[156:159], v[202:205], v[40:43]
	v_mfma_f32_16x16x32_bf16 v[28:31], v[148:151], v[228:231], v[28:31]
	v_mfma_f32_16x16x32_bf16 v[24:27], v[156:159], v[228:231], v[24:27]
	v_mfma_f32_16x16x32_bf16 v[12:15], v[148:151], v[236:239], v[12:15]
	v_mfma_f32_16x16x32_bf16 v[8:11], v[156:159], v[236:239], v[8:11]
	s_setprio 0
	s_setprio 1
	v_mfma_f32_16x16x32_bf16 v[52:55], v[174:177], v[190:193], v[52:55]
	v_mfma_f32_16x16x32_bf16 v[48:51], v[182:185], v[190:193], v[48:51]
	v_mfma_f32_16x16x32_bf16 v[36:39], v[174:177], v[198:201], v[36:39]
	v_mfma_f32_16x16x32_bf16 v[32:35], v[182:185], v[198:201], v[32:35]
	v_mfma_f32_16x16x32_bf16 v[20:23], v[174:177], v[220:223], v[20:23]
	v_mfma_f32_16x16x32_bf16 v[16:19], v[182:185], v[220:223], v[16:19]
	v_mfma_f32_16x16x32_bf16 v[4:7], v[174:177], v[232:235], v[4:7]
	v_mfma_f32_16x16x32_bf16 v[0:3], v[182:185], v[232:235], v[0:3]
	v_mfma_f32_16x16x32_bf16 v[52:55], v[178:181], v[194:197], v[52:55]
	v_mfma_f32_16x16x32_bf16 v[48:51], v[186:189], v[194:197], v[48:51]
	v_mfma_f32_16x16x32_bf16 v[36:39], v[178:181], v[202:205], v[36:39]
	v_mfma_f32_16x16x32_bf16 v[32:35], v[186:189], v[202:205], v[32:35]
	v_mfma_f32_16x16x32_bf16 v[20:23], v[178:181], v[228:231], v[20:23]
	v_mfma_f32_16x16x32_bf16 v[16:19], v[186:189], v[228:231], v[16:19]
	v_mfma_f32_16x16x32_bf16 v[4:7], v[178:181], v[236:239], v[4:7]
	v_mfma_f32_16x16x32_bf16 v[0:3], v[186:189], v[236:239], v[0:3]
	s_setprio 0
	s_barrier
	s_add_i32 s53, s53, 2
	s_add_u32 s60, s60, 0x100
	s_addc_u32 s61, s61, 0
	s_add_u32 s30, s30, 0x100
	s_addc_u32 s31, s31, 0
	s_cmp_gt_u32 s53, 13
	s_cbranch_scc0 .LBB0_771
	s_and_b64 vcc, exec, s[48:49]
	s_mov_b64 s[30:31], s[34:35]
	s_cbranch_vccz .LBB0_774
	s_barrier

.LBB0_858:
	s_add_u32 s61, s66, 0xfffe0080
	s_addc_u32 s68, s67, -1
	s_add_i32 s83, 0, 0x10000
	s_cmp_eq_u32 s59, 4
	s_cselect_b32 s71, s6, s68
	s_cselect_b32 s70, s7, s61
	v_add_u32_e32 v136, s83, v157
	s_cselect_b32 s69, s28, s31
	s_cselect_b32 s68, s29, s30
	s_add_i32 s61, 0, 0x14000
	ds_read_b128 v[128:131], v136
	ds_read_b128 v[132:135], v136 offset:1024
	ds_read_b128 v[148:151], v136 offset:2048
	ds_read_b128 v[152:155], v136 offset:3072
	v_add_u32_e32 v136, s61, v157
	ds_read_b128 v[174:177], v136
	ds_read_b128 v[178:181], v136 offset:1024
	ds_read_b128 v[182:185], v136 offset:2048
	ds_read_b128 v[186:189], v136 offset:3072
	v_lshl_add_u64 v[136:137], s[66:67], 0, v[144:145]
	s_add_i32 m0, s25, 0xc000
	ds_read_b128 v[190:193], v159
	ds_read_b128 v[194:197], v159 offset:1024
	ds_read_b128 v[198:201], v159 offset:2048
	ds_read_b128 v[202:205], v159 offset:3072
	ds_read_b128 v[220:223], v159 offset:4096
	ds_read_b128 v[228:231], v159 offset:5120
	ds_read_b128 v[232:235], v159 offset:6144
	ds_read_b128 v[236:239], v159 offset:7168
	global_load_lds_dwordx4 v[136:137], off
	v_lshl_add_u64 v[136:137], s[66:67], 0, v[146:147]
	s_add_i32 m0, s25, 0xe000
	s_nop 0
	global_load_lds_dwordx4 v[136:137], off
	s_waitcnt vmcnt(8)
	s_waitcnt lgkmcnt(0)
	s_barrier
	s_setprio 1
	s_waitcnt lgkmcnt(0)
	v_mfma_f32_16x16x32_bf16 v[124:127], v[128:131], v[190:193], v[124:127]
	v_mfma_f32_16x16x32_bf16 v[120:123], v[148:151], v[190:193], v[120:123]
	v_mfma_f32_16x16x32_bf16 v[108:111], v[128:131], v[198:201], v[108:111]
	v_mfma_f32_16x16x32_bf16 v[104:107], v[148:151], v[198:201], v[104:107]
	v_mfma_f32_16x16x32_bf16 v[92:95], v[128:131], v[220:223], v[92:95]
	v_mfma_f32_16x16x32_bf16 v[88:91], v[148:151], v[220:223], v[88:91]
	v_mfma_f32_16x16x32_bf16 v[76:79], v[128:131], v[232:235], v[76:79]
	v_mfma_f32_16x16x32_bf16 v[72:75], v[148:151], v[232:235], v[72:75]
	v_mfma_f32_16x16x32_bf16 v[124:127], v[132:135], v[194:197], v[124:127]
	v_mfma_f32_16x16x32_bf16 v[120:123], v[152:155], v[194:197], v[120:123]
	v_mfma_f32_16x16x32_bf16 v[108:111], v[132:135], v[202:205], v[108:111]
	v_mfma_f32_16x16x32_bf16 v[104:107], v[152:155], v[202:205], v[104:107]
	v_mfma_f32_16x16x32_bf16 v[92:95], v[132:135], v[228:231], v[92:95]
	v_mfma_f32_16x16x32_bf16 v[88:91], v[152:155], v[228:231], v[88:91]
	v_mfma_f32_16x16x32_bf16 v[76:79], v[132:135], v[236:239], v[76:79]
	v_mfma_f32_16x16x32_bf16 v[72:75], v[152:155], v[236:239], v[72:75]
	s_setprio 0
	s_setprio 1
	v_mfma_f32_16x16x32_bf16 v[116:119], v[174:177], v[190:193], v[116:119]
	v_mfma_f32_16x16x32_bf16 v[112:115], v[182:185], v[190:193], v[112:115]
	v_mfma_f32_16x16x32_bf16 v[100:103], v[174:177], v[198:201], v[100:103]
	v_mfma_f32_16x16x32_bf16 v[96:99], v[182:185], v[198:201], v[96:99]
	v_mfma_f32_16x16x32_bf16 v[84:87], v[174:177], v[220:223], v[84:87]
	v_mfma_f32_16x16x32_bf16 v[80:83], v[182:185], v[220:223], v[80:83]
	v_mfma_f32_16x16x32_bf16 v[68:71], v[174:177], v[232:235], v[68:71]
	v_mfma_f32_16x16x32_bf16 v[64:67], v[182:185], v[232:235], v[64:67]
	v_mfma_f32_16x16x32_bf16 v[116:119], v[178:181], v[194:197], v[116:119]
	v_mfma_f32_16x16x32_bf16 v[112:115], v[186:189], v[194:197], v[112:115]
	v_mfma_f32_16x16x32_bf16 v[100:103], v[178:181], v[202:205], v[100:103]
	v_mfma_f32_16x16x32_bf16 v[96:99], v[186:189], v[202:205], v[96:99]
	v_mfma_f32_16x16x32_bf16 v[84:87], v[178:181], v[228:231], v[84:87]
	v_mfma_f32_16x16x32_bf16 v[80:83], v[186:189], v[228:231], v[80:83]
	v_mfma_f32_16x16x32_bf16 v[68:71], v[178:181], v[236:239], v[68:71]
	v_mfma_f32_16x16x32_bf16 v[64:67], v[186:189], v[236:239], v[64:67]
	s_setprio 0
	s_barrier
	s_add_i32 s83, s83, s22
	v_lshl_add_u64 v[136:137], s[68:69], 0, v[162:163]
	s_mov_b32 m0, s83
	s_nop 0
	global_load_lds_dwordx4 v[136:137], off
	s_add_i32 m0, s83, 0x2000
	s_add_u32 s84, s68, 0x20000
	v_lshl_add_u64 v[240:241], s[68:69], 0, v[138:139]
	s_addc_u32 s85, s69, 0
	s_add_i32 s61, s61, s22
	global_load_lds_dwordx4 v[240:241], off
	v_lshl_add_u64 v[242:243], s[84:85], 0, v[162:163]
	s_mov_b32 m0, s61
	v_lshl_add_u64 v[244:245], s[70:71], 0, v[140:141]
	global_load_lds_dwordx4 v[242:243], off
	v_lshl_add_u64 v[242:243], s[84:85], 0, v[138:139]
	s_add_i32 m0, s61, 0x2000
	s_nop 0
	global_load_lds_dwordx4 v[242:243], off
	v_lshl_add_u64 v[242:243], s[70:71], 0, v[142:143]
	s_mov_b32 m0, s25
	s_nop 0
	global_load_lds_dwordx4 v[242:243], off
	s_mov_b32 m0, s72
	s_nop 0
	global_load_lds_dwordx4 v[244:245], off
	ds_read_b128 v[190:193], v159 offset:16384
	ds_read_b128 v[194:197], v159 offset:17408
	ds_read_b128 v[198:201], v159 offset:18432
	ds_read_b128 v[202:205], v159 offset:19456
	ds_read_b128 v[220:223], v159 offset:20480
	ds_read_b128 v[228:231], v159 offset:21504
	ds_read_b128 v[232:235], v159 offset:22528
	ds_read_b128 v[236:239], v159 offset:23552
	s_waitcnt vmcnt(8)
	s_waitcnt lgkmcnt(0)
	s_barrier
	s_setprio 1
	s_waitcnt lgkmcnt(0)
	v_mfma_f32_16x16x32_bf16 v[60:63], v[128:131], v[190:193], v[60:63]
	v_mfma_f32_16x16x32_bf16 v[56:59], v[148:151], v[190:193], v[56:59]
	v_mfma_f32_16x16x32_bf16 v[44:47], v[128:131], v[198:201], v[44:47]
	v_mfma_f32_16x16x32_bf16 v[40:43], v[148:151], v[198:201], v[40:43]
	v_mfma_f32_16x16x32_bf16 v[28:31], v[128:131], v[220:223], v[28:31]
	v_mfma_f32_16x16x32_bf16 v[24:27], v[148:151], v[220:223], v[24:27]
	v_mfma_f32_16x16x32_bf16 v[12:15], v[128:131], v[232:235], v[12:15]
	v_mfma_f32_16x16x32_bf16 v[8:11], v[148:151], v[232:235], v[8:11]
	v_mfma_f32_16x16x32_bf16 v[60:63], v[132:135], v[194:197], v[60:63]
	v_mfma_f32_16x16x32_bf16 v[56:59], v[152:155], v[194:197], v[56:59]
	v_mfma_f32_16x16x32_bf16 v[44:47], v[132:135], v[202:205], v[44:47]
	v_mfma_f32_16x16x32_bf16 v[40:43], v[152:155], v[202:205], v[40:43]
	v_mfma_f32_16x16x32_bf16 v[28:31], v[132:135], v[228:231], v[28:31]
	v_mfma_f32_16x16x32_bf16 v[24:27], v[152:155], v[228:231], v[24:27]
	v_mfma_f32_16x16x32_bf16 v[12:15], v[132:135], v[236:239], v[12:15]
	v_mfma_f32_16x16x32_bf16 v[8:11], v[152:155], v[236:239], v[8:11]
	s_setprio 0
	s_setprio 1
	v_mfma_f32_16x16x32_bf16 v[52:55], v[174:177], v[190:193], v[52:55]
	v_mfma_f32_16x16x32_bf16 v[48:51], v[182:185], v[190:193], v[48:51]
	v_mfma_f32_16x16x32_bf16 v[36:39], v[174:177], v[198:201], v[36:39]
	v_mfma_f32_16x16x32_bf16 v[32:35], v[182:185], v[198:201], v[32:35]
	v_mfma_f32_16x16x32_bf16 v[20:23], v[174:177], v[220:223], v[20:23]
	v_mfma_f32_16x16x32_bf16 v[16:19], v[182:185], v[220:223], v[16:19]
	v_mfma_f32_16x16x32_bf16 v[4:7], v[174:177], v[232:235], v[4:7]
	v_mfma_f32_16x16x32_bf16 v[0:3], v[182:185], v[232:235], v[0:3]
	v_mfma_f32_16x16x32_bf16 v[52:55], v[178:181], v[194:197], v[52:55]
	v_mfma_f32_16x16x32_bf16 v[48:51], v[186:189], v[194:197], v[48:51]
	v_mfma_f32_16x16x32_bf16 v[36:39], v[178:181], v[202:205], v[36:39]
	v_mfma_f32_16x16x32_bf16 v[32:35], v[186:189], v[202:205], v[32:35]
	v_mfma_f32_16x16x32_bf16 v[20:23], v[178:181], v[228:231], v[20:23]
	v_mfma_f32_16x16x32_bf16 v[16:19], v[186:189], v[228:231], v[16:19]
	v_mfma_f32_16x16x32_bf16 v[4:7], v[178:181], v[236:239], v[4:7]
	v_mfma_f32_16x16x32_bf16 v[0:3], v[186:189], v[236:239], v[0:3]
	s_setprio 0
	s_barrier
	s_add_i32 s61, 0, 0x18000
	s_add_i32 s83, 0, 0x1c000
	v_add_u32_e32 v152, s61, v157
	v_add_u32_e32 v186, s83, v157
	ds_read_b128 v[128:131], v152
	ds_read_b128 v[132:135], v152 offset:1024
	ds_read_b128 v[148:151], v152 offset:2048
	ds_read_b128 v[152:155], v152 offset:3072
	ds_read_b128 v[174:177], v186
	ds_read_b128 v[178:181], v186 offset:1024
	ds_read_b128 v[182:185], v186 offset:2048
	ds_read_b128 v[186:189], v186 offset:3072
	s_add_u32 s70, s70, 0x20000
	s_addc_u32 s71, s71, 0
	s_mov_b32 m0, s73
	v_lshl_add_u64 v[246:247], s[70:71], 0, v[142:143]
	ds_read_b128 v[190:193], v159 offset:32768
	ds_read_b128 v[194:197], v159 offset:33792
	ds_read_b128 v[198:201], v159 offset:34816
	ds_read_b128 v[202:205], v159 offset:35840
	ds_read_b128 v[220:223], v159 offset:36864
	ds_read_b128 v[228:231], v159 offset:37888
	ds_read_b128 v[232:235], v159 offset:38912
	ds_read_b128 v[236:239], v159 offset:39936
	global_load_lds_dwordx4 v[246:247], off
	v_lshl_add_u64 v[246:247], s[70:71], 0, v[140:141]
	s_mov_b32 m0, s74
	s_nop 0
	global_load_lds_dwordx4 v[246:247], off
	s_waitcnt vmcnt(8)
	s_waitcnt lgkmcnt(0)
	s_barrier
	s_setprio 1
	s_waitcnt lgkmcnt(0)
	v_mfma_f32_16x16x32_bf16 v[124:127], v[128:131], v[190:193], v[124:127]
	v_mfma_f32_16x16x32_bf16 v[120:123], v[148:151], v[190:193], v[120:123]
	v_mfma_f32_16x16x32_bf16 v[108:111], v[128:131], v[198:201], v[108:111]
	v_mfma_f32_16x16x32_bf16 v[104:107], v[148:151], v[198:201], v[104:107]
	v_mfma_f32_16x16x32_bf16 v[92:95], v[128:131], v[220:223], v[92:95]
	v_mfma_f32_16x16x32_bf16 v[88:91], v[148:151], v[220:223], v[88:91]
	v_mfma_f32_16x16x32_bf16 v[76:79], v[128:131], v[232:235], v[76:79]
	v_mfma_f32_16x16x32_bf16 v[72:75], v[148:151], v[232:235], v[72:75]
	v_mfma_f32_16x16x32_bf16 v[124:127], v[132:135], v[194:197], v[124:127]
	v_mfma_f32_16x16x32_bf16 v[120:123], v[152:155], v[194:197], v[120:123]
	v_mfma_f32_16x16x32_bf16 v[108:111], v[132:135], v[202:205], v[108:111]
	v_mfma_f32_16x16x32_bf16 v[104:107], v[152:155], v[202:205], v[104:107]
	v_mfma_f32_16x16x32_bf16 v[92:95], v[132:135], v[228:231], v[92:95]
	v_mfma_f32_16x16x32_bf16 v[88:91], v[152:155], v[228:231], v[88:91]
	v_mfma_f32_16x16x32_bf16 v[76:79], v[132:135], v[236:239], v[76:79]
	v_mfma_f32_16x16x32_bf16 v[72:75], v[152:155], v[236:239], v[72:75]
	s_setprio 0
	s_setprio 1
	v_mfma_f32_16x16x32_bf16 v[116:119], v[174:177], v[190:193], v[116:119]
	v_mfma_f32_16x16x32_bf16 v[112:115], v[182:185], v[190:193], v[112:115]
	v_mfma_f32_16x16x32_bf16 v[100:103], v[174:177], v[198:201], v[100:103]
	v_mfma_f32_16x16x32_bf16 v[96:99], v[182:185], v[198:201], v[96:99]
	v_mfma_f32_16x16x32_bf16 v[84:87], v[174:177], v[220:223], v[84:87]
	v_mfma_f32_16x16x32_bf16 v[80:83], v[182:185], v[220:223], v[80:83]
	v_mfma_f32_16x16x32_bf16 v[68:71], v[174:177], v[232:235], v[68:71]
	v_mfma_f32_16x16x32_bf16 v[64:67], v[182:185], v[232:235], v[64:67]
	v_mfma_f32_16x16x32_bf16 v[116:119], v[178:181], v[194:197], v[116:119]
	v_mfma_f32_16x16x32_bf16 v[112:115], v[186:189], v[194:197], v[112:115]
	v_mfma_f32_16x16x32_bf16 v[100:103], v[178:181], v[202:205], v[100:103]
	v_mfma_f32_16x16x32_bf16 v[96:99], v[186:189], v[202:205], v[96:99]
	v_mfma_f32_16x16x32_bf16 v[84:87], v[178:181], v[228:231], v[84:87]
	v_mfma_f32_16x16x32_bf16 v[80:83], v[186:189], v[228:231], v[80:83]
	v_mfma_f32_16x16x32_bf16 v[68:71], v[178:181], v[236:239], v[68:71]
	v_mfma_f32_16x16x32_bf16 v[64:67], v[186:189], v[236:239], v[64:67]
	s_setprio 0
	s_barrier
	s_add_i32 s61, s61, s22
	v_lshl_add_u64 v[136:137], v[136:137], 0, s[4:5]
	s_mov_b32 m0, s61
	s_nop 0
	global_load_lds_dwordx4 v[136:137], off
	s_add_i32 m0, s61, 0x2000
	s_add_u32 s68, s68, 0x20080
	v_lshl_add_u64 v[136:137], v[240:241], 0, s[4:5]
	s_addc_u32 s69, s69, 0
	s_add_i32 s61, s83, s22
	global_load_lds_dwordx4 v[136:137], off
	v_lshl_add_u64 v[136:137], s[68:69], 0, v[162:163]
	s_mov_b32 m0, s61
	s_nop 0
	global_load_lds_dwordx4 v[136:137], off
	v_lshl_add_u64 v[136:137], s[68:69], 0, v[138:139]
	s_add_i32 m0, s61, 0x2000
	s_nop 0
	global_load_lds_dwordx4 v[136:137], off
	v_lshl_add_u64 v[136:137], v[242:243], 0, s[4:5]
	s_mov_b32 m0, s75
	s_nop 0
	global_load_lds_dwordx4 v[136:137], off
	v_lshl_add_u64 v[136:137], v[244:245], 0, s[4:5]
	s_mov_b32 m0, s76
	s_nop 0
	global_load_lds_dwordx4 v[136:137], off
	ds_read_b128 v[190:193], v159 offset:49152
	ds_read_b128 v[194:197], v159 offset:50176
	ds_read_b128 v[198:201], v159 offset:51200
	ds_read_b128 v[202:205], v159 offset:52224
	ds_read_b128 v[220:223], v159 offset:53248
	ds_read_b128 v[228:231], v159 offset:54272
	ds_read_b128 v[232:235], v159 offset:55296
	ds_read_b128 v[236:239], v159 offset:56320
	s_waitcnt vmcnt(8)
	s_waitcnt lgkmcnt(0)
	s_barrier
	s_setprio 1
	s_waitcnt lgkmcnt(0)
	v_mfma_f32_16x16x32_bf16 v[60:63], v[128:131], v[190:193], v[60:63]
	v_mfma_f32_16x16x32_bf16 v[56:59], v[148:151], v[190:193], v[56:59]
	v_mfma_f32_16x16x32_bf16 v[44:47], v[128:131], v[198:201], v[44:47]
	v_mfma_f32_16x16x32_bf16 v[40:43], v[148:151], v[198:201], v[40:43]
	v_mfma_f32_16x16x32_bf16 v[28:31], v[128:131], v[220:223], v[28:31]
	v_mfma_f32_16x16x32_bf16 v[24:27], v[148:151], v[220:223], v[24:27]
	v_mfma_f32_16x16x32_bf16 v[12:15], v[128:131], v[232:235], v[12:15]
	v_mfma_f32_16x16x32_bf16 v[8:11], v[148:151], v[232:235], v[8:11]
	v_mfma_f32_16x16x32_bf16 v[60:63], v[132:135], v[194:197], v[60:63]
	v_mfma_f32_16x16x32_bf16 v[56:59], v[152:155], v[194:197], v[56:59]
	v_mfma_f32_16x16x32_bf16 v[44:47], v[132:135], v[202:205], v[44:47]
	v_mfma_f32_16x16x32_bf16 v[40:43], v[152:155], v[202:205], v[40:43]
	v_mfma_f32_16x16x32_bf16 v[28:31], v[132:135], v[228:231], v[28:31]
	v_mfma_f32_16x16x32_bf16 v[24:27], v[152:155], v[228:231], v[24:27]
	v_mfma_f32_16x16x32_bf16 v[12:15], v[132:135], v[236:239], v[12:15]
	v_mfma_f32_16x16x32_bf16 v[8:11], v[152:155], v[236:239], v[8:11]
	s_setprio 0
	s_setprio 1
	v_mfma_f32_16x16x32_bf16 v[52:55], v[174:177], v[190:193], v[52:55]
	v_mfma_f32_16x16x32_bf16 v[48:51], v[182:185], v[190:193], v[48:51]
	v_mfma_f32_16x16x32_bf16 v[36:39], v[174:177], v[198:201], v[36:39]
	v_mfma_f32_16x16x32_bf16 v[32:35], v[182:185], v[198:201], v[32:35]
	v_mfma_f32_16x16x32_bf16 v[20:23], v[174:177], v[220:223], v[20:23]
	v_mfma_f32_16x16x32_bf16 v[16:19], v[182:185], v[220:223], v[16:19]
	v_mfma_f32_16x16x32_bf16 v[4:7], v[174:177], v[232:235], v[4:7]
	v_mfma_f32_16x16x32_bf16 v[0:3], v[182:185], v[232:235], v[0:3]
	v_mfma_f32_16x16x32_bf16 v[52:55], v[178:181], v[194:197], v[52:55]
	v_mfma_f32_16x16x32_bf16 v[48:51], v[186:189], v[194:197], v[48:51]
	v_mfma_f32_16x16x32_bf16 v[36:39], v[178:181], v[202:205], v[36:39]
	v_mfma_f32_16x16x32_bf16 v[32:35], v[186:189], v[202:205], v[32:35]
	v_mfma_f32_16x16x32_bf16 v[20:23], v[178:181], v[228:231], v[20:23]
	v_mfma_f32_16x16x32_bf16 v[16:19], v[186:189], v[228:231], v[16:19]
	v_mfma_f32_16x16x32_bf16 v[4:7], v[178:181], v[236:239], v[4:7]
	v_mfma_f32_16x16x32_bf16 v[0:3], v[186:189], v[236:239], v[0:3]
	s_setprio 0
	s_barrier
	s_add_i32 s59, s59, 2
	s_add_u32 s66, s66, 0x100
	s_addc_u32 s67, s67, 0
	s_add_u32 s30, s30, 0x100
	s_addc_u32 s31, s31, 0
	s_cmp_gt_u32 s59, 5
	s_cbranch_scc0 .LBB0_858
	s_and_b64 vcc, exec, s[56:57]
	s_cbranch_vccz .LBB0_861
	s_barrier

.LBB0_975:
	s_add_u32 s29, s60, 0xfffc0080
	s_addc_u32 s30, s61, -1
	s_add_i32 s31, 0, 0x10000
	s_cmp_eq_u32 s28, 12
	s_cselect_b32 s65, s6, s30
	s_cselect_b32 s64, s7, s29
	v_add_u32_e32 v142, s31, v145
	s_cselect_b32 s63, s24, s27
	s_cselect_b32 s62, s25, s26
	s_add_i32 s29, 0, 0x14000
	ds_read_b128 v[138:141], v142
	ds_read_b128 v[148:151], v142 offset:1024
	ds_read_b128 v[152:155], v142 offset:2048
	ds_read_b128 v[156:159], v142 offset:3072
	v_add_u32_e32 v142, s29, v145
	ds_read_b128 v[174:177], v142
	ds_read_b128 v[178:181], v142 offset:1024
	ds_read_b128 v[182:185], v142 offset:2048
	ds_read_b128 v[186:189], v142 offset:3072
	v_lshl_add_u64 v[142:143], s[60:61], 0, v[134:135]
	s_add_i32 m0, s69, 0xc000
	ds_read_b128 v[190:193], v147
	ds_read_b128 v[194:197], v147 offset:1024
	ds_read_b128 v[198:201], v147 offset:2048
	ds_read_b128 v[202:205], v147 offset:3072
	ds_read_b128 v[220:223], v147 offset:4096
	ds_read_b128 v[228:231], v147 offset:5120
	ds_read_b128 v[232:235], v147 offset:6144
	ds_read_b128 v[236:239], v147 offset:7168
	global_load_lds_dwordx4 v[142:143], off
	v_lshl_add_u64 v[142:143], s[60:61], 0, v[136:137]
	s_add_i32 m0, s69, 0xe000
	s_nop 0
	global_load_lds_dwordx4 v[142:143], off
	s_waitcnt vmcnt(8)
	s_waitcnt lgkmcnt(0)
	s_barrier
	s_setprio 1
	s_waitcnt lgkmcnt(0)
	v_mfma_f32_16x16x32_bf16 v[124:127], v[138:141], v[190:193], v[124:127]
	v_mfma_f32_16x16x32_bf16 v[120:123], v[152:155], v[190:193], v[120:123]
	v_mfma_f32_16x16x32_bf16 v[108:111], v[138:141], v[198:201], v[108:111]
	v_mfma_f32_16x16x32_bf16 v[104:107], v[152:155], v[198:201], v[104:107]
	v_mfma_f32_16x16x32_bf16 v[92:95], v[138:141], v[220:223], v[92:95]
	v_mfma_f32_16x16x32_bf16 v[88:91], v[152:155], v[220:223], v[88:91]
	v_mfma_f32_16x16x32_bf16 v[76:79], v[138:141], v[232:235], v[76:79]
	v_mfma_f32_16x16x32_bf16 v[72:75], v[152:155], v[232:235], v[72:75]
	v_mfma_f32_16x16x32_bf16 v[124:127], v[148:151], v[194:197], v[124:127]
	v_mfma_f32_16x16x32_bf16 v[120:123], v[156:159], v[194:197], v[120:123]
	v_mfma_f32_16x16x32_bf16 v[108:111], v[148:151], v[202:205], v[108:111]
	v_mfma_f32_16x16x32_bf16 v[104:107], v[156:159], v[202:205], v[104:107]
	v_mfma_f32_16x16x32_bf16 v[92:95], v[148:151], v[228:231], v[92:95]
	v_mfma_f32_16x16x32_bf16 v[88:91], v[156:159], v[228:231], v[88:91]
	v_mfma_f32_16x16x32_bf16 v[76:79], v[148:151], v[236:239], v[76:79]
	v_mfma_f32_16x16x32_bf16 v[72:75], v[156:159], v[236:239], v[72:75]
	s_setprio 0
	s_setprio 1
	v_mfma_f32_16x16x32_bf16 v[116:119], v[174:177], v[190:193], v[116:119]
	v_mfma_f32_16x16x32_bf16 v[112:115], v[182:185], v[190:193], v[112:115]
	v_mfma_f32_16x16x32_bf16 v[100:103], v[174:177], v[198:201], v[100:103]
	v_mfma_f32_16x16x32_bf16 v[96:99], v[182:185], v[198:201], v[96:99]
	v_mfma_f32_16x16x32_bf16 v[84:87], v[174:177], v[220:223], v[84:87]
	v_mfma_f32_16x16x32_bf16 v[80:83], v[182:185], v[220:223], v[80:83]
	v_mfma_f32_16x16x32_bf16 v[68:71], v[174:177], v[232:235], v[68:71]
	v_mfma_f32_16x16x32_bf16 v[64:67], v[182:185], v[232:235], v[64:67]
	v_mfma_f32_16x16x32_bf16 v[116:119], v[178:181], v[194:197], v[116:119]
	v_mfma_f32_16x16x32_bf16 v[112:115], v[186:189], v[194:197], v[112:115]
	v_mfma_f32_16x16x32_bf16 v[100:103], v[178:181], v[202:205], v[100:103]
	v_mfma_f32_16x16x32_bf16 v[96:99], v[186:189], v[202:205], v[96:99]
	v_mfma_f32_16x16x32_bf16 v[84:87], v[178:181], v[228:231], v[84:87]
	v_mfma_f32_16x16x32_bf16 v[80:83], v[186:189], v[228:231], v[80:83]
	v_mfma_f32_16x16x32_bf16 v[68:71], v[178:181], v[236:239], v[68:71]
	v_mfma_f32_16x16x32_bf16 v[64:67], v[186:189], v[236:239], v[64:67]
	s_setprio 0
	s_barrier
	s_add_i32 s30, s31, s68
	v_lshl_add_u64 v[142:143], s[62:63], 0, v[162:163]
	s_mov_b32 m0, s30
	s_nop 0
	global_load_lds_dwordx4 v[142:143], off
	s_add_i32 m0, s30, 0x2000
	s_add_u32 s30, s62, 0x40000
	v_lshl_add_u64 v[240:241], s[62:63], 0, v[128:129]
	s_addc_u32 s31, s63, 0
	s_add_i32 s29, s29, s68
	global_load_lds_dwordx4 v[240:241], off
	v_lshl_add_u64 v[242:243], s[30:31], 0, v[162:163]
	s_mov_b32 m0, s29
	v_lshl_add_u64 v[244:245], s[64:65], 0, v[130:131]
	global_load_lds_dwordx4 v[242:243], off
	v_lshl_add_u64 v[242:243], s[30:31], 0, v[128:129]
	s_add_i32 m0, s29, 0x2000
	s_nop 0
	global_load_lds_dwordx4 v[242:243], off
	v_lshl_add_u64 v[242:243], s[64:65], 0, v[132:133]
	s_mov_b32 m0, s69
	s_nop 0
	global_load_lds_dwordx4 v[242:243], off
	s_mov_b32 m0, s70
	s_nop 0
	global_load_lds_dwordx4 v[244:245], off
	ds_read_b128 v[190:193], v147 offset:16384
	ds_read_b128 v[194:197], v147 offset:17408
	ds_read_b128 v[198:201], v147 offset:18432
	ds_read_b128 v[202:205], v147 offset:19456
	ds_read_b128 v[220:223], v147 offset:20480
	ds_read_b128 v[228:231], v147 offset:21504
	ds_read_b128 v[232:235], v147 offset:22528
	ds_read_b128 v[236:239], v147 offset:23552
	s_waitcnt vmcnt(8)
	s_waitcnt lgkmcnt(0)
	s_barrier
	s_setprio 1
	s_waitcnt lgkmcnt(0)
	v_mfma_f32_16x16x32_bf16 v[60:63], v[138:141], v[190:193], v[60:63]
	v_mfma_f32_16x16x32_bf16 v[56:59], v[152:155], v[190:193], v[56:59]
	v_mfma_f32_16x16x32_bf16 v[44:47], v[138:141], v[198:201], v[44:47]
	v_mfma_f32_16x16x32_bf16 v[40:43], v[152:155], v[198:201], v[40:43]
	v_mfma_f32_16x16x32_bf16 v[28:31], v[138:141], v[220:223], v[28:31]
	v_mfma_f32_16x16x32_bf16 v[24:27], v[152:155], v[220:223], v[24:27]
	v_mfma_f32_16x16x32_bf16 v[12:15], v[138:141], v[232:235], v[12:15]
	v_mfma_f32_16x16x32_bf16 v[8:11], v[152:155], v[232:235], v[8:11]
	v_mfma_f32_16x16x32_bf16 v[60:63], v[148:151], v[194:197], v[60:63]
	v_mfma_f32_16x16x32_bf16 v[56:59], v[156:159], v[194:197], v[56:59]
	v_mfma_f32_16x16x32_bf16 v[44:47], v[148:151], v[202:205], v[44:47]
	v_mfma_f32_16x16x32_bf16 v[40:43], v[156:159], v[202:205], v[40:43]
	v_mfma_f32_16x16x32_bf16 v[28:31], v[148:151], v[228:231], v[28:31]
	v_mfma_f32_16x16x32_bf16 v[24:27], v[156:159], v[228:231], v[24:27]
	v_mfma_f32_16x16x32_bf16 v[12:15], v[148:151], v[236:239], v[12:15]
	v_mfma_f32_16x16x32_bf16 v[8:11], v[156:159], v[236:239], v[8:11]
	s_setprio 0
	s_setprio 1
	v_mfma_f32_16x16x32_bf16 v[52:55], v[174:177], v[190:193], v[52:55]
	v_mfma_f32_16x16x32_bf16 v[48:51], v[182:185], v[190:193], v[48:51]
	v_mfma_f32_16x16x32_bf16 v[36:39], v[174:177], v[198:201], v[36:39]
	v_mfma_f32_16x16x32_bf16 v[32:35], v[182:185], v[198:201], v[32:35]
	v_mfma_f32_16x16x32_bf16 v[20:23], v[174:177], v[220:223], v[20:23]
	v_mfma_f32_16x16x32_bf16 v[16:19], v[182:185], v[220:223], v[16:19]
	v_mfma_f32_16x16x32_bf16 v[4:7], v[174:177], v[232:235], v[4:7]
	v_mfma_f32_16x16x32_bf16 v[0:3], v[182:185], v[232:235], v[0:3]
	v_mfma_f32_16x16x32_bf16 v[52:55], v[178:181], v[194:197], v[52:55]
	v_mfma_f32_16x16x32_bf16 v[48:51], v[186:189], v[194:197], v[48:51]
	v_mfma_f32_16x16x32_bf16 v[36:39], v[178:181], v[202:205], v[36:39]
	v_mfma_f32_16x16x32_bf16 v[32:35], v[186:189], v[202:205], v[32:35]
	v_mfma_f32_16x16x32_bf16 v[20:23], v[178:181], v[228:231], v[20:23]
	v_mfma_f32_16x16x32_bf16 v[16:19], v[186:189], v[228:231], v[16:19]
	v_mfma_f32_16x16x32_bf16 v[4:7], v[178:181], v[236:239], v[4:7]
	v_mfma_f32_16x16x32_bf16 v[0:3], v[186:189], v[236:239], v[0:3]
	s_setprio 0
	s_barrier
	s_add_i32 s29, 0, 0x18000
	s_add_i32 s53, 0, 0x1c000
	v_add_u32_e32 v156, s29, v145
	v_add_u32_e32 v186, s53, v145
	ds_read_b128 v[138:141], v156
	ds_read_b128 v[148:151], v156 offset:1024
	ds_read_b128 v[152:155], v156 offset:2048
	ds_read_b128 v[156:159], v156 offset:3072
	ds_read_b128 v[174:177], v186
	ds_read_b128 v[178:181], v186 offset:1024
	ds_read_b128 v[182:185], v186 offset:2048
	ds_read_b128 v[186:189], v186 offset:3072
	s_add_u32 s30, s64, 0x40000
	s_addc_u32 s31, s65, 0
	s_mov_b32 m0, s71
	v_lshl_add_u64 v[246:247], s[30:31], 0, v[132:133]
	ds_read_b128 v[190:193], v147 offset:32768
	ds_read_b128 v[194:197], v147 offset:33792
	ds_read_b128 v[198:201], v147 offset:34816
	ds_read_b128 v[202:205], v147 offset:35840
	ds_read_b128 v[220:223], v147 offset:36864
	ds_read_b128 v[228:231], v147 offset:37888
	ds_read_b128 v[232:235], v147 offset:38912
	ds_read_b128 v[236:239], v147 offset:39936
	global_load_lds_dwordx4 v[246:247], off
	v_lshl_add_u64 v[246:247], s[30:31], 0, v[130:131]
	s_mov_b32 m0, s72
	s_nop 0
	global_load_lds_dwordx4 v[246:247], off
	s_waitcnt vmcnt(8)
	s_waitcnt lgkmcnt(0)
	s_barrier
	s_setprio 1
	s_waitcnt lgkmcnt(0)
	v_mfma_f32_16x16x32_bf16 v[124:127], v[138:141], v[190:193], v[124:127]
	v_mfma_f32_16x16x32_bf16 v[120:123], v[152:155], v[190:193], v[120:123]
	v_mfma_f32_16x16x32_bf16 v[108:111], v[138:141], v[198:201], v[108:111]
	v_mfma_f32_16x16x32_bf16 v[104:107], v[152:155], v[198:201], v[104:107]
	v_mfma_f32_16x16x32_bf16 v[92:95], v[138:141], v[220:223], v[92:95]
	v_mfma_f32_16x16x32_bf16 v[88:91], v[152:155], v[220:223], v[88:91]
	v_mfma_f32_16x16x32_bf16 v[76:79], v[138:141], v[232:235], v[76:79]
	v_mfma_f32_16x16x32_bf16 v[72:75], v[152:155], v[232:235], v[72:75]
	v_mfma_f32_16x16x32_bf16 v[124:127], v[148:151], v[194:197], v[124:127]
	v_mfma_f32_16x16x32_bf16 v[120:123], v[156:159], v[194:197], v[120:123]
	v_mfma_f32_16x16x32_bf16 v[108:111], v[148:151], v[202:205], v[108:111]
	v_mfma_f32_16x16x32_bf16 v[104:107], v[156:159], v[202:205], v[104:107]
	v_mfma_f32_16x16x32_bf16 v[92:95], v[148:151], v[228:231], v[92:95]
	v_mfma_f32_16x16x32_bf16 v[88:91], v[156:159], v[228:231], v[88:91]
	v_mfma_f32_16x16x32_bf16 v[76:79], v[148:151], v[236:239], v[76:79]
	v_mfma_f32_16x16x32_bf16 v[72:75], v[156:159], v[236:239], v[72:75]
	s_setprio 0
	s_setprio 1
	v_mfma_f32_16x16x32_bf16 v[116:119], v[174:177], v[190:193], v[116:119]
	v_mfma_f32_16x16x32_bf16 v[112:115], v[182:185], v[190:193], v[112:115]
	v_mfma_f32_16x16x32_bf16 v[100:103], v[174:177], v[198:201], v[100:103]
	v_mfma_f32_16x16x32_bf16 v[96:99], v[182:185], v[198:201], v[96:99]
	v_mfma_f32_16x16x32_bf16 v[84:87], v[174:177], v[220:223], v[84:87]
	v_mfma_f32_16x16x32_bf16 v[80:83], v[182:185], v[220:223], v[80:83]
	v_mfma_f32_16x16x32_bf16 v[68:71], v[174:177], v[232:235], v[68:71]
	v_mfma_f32_16x16x32_bf16 v[64:67], v[182:185], v[232:235], v[64:67]
	v_mfma_f32_16x16x32_bf16 v[116:119], v[178:181], v[194:197], v[116:119]
	v_mfma_f32_16x16x32_bf16 v[112:115], v[186:189], v[194:197], v[112:115]
	v_mfma_f32_16x16x32_bf16 v[100:103], v[178:181], v[202:205], v[100:103]
	v_mfma_f32_16x16x32_bf16 v[96:99], v[186:189], v[202:205], v[96:99]
	v_mfma_f32_16x16x32_bf16 v[84:87], v[178:181], v[228:231], v[84:87]
	v_mfma_f32_16x16x32_bf16 v[80:83], v[186:189], v[228:231], v[80:83]
	v_mfma_f32_16x16x32_bf16 v[68:71], v[178:181], v[236:239], v[68:71]
	v_mfma_f32_16x16x32_bf16 v[64:67], v[186:189], v[236:239], v[64:67]
	s_setprio 0
	s_barrier
	s_add_i32 s29, s29, s68
	v_lshl_add_u64 v[142:143], v[142:143], 0, s[4:5]
	s_mov_b32 m0, s29
	s_nop 0
	global_load_lds_dwordx4 v[142:143], off
	s_add_i32 m0, s29, 0x2000
	s_add_u32 s30, s62, 0x40080
	v_lshl_add_u64 v[142:143], v[240:241], 0, s[4:5]
	s_addc_u32 s31, s63, 0
	s_add_i32 s29, s53, s68
	global_load_lds_dwordx4 v[142:143], off
	v_lshl_add_u64 v[142:143], s[30:31], 0, v[162:163]
	s_mov_b32 m0, s29
	s_nop 0
	global_load_lds_dwordx4 v[142:143], off
	v_lshl_add_u64 v[142:143], s[30:31], 0, v[128:129]
	s_add_i32 m0, s29, 0x2000
	s_nop 0
	global_load_lds_dwordx4 v[142:143], off
	v_lshl_add_u64 v[142:143], v[242:243], 0, s[4:5]
	s_mov_b32 m0, s74
	s_nop 0
	global_load_lds_dwordx4 v[142:143], off
	v_lshl_add_u64 v[142:143], v[244:245], 0, s[4:5]
	s_mov_b32 m0, s75
	s_nop 0
	global_load_lds_dwordx4 v[142:143], off
	ds_read_b128 v[190:193], v147 offset:49152
	ds_read_b128 v[194:197], v147 offset:50176
	ds_read_b128 v[198:201], v147 offset:51200
	ds_read_b128 v[202:205], v147 offset:52224
	ds_read_b128 v[220:223], v147 offset:53248
	ds_read_b128 v[228:231], v147 offset:54272
	ds_read_b128 v[232:235], v147 offset:55296
	ds_read_b128 v[236:239], v147 offset:56320
	s_waitcnt vmcnt(8)
	s_waitcnt lgkmcnt(0)
	s_barrier
	s_setprio 1
	s_waitcnt lgkmcnt(0)
	v_mfma_f32_16x16x32_bf16 v[60:63], v[138:141], v[190:193], v[60:63]
	v_mfma_f32_16x16x32_bf16 v[56:59], v[152:155], v[190:193], v[56:59]
	v_mfma_f32_16x16x32_bf16 v[44:47], v[138:141], v[198:201], v[44:47]
	v_mfma_f32_16x16x32_bf16 v[40:43], v[152:155], v[198:201], v[40:43]
	v_mfma_f32_16x16x32_bf16 v[28:31], v[138:141], v[220:223], v[28:31]
	v_mfma_f32_16x16x32_bf16 v[24:27], v[152:155], v[220:223], v[24:27]
	v_mfma_f32_16x16x32_bf16 v[12:15], v[138:141], v[232:235], v[12:15]
	v_mfma_f32_16x16x32_bf16 v[8:11], v[152:155], v[232:235], v[8:11]
	v_mfma_f32_16x16x32_bf16 v[60:63], v[148:151], v[194:197], v[60:63]
	v_mfma_f32_16x16x32_bf16 v[56:59], v[156:159], v[194:197], v[56:59]
	v_mfma_f32_16x16x32_bf16 v[44:47], v[148:151], v[202:205], v[44:47]
	v_mfma_f32_16x16x32_bf16 v[40:43], v[156:159], v[202:205], v[40:43]
	v_mfma_f32_16x16x32_bf16 v[28:31], v[148:151], v[228:231], v[28:31]
	v_mfma_f32_16x16x32_bf16 v[24:27], v[156:159], v[228:231], v[24:27]
	v_mfma_f32_16x16x32_bf16 v[12:15], v[148:151], v[236:239], v[12:15]
	v_mfma_f32_16x16x32_bf16 v[8:11], v[156:159], v[236:239], v[8:11]
	s_setprio 0
	s_setprio 1
	v_mfma_f32_16x16x32_bf16 v[52:55], v[174:177], v[190:193], v[52:55]
	v_mfma_f32_16x16x32_bf16 v[48:51], v[182:185], v[190:193], v[48:51]
	v_mfma_f32_16x16x32_bf16 v[36:39], v[174:177], v[198:201], v[36:39]
	v_mfma_f32_16x16x32_bf16 v[32:35], v[182:185], v[198:201], v[32:35]
	v_mfma_f32_16x16x32_bf16 v[20:23], v[174:177], v[220:223], v[20:23]
	v_mfma_f32_16x16x32_bf16 v[16:19], v[182:185], v[220:223], v[16:19]
	v_mfma_f32_16x16x32_bf16 v[4:7], v[174:177], v[232:235], v[4:7]
	v_mfma_f32_16x16x32_bf16 v[0:3], v[182:185], v[232:235], v[0:3]
	v_mfma_f32_16x16x32_bf16 v[52:55], v[178:181], v[194:197], v[52:55]
	v_mfma_f32_16x16x32_bf16 v[48:51], v[186:189], v[194:197], v[48:51]
	v_mfma_f32_16x16x32_bf16 v[36:39], v[178:181], v[202:205], v[36:39]
	v_mfma_f32_16x16x32_bf16 v[32:35], v[186:189], v[202:205], v[32:35]
	v_mfma_f32_16x16x32_bf16 v[20:23], v[178:181], v[228:231], v[20:23]
	v_mfma_f32_16x16x32_bf16 v[16:19], v[186:189], v[228:231], v[16:19]
	v_mfma_f32_16x16x32_bf16 v[4:7], v[178:181], v[236:239], v[4:7]
	v_mfma_f32_16x16x32_bf16 v[0:3], v[186:189], v[236:239], v[0:3]
	s_setprio 0
	s_barrier
	s_add_i32 s28, s28, 2
	s_add_u32 s60, s60, 0x100
	s_addc_u32 s61, s61, 0
	s_add_u32 s26, s26, 0x100
	s_addc_u32 s27, s27, 0
	s_cmp_gt_u32 s28, 13
	s_cbranch_scc0 .LBB0_975
	s_and_b64 vcc, exec, s[50:51]
	s_cbranch_vccz .LBB0_978
	s_barrier

.LBB0_1066:
	s_add_u32 s29, s58, 0xfffc0080
	s_addc_u32 s30, s59, -1
	s_add_i32 s31, 0, 0x10000
	s_cmp_eq_u32 s28, 12
	s_cselect_b32 s63, s6, s30
	s_cselect_b32 s62, s7, s29
	v_add_u32_e32 v142, s31, v144
	s_cselect_b32 s61, s24, s27
	s_cselect_b32 s60, s25, s26
	s_add_i32 s29, 0, 0x14000
	ds_read_b128 v[138:141], v142
	ds_read_b128 v[148:151], v142 offset:1024
	ds_read_b128 v[152:155], v142 offset:2048
	ds_read_b128 v[156:159], v142 offset:3072
	v_add_u32_e32 v142, s29, v144
	ds_read_b128 v[174:177], v142
	ds_read_b128 v[178:181], v142 offset:1024
	ds_read_b128 v[182:185], v142 offset:2048
	ds_read_b128 v[186:189], v142 offset:3072
	v_lshl_add_u64 v[240:241], s[58:59], 0, v[134:135]
	s_add_i32 m0, s67, 0xc000
	ds_read_b128 v[190:193], v146
	ds_read_b128 v[194:197], v146 offset:1024
	ds_read_b128 v[198:201], v146 offset:2048
	ds_read_b128 v[202:205], v146 offset:3072
	ds_read_b128 v[220:223], v146 offset:4096
	ds_read_b128 v[228:231], v146 offset:5120
	ds_read_b128 v[232:235], v146 offset:6144
	ds_read_b128 v[236:239], v146 offset:7168
	global_load_lds_dwordx4 v[240:241], off
	v_lshl_add_u64 v[240:241], s[58:59], 0, v[136:137]
	s_add_i32 m0, s67, 0xe000
	s_nop 0
	global_load_lds_dwordx4 v[240:241], off
	s_waitcnt vmcnt(8)
	s_waitcnt lgkmcnt(0)
	s_barrier
	s_setprio 1
	s_waitcnt lgkmcnt(0)
	v_mfma_f32_16x16x32_bf16 v[124:127], v[138:141], v[190:193], v[124:127]
	v_mfma_f32_16x16x32_bf16 v[120:123], v[152:155], v[190:193], v[120:123]
	v_mfma_f32_16x16x32_bf16 v[108:111], v[138:141], v[198:201], v[108:111]
	v_mfma_f32_16x16x32_bf16 v[104:107], v[152:155], v[198:201], v[104:107]
	v_mfma_f32_16x16x32_bf16 v[92:95], v[138:141], v[220:223], v[92:95]
	v_mfma_f32_16x16x32_bf16 v[88:91], v[152:155], v[220:223], v[88:91]
	v_mfma_f32_16x16x32_bf16 v[76:79], v[138:141], v[232:235], v[76:79]
	v_mfma_f32_16x16x32_bf16 v[72:75], v[152:155], v[232:235], v[72:75]
	v_mfma_f32_16x16x32_bf16 v[124:127], v[148:151], v[194:197], v[124:127]
	v_mfma_f32_16x16x32_bf16 v[120:123], v[156:159], v[194:197], v[120:123]
	v_mfma_f32_16x16x32_bf16 v[108:111], v[148:151], v[202:205], v[108:111]
	v_mfma_f32_16x16x32_bf16 v[104:107], v[156:159], v[202:205], v[104:107]
	v_mfma_f32_16x16x32_bf16 v[92:95], v[148:151], v[228:231], v[92:95]
	v_mfma_f32_16x16x32_bf16 v[88:91], v[156:159], v[228:231], v[88:91]
	v_mfma_f32_16x16x32_bf16 v[76:79], v[148:151], v[236:239], v[76:79]
	v_mfma_f32_16x16x32_bf16 v[72:75], v[156:159], v[236:239], v[72:75]
	s_setprio 0
	s_setprio 1
	v_mfma_f32_16x16x32_bf16 v[116:119], v[174:177], v[190:193], v[116:119]
	v_mfma_f32_16x16x32_bf16 v[112:115], v[182:185], v[190:193], v[112:115]
	v_mfma_f32_16x16x32_bf16 v[100:103], v[174:177], v[198:201], v[100:103]
	v_mfma_f32_16x16x32_bf16 v[96:99], v[182:185], v[198:201], v[96:99]
	v_mfma_f32_16x16x32_bf16 v[84:87], v[174:177], v[220:223], v[84:87]
	v_mfma_f32_16x16x32_bf16 v[80:83], v[182:185], v[220:223], v[80:83]
	v_mfma_f32_16x16x32_bf16 v[68:71], v[174:177], v[232:235], v[68:71]
	v_mfma_f32_16x16x32_bf16 v[64:67], v[182:185], v[232:235], v[64:67]
	v_mfma_f32_16x16x32_bf16 v[116:119], v[178:181], v[194:197], v[116:119]
	v_mfma_f32_16x16x32_bf16 v[112:115], v[186:189], v[194:197], v[112:115]
	v_mfma_f32_16x16x32_bf16 v[100:103], v[178:181], v[202:205], v[100:103]
	v_mfma_f32_16x16x32_bf16 v[96:99], v[186:189], v[202:205], v[96:99]
	v_mfma_f32_16x16x32_bf16 v[84:87], v[178:181], v[228:231], v[84:87]
	v_mfma_f32_16x16x32_bf16 v[80:83], v[186:189], v[228:231], v[80:83]
	v_mfma_f32_16x16x32_bf16 v[68:71], v[178:181], v[236:239], v[68:71]
	v_mfma_f32_16x16x32_bf16 v[64:67], v[186:189], v[236:239], v[64:67]
	s_setprio 0
	s_barrier
	s_add_i32 s30, s31, s66
	v_lshl_add_u64 v[240:241], s[60:61], 0, v[162:163]
	s_mov_b32 m0, s30
	s_nop 0
	global_load_lds_dwordx4 v[240:241], off
	s_add_i32 m0, s30, 0x2000
	s_add_u32 s30, s60, 0x40000
	v_lshl_add_u64 v[242:243], s[60:61], 0, v[128:129]
	s_addc_u32 s31, s61, 0
	s_add_i32 s29, s29, s66
	global_load_lds_dwordx4 v[242:243], off
	v_lshl_add_u64 v[244:245], s[30:31], 0, v[162:163]
	s_mov_b32 m0, s29
	v_lshl_add_u64 v[246:247], s[62:63], 0, v[130:131]
	global_load_lds_dwordx4 v[244:245], off
	v_lshl_add_u64 v[244:245], s[30:31], 0, v[128:129]
	s_add_i32 m0, s29, 0x2000
	s_nop 0
	global_load_lds_dwordx4 v[244:245], off
	v_lshl_add_u64 v[244:245], s[62:63], 0, v[132:133]
	s_mov_b32 m0, s67
	s_nop 0
	global_load_lds_dwordx4 v[244:245], off
	s_mov_b32 m0, s68
	s_nop 0
	global_load_lds_dwordx4 v[246:247], off
	ds_read_b128 v[190:193], v146 offset:16384
	ds_read_b128 v[194:197], v146 offset:17408
	ds_read_b128 v[198:201], v146 offset:18432
	ds_read_b128 v[202:205], v146 offset:19456
	ds_read_b128 v[220:223], v146 offset:20480
	ds_read_b128 v[228:231], v146 offset:21504
	ds_read_b128 v[232:235], v146 offset:22528
	ds_read_b128 v[236:239], v146 offset:23552
	s_waitcnt vmcnt(8)
	s_waitcnt lgkmcnt(0)
	s_barrier
	s_setprio 1
	s_waitcnt lgkmcnt(0)
	v_mfma_f32_16x16x32_bf16 v[60:63], v[138:141], v[190:193], v[60:63]
	v_mfma_f32_16x16x32_bf16 v[56:59], v[152:155], v[190:193], v[56:59]
	v_mfma_f32_16x16x32_bf16 v[44:47], v[138:141], v[198:201], v[44:47]
	v_mfma_f32_16x16x32_bf16 v[40:43], v[152:155], v[198:201], v[40:43]
	v_mfma_f32_16x16x32_bf16 v[28:31], v[138:141], v[220:223], v[28:31]
	v_mfma_f32_16x16x32_bf16 v[24:27], v[152:155], v[220:223], v[24:27]
	v_mfma_f32_16x16x32_bf16 v[12:15], v[138:141], v[232:235], v[12:15]
	v_mfma_f32_16x16x32_bf16 v[8:11], v[152:155], v[232:235], v[8:11]
	v_mfma_f32_16x16x32_bf16 v[60:63], v[148:151], v[194:197], v[60:63]
	v_mfma_f32_16x16x32_bf16 v[56:59], v[156:159], v[194:197], v[56:59]
	v_mfma_f32_16x16x32_bf16 v[44:47], v[148:151], v[202:205], v[44:47]
	v_mfma_f32_16x16x32_bf16 v[40:43], v[156:159], v[202:205], v[40:43]
	v_mfma_f32_16x16x32_bf16 v[28:31], v[148:151], v[228:231], v[28:31]
	v_mfma_f32_16x16x32_bf16 v[24:27], v[156:159], v[228:231], v[24:27]
	v_mfma_f32_16x16x32_bf16 v[12:15], v[148:151], v[236:239], v[12:15]
	v_mfma_f32_16x16x32_bf16 v[8:11], v[156:159], v[236:239], v[8:11]
	s_setprio 0
	s_setprio 1
	v_mfma_f32_16x16x32_bf16 v[52:55], v[174:177], v[190:193], v[52:55]
	v_mfma_f32_16x16x32_bf16 v[48:51], v[182:185], v[190:193], v[48:51]
	v_mfma_f32_16x16x32_bf16 v[36:39], v[174:177], v[198:201], v[36:39]
	v_mfma_f32_16x16x32_bf16 v[32:35], v[182:185], v[198:201], v[32:35]
	v_mfma_f32_16x16x32_bf16 v[20:23], v[174:177], v[220:223], v[20:23]
	v_mfma_f32_16x16x32_bf16 v[16:19], v[182:185], v[220:223], v[16:19]
	v_mfma_f32_16x16x32_bf16 v[4:7], v[174:177], v[232:235], v[4:7]
	v_mfma_f32_16x16x32_bf16 v[0:3], v[182:185], v[232:235], v[0:3]
	v_mfma_f32_16x16x32_bf16 v[52:55], v[178:181], v[194:197], v[52:55]
	v_mfma_f32_16x16x32_bf16 v[48:51], v[186:189], v[194:197], v[48:51]
	v_mfma_f32_16x16x32_bf16 v[36:39], v[178:181], v[202:205], v[36:39]
	v_mfma_f32_16x16x32_bf16 v[32:35], v[186:189], v[202:205], v[32:35]
	v_mfma_f32_16x16x32_bf16 v[20:23], v[178:181], v[228:231], v[20:23]
	v_mfma_f32_16x16x32_bf16 v[16:19], v[186:189], v[228:231], v[16:19]
	v_mfma_f32_16x16x32_bf16 v[4:7], v[178:181], v[236:239], v[4:7]
	v_mfma_f32_16x16x32_bf16 v[0:3], v[186:189], v[236:239], v[0:3]
	s_setprio 0
	s_barrier
	s_add_i32 s29, 0, 0x18000
	v_add_u32_e32 v142, s29, v144
	s_add_i32 s51, 0, 0x1c000
	ds_read_b128 v[138:141], v142
	ds_read_b128 v[148:151], v142 offset:1024
	ds_read_b128 v[152:155], v142 offset:2048
	ds_read_b128 v[156:159], v142 offset:3072
	v_add_u32_e32 v142, s51, v144
	ds_read_b128 v[174:177], v142
	ds_read_b128 v[178:181], v142 offset:1024
	ds_read_b128 v[182:185], v142 offset:2048
	ds_read_b128 v[186:189], v142 offset:3072
	s_add_u32 s30, s62, 0x40000
	s_addc_u32 s31, s63, 0
	s_mov_b32 m0, s69
	v_lshl_add_u64 v[248:249], s[30:31], 0, v[132:133]
	ds_read_b128 v[190:193], v146 offset:32768
	ds_read_b128 v[194:197], v146 offset:33792
	ds_read_b128 v[198:201], v146 offset:34816
	ds_read_b128 v[202:205], v146 offset:35840
	ds_read_b128 v[220:223], v146 offset:36864
	ds_read_b128 v[228:231], v146 offset:37888
	ds_read_b128 v[232:235], v146 offset:38912
	ds_read_b128 v[236:239], v146 offset:39936
	global_load_lds_dwordx4 v[248:249], off
	v_lshl_add_u64 v[248:249], s[30:31], 0, v[130:131]
	s_mov_b32 m0, s70
	s_nop 0
	global_load_lds_dwordx4 v[248:249], off
	s_waitcnt vmcnt(8)
	s_waitcnt lgkmcnt(0)
	s_barrier
	s_setprio 1
	s_waitcnt lgkmcnt(0)
	v_mfma_f32_16x16x32_bf16 v[124:127], v[138:141], v[190:193], v[124:127]
	v_mfma_f32_16x16x32_bf16 v[120:123], v[152:155], v[190:193], v[120:123]
	v_mfma_f32_16x16x32_bf16 v[108:111], v[138:141], v[198:201], v[108:111]
	v_mfma_f32_16x16x32_bf16 v[104:107], v[152:155], v[198:201], v[104:107]
	v_mfma_f32_16x16x32_bf16 v[92:95], v[138:141], v[220:223], v[92:95]
	v_mfma_f32_16x16x32_bf16 v[88:91], v[152:155], v[220:223], v[88:91]
	v_mfma_f32_16x16x32_bf16 v[76:79], v[138:141], v[232:235], v[76:79]
	v_mfma_f32_16x16x32_bf16 v[72:75], v[152:155], v[232:235], v[72:75]
	v_mfma_f32_16x16x32_bf16 v[124:127], v[148:151], v[194:197], v[124:127]
	v_mfma_f32_16x16x32_bf16 v[120:123], v[156:159], v[194:197], v[120:123]
	v_mfma_f32_16x16x32_bf16 v[108:111], v[148:151], v[202:205], v[108:111]
	v_mfma_f32_16x16x32_bf16 v[104:107], v[156:159], v[202:205], v[104:107]
	v_mfma_f32_16x16x32_bf16 v[92:95], v[148:151], v[228:231], v[92:95]
	v_mfma_f32_16x16x32_bf16 v[88:91], v[156:159], v[228:231], v[88:91]
	v_mfma_f32_16x16x32_bf16 v[76:79], v[148:151], v[236:239], v[76:79]
	v_mfma_f32_16x16x32_bf16 v[72:75], v[156:159], v[236:239], v[72:75]
	s_setprio 0
	s_setprio 1
	v_mfma_f32_16x16x32_bf16 v[116:119], v[174:177], v[190:193], v[116:119]
	v_mfma_f32_16x16x32_bf16 v[112:115], v[182:185], v[190:193], v[112:115]
	v_mfma_f32_16x16x32_bf16 v[100:103], v[174:177], v[198:201], v[100:103]
	v_mfma_f32_16x16x32_bf16 v[96:99], v[182:185], v[198:201], v[96:99]
	v_mfma_f32_16x16x32_bf16 v[84:87], v[174:177], v[220:223], v[84:87]
	v_mfma_f32_16x16x32_bf16 v[80:83], v[182:185], v[220:223], v[80:83]
	v_mfma_f32_16x16x32_bf16 v[68:71], v[174:177], v[232:235], v[68:71]
	v_mfma_f32_16x16x32_bf16 v[64:67], v[182:185], v[232:235], v[64:67]
	v_mfma_f32_16x16x32_bf16 v[116:119], v[178:181], v[194:197], v[116:119]
	v_mfma_f32_16x16x32_bf16 v[112:115], v[186:189], v[194:197], v[112:115]
	v_mfma_f32_16x16x32_bf16 v[100:103], v[178:181], v[202:205], v[100:103]
	v_mfma_f32_16x16x32_bf16 v[96:99], v[186:189], v[202:205], v[96:99]
	v_mfma_f32_16x16x32_bf16 v[84:87], v[178:181], v[228:231], v[84:87]
	v_mfma_f32_16x16x32_bf16 v[80:83], v[186:189], v[228:231], v[80:83]
	v_mfma_f32_16x16x32_bf16 v[68:71], v[178:181], v[236:239], v[68:71]
	v_mfma_f32_16x16x32_bf16 v[64:67], v[186:189], v[236:239], v[64:67]
	s_setprio 0
	s_barrier
	s_add_i32 s29, s29, s66
	v_lshl_add_u64 v[240:241], v[240:241], 0, s[4:5]
	s_mov_b32 m0, s29
	s_nop 0
	global_load_lds_dwordx4 v[240:241], off
	s_add_i32 m0, s29, 0x2000
	s_add_u32 s30, s60, 0x40080
	v_lshl_add_u64 v[240:241], v[242:243], 0, s[4:5]
	s_addc_u32 s31, s61, 0
	s_add_i32 s29, s51, s66
	global_load_lds_dwordx4 v[240:241], off
	v_lshl_add_u64 v[240:241], s[30:31], 0, v[162:163]
	s_mov_b32 m0, s29
	s_nop 0
	global_load_lds_dwordx4 v[240:241], off
	v_lshl_add_u64 v[240:241], s[30:31], 0, v[128:129]
	s_add_i32 m0, s29, 0x2000
	s_nop 0
	global_load_lds_dwordx4 v[240:241], off
	v_lshl_add_u64 v[240:241], v[244:245], 0, s[4:5]
	s_mov_b32 m0, s71
	s_nop 0
	global_load_lds_dwordx4 v[240:241], off
	v_lshl_add_u64 v[240:241], v[246:247], 0, s[4:5]
	s_mov_b32 m0, s72
	s_nop 0
	global_load_lds_dwordx4 v[240:241], off
	ds_read_b128 v[190:193], v146 offset:49152
	ds_read_b128 v[194:197], v146 offset:50176
	ds_read_b128 v[198:201], v146 offset:51200
	ds_read_b128 v[202:205], v146 offset:52224
	ds_read_b128 v[220:223], v146 offset:53248
	ds_read_b128 v[228:231], v146 offset:54272
	ds_read_b128 v[232:235], v146 offset:55296
	ds_read_b128 v[236:239], v146 offset:56320
	s_waitcnt vmcnt(8)
	s_waitcnt lgkmcnt(0)
	s_barrier
	s_setprio 1
	s_waitcnt lgkmcnt(0)
	v_mfma_f32_16x16x32_bf16 v[60:63], v[138:141], v[190:193], v[60:63]
	v_mfma_f32_16x16x32_bf16 v[56:59], v[152:155], v[190:193], v[56:59]
	v_mfma_f32_16x16x32_bf16 v[44:47], v[138:141], v[198:201], v[44:47]
	v_mfma_f32_16x16x32_bf16 v[40:43], v[152:155], v[198:201], v[40:43]
	v_mfma_f32_16x16x32_bf16 v[28:31], v[138:141], v[220:223], v[28:31]
	v_mfma_f32_16x16x32_bf16 v[24:27], v[152:155], v[220:223], v[24:27]
	v_mfma_f32_16x16x32_bf16 v[12:15], v[138:141], v[232:235], v[12:15]
	v_mfma_f32_16x16x32_bf16 v[8:11], v[152:155], v[232:235], v[8:11]
	v_mfma_f32_16x16x32_bf16 v[60:63], v[148:151], v[194:197], v[60:63]
	v_mfma_f32_16x16x32_bf16 v[56:59], v[156:159], v[194:197], v[56:59]
	v_mfma_f32_16x16x32_bf16 v[44:47], v[148:151], v[202:205], v[44:47]
	v_mfma_f32_16x16x32_bf16 v[40:43], v[156:159], v[202:205], v[40:43]
	v_mfma_f32_16x16x32_bf16 v[28:31], v[148:151], v[228:231], v[28:31]
	v_mfma_f32_16x16x32_bf16 v[24:27], v[156:159], v[228:231], v[24:27]
	v_mfma_f32_16x16x32_bf16 v[12:15], v[148:151], v[236:239], v[12:15]
	v_mfma_f32_16x16x32_bf16 v[8:11], v[156:159], v[236:239], v[8:11]
	s_setprio 0
	s_setprio 1
	v_mfma_f32_16x16x32_bf16 v[52:55], v[174:177], v[190:193], v[52:55]
	v_mfma_f32_16x16x32_bf16 v[48:51], v[182:185], v[190:193], v[48:51]
	v_mfma_f32_16x16x32_bf16 v[36:39], v[174:177], v[198:201], v[36:39]
	v_mfma_f32_16x16x32_bf16 v[32:35], v[182:185], v[198:201], v[32:35]
	v_mfma_f32_16x16x32_bf16 v[20:23], v[174:177], v[220:223], v[20:23]
	v_mfma_f32_16x16x32_bf16 v[16:19], v[182:185], v[220:223], v[16:19]
	v_mfma_f32_16x16x32_bf16 v[4:7], v[174:177], v[232:235], v[4:7]
	v_mfma_f32_16x16x32_bf16 v[0:3], v[182:185], v[232:235], v[0:3]
	v_mfma_f32_16x16x32_bf16 v[52:55], v[178:181], v[194:197], v[52:55]
	v_mfma_f32_16x16x32_bf16 v[48:51], v[186:189], v[194:197], v[48:51]
	v_mfma_f32_16x16x32_bf16 v[36:39], v[178:181], v[202:205], v[36:39]
	v_mfma_f32_16x16x32_bf16 v[32:35], v[186:189], v[202:205], v[32:35]
	v_mfma_f32_16x16x32_bf16 v[20:23], v[178:181], v[228:231], v[20:23]
	v_mfma_f32_16x16x32_bf16 v[16:19], v[186:189], v[228:231], v[16:19]
	v_mfma_f32_16x16x32_bf16 v[4:7], v[178:181], v[236:239], v[4:7]
	v_mfma_f32_16x16x32_bf16 v[0:3], v[186:189], v[236:239], v[0:3]
	s_setprio 0
	s_barrier
	s_add_i32 s28, s28, 2
	s_add_u32 s58, s58, 0x100
	s_addc_u32 s59, s59, 0
	s_add_u32 s26, s26, 0x100
	s_addc_u32 s27, s27, 0
	s_cmp_gt_u32 s28, 13
	s_cbranch_scc0 .LBB0_1066
	s_and_b64 vcc, exec, s[48:49]
	s_cbranch_vccz .LBB0_1069
	s_barrier

.LBB0_1280:
	s_add_u32 s60, s58, 0x100
	s_addc_u32 s61, s59, 0
	s_add_i32 s25, 0, 0x10000
	s_cmp_eq_u32 s24, 40
	s_cselect_b32 s65, s45, s61
	s_cselect_b32 s64, s44, s60
	v_add_u32_e32 v142, s25, v145
	s_cselect_b32 s63, s57, s7
	s_cselect_b32 s62, s56, s6
	s_add_i32 s28, 0, 0x14000
	ds_read_b128 v[138:141], v142
	ds_read_b128 v[148:151], v142 offset:1024
	ds_read_b128 v[152:155], v142 offset:2048
	ds_read_b128 v[156:159], v142 offset:3072
	v_add_u32_e32 v142, s28, v145
	ds_read_b128 v[174:177], v142
	ds_read_b128 v[178:181], v142 offset:1024
	ds_read_b128 v[182:185], v142 offset:2048
	ds_read_b128 v[186:189], v142 offset:3072
	v_lshl_add_u64 v[142:143], s[58:59], 0, v[134:135]
	s_add_i32 m0, s68, 0xc000
	ds_read_b128 v[190:193], v147
	ds_read_b128 v[194:197], v147 offset:1024
	ds_read_b128 v[198:201], v147 offset:2048
	ds_read_b128 v[202:205], v147 offset:3072
	ds_read_b128 v[220:223], v147 offset:4096
	ds_read_b128 v[228:231], v147 offset:5120
	ds_read_b128 v[232:235], v147 offset:6144
	ds_read_b128 v[236:239], v147 offset:7168
	global_load_lds_dwordx4 v[142:143], off
	v_lshl_add_u64 v[142:143], s[58:59], 0, v[136:137]
	s_add_i32 m0, s68, 0xe000
	s_nop 0
	global_load_lds_dwordx4 v[142:143], off
	s_waitcnt vmcnt(8)
	s_waitcnt lgkmcnt(0)
	s_barrier
	s_setprio 1
	s_waitcnt lgkmcnt(0)
	v_mfma_f32_16x16x32_bf16 v[124:127], v[138:141], v[190:193], v[124:127]
	v_mfma_f32_16x16x32_bf16 v[120:123], v[152:155], v[190:193], v[120:123]
	v_mfma_f32_16x16x32_bf16 v[108:111], v[138:141], v[198:201], v[108:111]
	v_mfma_f32_16x16x32_bf16 v[104:107], v[152:155], v[198:201], v[104:107]
	v_mfma_f32_16x16x32_bf16 v[92:95], v[138:141], v[220:223], v[92:95]
	v_mfma_f32_16x16x32_bf16 v[88:91], v[152:155], v[220:223], v[88:91]
	v_mfma_f32_16x16x32_bf16 v[76:79], v[138:141], v[232:235], v[76:79]
	v_mfma_f32_16x16x32_bf16 v[72:75], v[152:155], v[232:235], v[72:75]
	v_mfma_f32_16x16x32_bf16 v[124:127], v[148:151], v[194:197], v[124:127]
	v_mfma_f32_16x16x32_bf16 v[120:123], v[156:159], v[194:197], v[120:123]
	v_mfma_f32_16x16x32_bf16 v[108:111], v[148:151], v[202:205], v[108:111]
	v_mfma_f32_16x16x32_bf16 v[104:107], v[156:159], v[202:205], v[104:107]
	v_mfma_f32_16x16x32_bf16 v[92:95], v[148:151], v[228:231], v[92:95]
	v_mfma_f32_16x16x32_bf16 v[88:91], v[156:159], v[228:231], v[88:91]
	v_mfma_f32_16x16x32_bf16 v[76:79], v[148:151], v[236:239], v[76:79]
	v_mfma_f32_16x16x32_bf16 v[72:75], v[156:159], v[236:239], v[72:75]
	s_setprio 0
	s_setprio 1
	v_mfma_f32_16x16x32_bf16 v[116:119], v[174:177], v[190:193], v[116:119]
	v_mfma_f32_16x16x32_bf16 v[112:115], v[182:185], v[190:193], v[112:115]
	v_mfma_f32_16x16x32_bf16 v[100:103], v[174:177], v[198:201], v[100:103]
	v_mfma_f32_16x16x32_bf16 v[96:99], v[182:185], v[198:201], v[96:99]
	v_mfma_f32_16x16x32_bf16 v[84:87], v[174:177], v[220:223], v[84:87]
	v_mfma_f32_16x16x32_bf16 v[80:83], v[182:185], v[220:223], v[80:83]
	v_mfma_f32_16x16x32_bf16 v[68:71], v[174:177], v[232:235], v[68:71]
	v_mfma_f32_16x16x32_bf16 v[64:67], v[182:185], v[232:235], v[64:67]
	v_mfma_f32_16x16x32_bf16 v[116:119], v[178:181], v[194:197], v[116:119]
	v_mfma_f32_16x16x32_bf16 v[112:115], v[186:189], v[194:197], v[112:115]
	v_mfma_f32_16x16x32_bf16 v[100:103], v[178:181], v[202:205], v[100:103]
	v_mfma_f32_16x16x32_bf16 v[96:99], v[186:189], v[202:205], v[96:99]
	v_mfma_f32_16x16x32_bf16 v[84:87], v[178:181], v[228:231], v[84:87]
	v_mfma_f32_16x16x32_bf16 v[80:83], v[186:189], v[228:231], v[80:83]
	v_mfma_f32_16x16x32_bf16 v[68:71], v[178:181], v[236:239], v[68:71]
	v_mfma_f32_16x16x32_bf16 v[64:67], v[186:189], v[236:239], v[64:67]
	s_setprio 0
	s_barrier
	s_add_i32 s25, s25, s67
	v_lshl_add_u64 v[142:143], s[62:63], 0, v[162:163]
	s_mov_b32 m0, s25
	s_nop 0
	global_load_lds_dwordx4 v[142:143], off
	s_add_i32 m0, s25, 0x2000
	s_add_u32 s26, s62, 0xb0000
	v_lshl_add_u64 v[240:241], s[62:63], 0, v[128:129]
	s_addc_u32 s27, s63, 0
	s_add_i32 s25, s28, s67
	global_load_lds_dwordx4 v[240:241], off
	v_lshl_add_u64 v[242:243], s[26:27], 0, v[162:163]
	s_mov_b32 m0, s25
	v_lshl_add_u64 v[244:245], s[64:65], 0, v[130:131]
	global_load_lds_dwordx4 v[242:243], off
	v_lshl_add_u64 v[242:243], s[26:27], 0, v[128:129]
	s_add_i32 m0, s25, 0x2000
	s_nop 0
	global_load_lds_dwordx4 v[242:243], off
	v_lshl_add_u64 v[242:243], s[64:65], 0, v[132:133]
	s_mov_b32 m0, s68
	s_nop 0
	global_load_lds_dwordx4 v[242:243], off
	s_mov_b32 m0, s69
	s_nop 0
	global_load_lds_dwordx4 v[244:245], off
	ds_read_b128 v[190:193], v147 offset:16384
	ds_read_b128 v[194:197], v147 offset:17408
	ds_read_b128 v[198:201], v147 offset:18432
	ds_read_b128 v[202:205], v147 offset:19456
	ds_read_b128 v[220:223], v147 offset:20480
	ds_read_b128 v[228:231], v147 offset:21504
	ds_read_b128 v[232:235], v147 offset:22528
	ds_read_b128 v[236:239], v147 offset:23552
	s_waitcnt vmcnt(8)
	s_waitcnt lgkmcnt(0)
	s_barrier
	s_setprio 1
	s_waitcnt lgkmcnt(0)
	v_mfma_f32_16x16x32_bf16 v[60:63], v[138:141], v[190:193], v[60:63]
	v_mfma_f32_16x16x32_bf16 v[56:59], v[152:155], v[190:193], v[56:59]
	v_mfma_f32_16x16x32_bf16 v[44:47], v[138:141], v[198:201], v[44:47]
	v_mfma_f32_16x16x32_bf16 v[40:43], v[152:155], v[198:201], v[40:43]
	v_mfma_f32_16x16x32_bf16 v[28:31], v[138:141], v[220:223], v[28:31]
	v_mfma_f32_16x16x32_bf16 v[24:27], v[152:155], v[220:223], v[24:27]
	v_mfma_f32_16x16x32_bf16 v[12:15], v[138:141], v[232:235], v[12:15]
	v_mfma_f32_16x16x32_bf16 v[8:11], v[152:155], v[232:235], v[8:11]
	v_mfma_f32_16x16x32_bf16 v[60:63], v[148:151], v[194:197], v[60:63]
	v_mfma_f32_16x16x32_bf16 v[56:59], v[156:159], v[194:197], v[56:59]
	v_mfma_f32_16x16x32_bf16 v[44:47], v[148:151], v[202:205], v[44:47]
	v_mfma_f32_16x16x32_bf16 v[40:43], v[156:159], v[202:205], v[40:43]
	v_mfma_f32_16x16x32_bf16 v[28:31], v[148:151], v[228:231], v[28:31]
	v_mfma_f32_16x16x32_bf16 v[24:27], v[156:159], v[228:231], v[24:27]
	v_mfma_f32_16x16x32_bf16 v[12:15], v[148:151], v[236:239], v[12:15]
	v_mfma_f32_16x16x32_bf16 v[8:11], v[156:159], v[236:239], v[8:11]
	s_setprio 0
	s_setprio 1
	v_mfma_f32_16x16x32_bf16 v[52:55], v[174:177], v[190:193], v[52:55]
	v_mfma_f32_16x16x32_bf16 v[48:51], v[182:185], v[190:193], v[48:51]
	v_mfma_f32_16x16x32_bf16 v[36:39], v[174:177], v[198:201], v[36:39]
	v_mfma_f32_16x16x32_bf16 v[32:35], v[182:185], v[198:201], v[32:35]
	v_mfma_f32_16x16x32_bf16 v[20:23], v[174:177], v[220:223], v[20:23]
	v_mfma_f32_16x16x32_bf16 v[16:19], v[182:185], v[220:223], v[16:19]
	v_mfma_f32_16x16x32_bf16 v[4:7], v[174:177], v[232:235], v[4:7]
	v_mfma_f32_16x16x32_bf16 v[0:3], v[182:185], v[232:235], v[0:3]
	v_mfma_f32_16x16x32_bf16 v[52:55], v[178:181], v[194:197], v[52:55]
	v_mfma_f32_16x16x32_bf16 v[48:51], v[186:189], v[194:197], v[48:51]
	v_mfma_f32_16x16x32_bf16 v[36:39], v[178:181], v[202:205], v[36:39]
	v_mfma_f32_16x16x32_bf16 v[32:35], v[186:189], v[202:205], v[32:35]
	v_mfma_f32_16x16x32_bf16 v[20:23], v[178:181], v[228:231], v[20:23]
	v_mfma_f32_16x16x32_bf16 v[16:19], v[186:189], v[228:231], v[16:19]
	v_mfma_f32_16x16x32_bf16 v[4:7], v[178:181], v[236:239], v[4:7]
	v_mfma_f32_16x16x32_bf16 v[0:3], v[186:189], v[236:239], v[0:3]
	s_setprio 0
	s_barrier
	s_add_i32 s25, 0, 0x18000
	s_add_i32 s28, 0, 0x1c000
	v_add_u32_e32 v156, s25, v145
	v_add_u32_e32 v186, s28, v145
	ds_read_b128 v[138:141], v156
	ds_read_b128 v[148:151], v156 offset:1024
	ds_read_b128 v[152:155], v156 offset:2048
	ds_read_b128 v[156:159], v156 offset:3072
	ds_read_b128 v[174:177], v186
	ds_read_b128 v[178:181], v186 offset:1024
	ds_read_b128 v[182:185], v186 offset:2048
	ds_read_b128 v[186:189], v186 offset:3072
	s_add_u32 s26, s64, 0xb0000
	s_addc_u32 s27, s65, 0
	s_mov_b32 m0, s70
	v_lshl_add_u64 v[246:247], s[26:27], 0, v[132:133]
	ds_read_b128 v[190:193], v147 offset:32768
	ds_read_b128 v[194:197], v147 offset:33792
	ds_read_b128 v[198:201], v147 offset:34816
	ds_read_b128 v[202:205], v147 offset:35840
	ds_read_b128 v[220:223], v147 offset:36864
	ds_read_b128 v[228:231], v147 offset:37888
	ds_read_b128 v[232:235], v147 offset:38912
	ds_read_b128 v[236:239], v147 offset:39936
	global_load_lds_dwordx4 v[246:247], off
	v_lshl_add_u64 v[246:247], s[26:27], 0, v[130:131]
	s_mov_b32 m0, s71
	s_nop 0
	global_load_lds_dwordx4 v[246:247], off
	s_waitcnt vmcnt(8)
	s_waitcnt lgkmcnt(0)
	s_barrier
	s_setprio 1
	s_waitcnt lgkmcnt(0)
	v_mfma_f32_16x16x32_bf16 v[124:127], v[138:141], v[190:193], v[124:127]
	v_mfma_f32_16x16x32_bf16 v[120:123], v[152:155], v[190:193], v[120:123]
	v_mfma_f32_16x16x32_bf16 v[108:111], v[138:141], v[198:201], v[108:111]
	v_mfma_f32_16x16x32_bf16 v[104:107], v[152:155], v[198:201], v[104:107]
	v_mfma_f32_16x16x32_bf16 v[92:95], v[138:141], v[220:223], v[92:95]
	v_mfma_f32_16x16x32_bf16 v[88:91], v[152:155], v[220:223], v[88:91]
	v_mfma_f32_16x16x32_bf16 v[76:79], v[138:141], v[232:235], v[76:79]
	v_mfma_f32_16x16x32_bf16 v[72:75], v[152:155], v[232:235], v[72:75]
	v_mfma_f32_16x16x32_bf16 v[124:127], v[148:151], v[194:197], v[124:127]
	v_mfma_f32_16x16x32_bf16 v[120:123], v[156:159], v[194:197], v[120:123]
	v_mfma_f32_16x16x32_bf16 v[108:111], v[148:151], v[202:205], v[108:111]
	v_mfma_f32_16x16x32_bf16 v[104:107], v[156:159], v[202:205], v[104:107]
	v_mfma_f32_16x16x32_bf16 v[92:95], v[148:151], v[228:231], v[92:95]
	v_mfma_f32_16x16x32_bf16 v[88:91], v[156:159], v[228:231], v[88:91]
	v_mfma_f32_16x16x32_bf16 v[76:79], v[148:151], v[236:239], v[76:79]
	v_mfma_f32_16x16x32_bf16 v[72:75], v[156:159], v[236:239], v[72:75]
	s_setprio 0
	s_setprio 1
	v_mfma_f32_16x16x32_bf16 v[116:119], v[174:177], v[190:193], v[116:119]
	v_mfma_f32_16x16x32_bf16 v[112:115], v[182:185], v[190:193], v[112:115]
	v_mfma_f32_16x16x32_bf16 v[100:103], v[174:177], v[198:201], v[100:103]
	v_mfma_f32_16x16x32_bf16 v[96:99], v[182:185], v[198:201], v[96:99]
	v_mfma_f32_16x16x32_bf16 v[84:87], v[174:177], v[220:223], v[84:87]
	v_mfma_f32_16x16x32_bf16 v[80:83], v[182:185], v[220:223], v[80:83]
	v_mfma_f32_16x16x32_bf16 v[68:71], v[174:177], v[232:235], v[68:71]
	v_mfma_f32_16x16x32_bf16 v[64:67], v[182:185], v[232:235], v[64:67]
	v_mfma_f32_16x16x32_bf16 v[116:119], v[178:181], v[194:197], v[116:119]
	v_mfma_f32_16x16x32_bf16 v[112:115], v[186:189], v[194:197], v[112:115]
	v_mfma_f32_16x16x32_bf16 v[100:103], v[178:181], v[202:205], v[100:103]
	v_mfma_f32_16x16x32_bf16 v[96:99], v[186:189], v[202:205], v[96:99]
	v_mfma_f32_16x16x32_bf16 v[84:87], v[178:181], v[228:231], v[84:87]
	v_mfma_f32_16x16x32_bf16 v[80:83], v[186:189], v[228:231], v[80:83]
	v_mfma_f32_16x16x32_bf16 v[68:71], v[178:181], v[236:239], v[68:71]
	v_mfma_f32_16x16x32_bf16 v[64:67], v[186:189], v[236:239], v[64:67]
	s_setprio 0
	s_barrier
	s_add_i32 s25, s25, s67
	v_lshl_add_u64 v[142:143], v[142:143], 0, s[4:5]
	s_mov_b32 m0, s25
	s_nop 0
	global_load_lds_dwordx4 v[142:143], off
	s_add_i32 m0, s25, 0x2000
	s_add_u32 s26, s62, 0xb0080
	v_lshl_add_u64 v[142:143], v[240:241], 0, s[4:5]
	s_addc_u32 s27, s63, 0
	s_add_i32 s25, s28, s67
	global_load_lds_dwordx4 v[142:143], off
	v_lshl_add_u64 v[142:143], s[26:27], 0, v[162:163]
	s_mov_b32 m0, s25
	s_nop 0
	global_load_lds_dwordx4 v[142:143], off
	v_lshl_add_u64 v[142:143], s[26:27], 0, v[128:129]
	s_add_i32 m0, s25, 0x2000
	s_nop 0
	global_load_lds_dwordx4 v[142:143], off
	v_lshl_add_u64 v[142:143], v[242:243], 0, s[4:5]
	s_mov_b32 m0, s73
	s_nop 0
	global_load_lds_dwordx4 v[142:143], off
	v_lshl_add_u64 v[142:143], v[244:245], 0, s[4:5]
	s_mov_b32 m0, s74
	s_nop 0
	global_load_lds_dwordx4 v[142:143], off
	ds_read_b128 v[190:193], v147 offset:49152
	ds_read_b128 v[194:197], v147 offset:50176
	ds_read_b128 v[198:201], v147 offset:51200
	ds_read_b128 v[202:205], v147 offset:52224
	ds_read_b128 v[220:223], v147 offset:53248
	ds_read_b128 v[228:231], v147 offset:54272
	ds_read_b128 v[232:235], v147 offset:55296
	ds_read_b128 v[236:239], v147 offset:56320
	s_waitcnt vmcnt(8)
	s_waitcnt lgkmcnt(0)
	s_barrier
	s_setprio 1
	s_waitcnt lgkmcnt(0)
	v_mfma_f32_16x16x32_bf16 v[60:63], v[138:141], v[190:193], v[60:63]
	v_mfma_f32_16x16x32_bf16 v[56:59], v[152:155], v[190:193], v[56:59]
	v_mfma_f32_16x16x32_bf16 v[44:47], v[138:141], v[198:201], v[44:47]
	v_mfma_f32_16x16x32_bf16 v[40:43], v[152:155], v[198:201], v[40:43]
	v_mfma_f32_16x16x32_bf16 v[28:31], v[138:141], v[220:223], v[28:31]
	v_mfma_f32_16x16x32_bf16 v[24:27], v[152:155], v[220:223], v[24:27]
	v_mfma_f32_16x16x32_bf16 v[12:15], v[138:141], v[232:235], v[12:15]
	v_mfma_f32_16x16x32_bf16 v[8:11], v[152:155], v[232:235], v[8:11]
	v_mfma_f32_16x16x32_bf16 v[60:63], v[148:151], v[194:197], v[60:63]
	v_mfma_f32_16x16x32_bf16 v[56:59], v[156:159], v[194:197], v[56:59]
	v_mfma_f32_16x16x32_bf16 v[44:47], v[148:151], v[202:205], v[44:47]
	v_mfma_f32_16x16x32_bf16 v[40:43], v[156:159], v[202:205], v[40:43]
	v_mfma_f32_16x16x32_bf16 v[28:31], v[148:151], v[228:231], v[28:31]
	v_mfma_f32_16x16x32_bf16 v[24:27], v[156:159], v[228:231], v[24:27]
	v_mfma_f32_16x16x32_bf16 v[12:15], v[148:151], v[236:239], v[12:15]
	v_mfma_f32_16x16x32_bf16 v[8:11], v[156:159], v[236:239], v[8:11]
	s_setprio 0
	s_setprio 1
	v_mfma_f32_16x16x32_bf16 v[52:55], v[174:177], v[190:193], v[52:55]
	v_mfma_f32_16x16x32_bf16 v[48:51], v[182:185], v[190:193], v[48:51]
	v_mfma_f32_16x16x32_bf16 v[36:39], v[174:177], v[198:201], v[36:39]
	v_mfma_f32_16x16x32_bf16 v[32:35], v[182:185], v[198:201], v[32:35]
	v_mfma_f32_16x16x32_bf16 v[20:23], v[174:177], v[220:223], v[20:23]
	v_mfma_f32_16x16x32_bf16 v[16:19], v[182:185], v[220:223], v[16:19]
	v_mfma_f32_16x16x32_bf16 v[4:7], v[174:177], v[232:235], v[4:7]
	v_mfma_f32_16x16x32_bf16 v[0:3], v[182:185], v[232:235], v[0:3]
	v_mfma_f32_16x16x32_bf16 v[52:55], v[178:181], v[194:197], v[52:55]
	v_mfma_f32_16x16x32_bf16 v[48:51], v[186:189], v[194:197], v[48:51]
	v_mfma_f32_16x16x32_bf16 v[36:39], v[178:181], v[202:205], v[36:39]
	v_mfma_f32_16x16x32_bf16 v[32:35], v[186:189], v[202:205], v[32:35]
	v_mfma_f32_16x16x32_bf16 v[20:23], v[178:181], v[228:231], v[20:23]
	v_mfma_f32_16x16x32_bf16 v[16:19], v[186:189], v[228:231], v[16:19]
	v_mfma_f32_16x16x32_bf16 v[4:7], v[178:181], v[236:239], v[4:7]
	v_mfma_f32_16x16x32_bf16 v[0:3], v[186:189], v[236:239], v[0:3]
	s_setprio 0
	s_barrier
	s_add_i32 s24, s24, 2
	s_add_u32 s6, s6, 0x100
	s_addc_u32 s7, s7, 0
	s_cmp_gt_u32 s24, 41
	s_mov_b64 s[58:59], s[60:61]
	s_cbranch_scc0 .LBB0_1280
	s_and_b64 vcc, exec, s[54:55]
	s_cbranch_vccz .LBB0_1283
	s_barrier
